# GEMM k-loops of both wave groups rewritten unrolled: LDS stage writes + prefetch moved into the MFMA segments, LDS-read segments read only
# speedup vs baseline: 1.3640x; 1.0107x over previous
.LBB0_205:
	ds_read_b128 v[112:115], v237
	ds_read_b128 v[116:119], v237 offset:32
	ds_read_b128 v[120:123], v237 offset:4608
	ds_read_b128 v[124:127], v237 offset:4640
	ds_read_b128 v[130:133], v238 offset:36864
	ds_read_b128 v[134:137], v238 offset:36896
	ds_read_b128 v[138:141], v238 offset:41472
	ds_read_b128 v[142:145], v238 offset:41504
	ds_read_b128 v[146:149], v237 offset:64
	ds_read_b128 v[150:153], v237 offset:96
	ds_read_b128 v[154:157], v237 offset:4672
	ds_read_b128 v[158:161], v237 offset:4704
	ds_read_b128 v[162:165], v238 offset:36928
	ds_read_b128 v[166:169], v238 offset:36960
	ds_read_b128 v[170:173], v238 offset:41536
	ds_read_b128 v[174:177], v238 offset:41568
	s_waitcnt vmcnt(11)
	ds_write_b128 v235, v[64:67] offset:55296
	s_waitcnt vmcnt(10)
	ds_write_b128 v235, v[68:71] offset:64512
	s_waitcnt vmcnt(9)
	ds_write_b128 v239, v[80:83] offset:18432
	s_waitcnt vmcnt(8)
	ds_write_b128 v239, v[84:87] offset:27648
	s_waitcnt vmcnt(7)
	ds_write_b128 v240, v[96:99]
	s_waitcnt vmcnt(6)
	ds_write_b128 v240, v[100:103] offset:9216
	global_load_dwordx4 v[64:67], v[194:195], off offset:384
	global_load_dwordx4 v[68:71], v[198:199], off offset:384
	global_load_dwordx4 v[80:83], v[200:201], off offset:384
	global_load_dwordx4 v[84:87], v[202:203], off offset:384
	global_load_dwordx4 v[96:99], v[196:197], off offset:384
	global_load_dwordx4 v[100:103], v[204:205], off offset:384
	s_waitcnt lgkmcnt(0)
	s_barrier
	v_mfma_f32_32x32x16_bf16 v[48:63], v[112:115], v[130:133], v[48:63]
	v_mfma_f32_32x32x16_bf16 v[32:47], v[112:115], v[138:141], v[32:47]
	s_waitcnt vmcnt(11)
	ds_write_b128 v235, v[72:75]
	v_mfma_f32_32x32x16_bf16 v[16:31], v[120:123], v[130:133], v[16:31]
	v_mfma_f32_32x32x16_bf16 v[0:15], v[120:123], v[138:141], v[0:15]
	s_waitcnt vmcnt(10)
	ds_write_b128 v235, v[76:79] offset:9216
	v_mfma_f32_32x32x16_bf16 v[48:63], v[116:119], v[134:137], v[48:63]
	v_mfma_f32_32x32x16_bf16 v[32:47], v[116:119], v[142:145], v[32:47]
	s_waitcnt vmcnt(9)
	ds_write_b128 v235, v[88:91] offset:18432
	v_mfma_f32_32x32x16_bf16 v[16:31], v[124:127], v[134:137], v[16:31]
	v_mfma_f32_32x32x16_bf16 v[0:15], v[124:127], v[142:145], v[0:15]
	s_waitcnt vmcnt(8)
	ds_write_b128 v235, v[92:95] offset:27648
	v_mfma_f32_32x32x16_bf16 v[48:63], v[146:149], v[162:165], v[48:63]
	v_mfma_f32_32x32x16_bf16 v[32:47], v[146:149], v[170:173], v[32:47]
	s_waitcnt vmcnt(7)
	ds_write_b128 v235, v[104:107] offset:36864
	v_mfma_f32_32x32x16_bf16 v[16:31], v[154:157], v[162:165], v[16:31]
	v_mfma_f32_32x32x16_bf16 v[0:15], v[154:157], v[170:173], v[0:15]
	s_waitcnt vmcnt(6)
	ds_write_b128 v235, v[108:111] offset:46080
	v_mfma_f32_32x32x16_bf16 v[48:63], v[150:153], v[166:169], v[48:63]
	v_mfma_f32_32x32x16_bf16 v[32:47], v[150:153], v[174:177], v[32:47]
	v_mfma_f32_32x32x16_bf16 v[16:31], v[158:161], v[166:169], v[16:31]
	v_mfma_f32_32x32x16_bf16 v[0:15], v[158:161], v[174:177], v[0:15]
	global_load_dwordx4 v[72:75], v[194:195], off offset:512
	global_load_dwordx4 v[76:79], v[198:199], off offset:512
	global_load_dwordx4 v[88:91], v[200:201], off offset:512
	global_load_dwordx4 v[92:95], v[202:203], off offset:512
	global_load_dwordx4 v[104:107], v[196:197], off offset:512
	global_load_dwordx4 v[108:111], v[204:205], off offset:512
	s_waitcnt lgkmcnt(0)
	s_barrier
	ds_read_b128 v[162:165], v237 offset:55296
	ds_read_b128 v[130:133], v237 offset:55328
	ds_read_b128 v[170:173], v241
	ds_read_b128 v[134:137], v241 offset:32
	ds_read_b128 v[166:169], v237 offset:59904
	ds_read_b128 v[142:145], v237 offset:59936
	ds_read_b128 v[174:177], v241 offset:4608
	ds_read_b128 v[150:153], v241 offset:4640
	ds_read_b128 v[138:141], v237 offset:55360
	ds_read_b128 v[116:119], v237 offset:55392
	ds_read_b128 v[146:149], v237 offset:59968
	ds_read_b128 v[112:115], v237 offset:60000
	ds_read_b128 v[154:157], v241 offset:64
	ds_read_b128 v[120:123], v241 offset:96
	ds_read_b128 v[158:161], v241 offset:4672
	ds_read_b128 v[124:127], v241 offset:4704
	s_waitcnt lgkmcnt(0)
	s_barrier
	v_mfma_f32_32x32x16_bf16 v[48:63], v[162:165], v[170:173], v[48:63]
	v_mfma_f32_32x32x16_bf16 v[32:47], v[162:165], v[174:177], v[32:47]
	s_waitcnt vmcnt(11)
	ds_write_b128 v235, v[64:67] offset:55296
	v_mfma_f32_32x32x16_bf16 v[16:31], v[166:169], v[170:173], v[16:31]
	v_mfma_f32_32x32x16_bf16 v[0:15], v[166:169], v[174:177], v[0:15]
	s_waitcnt vmcnt(10)
	ds_write_b128 v235, v[68:71] offset:64512
	v_mfma_f32_32x32x16_bf16 v[48:63], v[130:133], v[134:137], v[48:63]
	v_mfma_f32_32x32x16_bf16 v[32:47], v[130:133], v[150:153], v[32:47]
	s_waitcnt vmcnt(9)
	ds_write_b128 v239, v[80:83] offset:18432
	v_mfma_f32_32x32x16_bf16 v[16:31], v[142:145], v[134:137], v[16:31]
	v_mfma_f32_32x32x16_bf16 v[0:15], v[142:145], v[150:153], v[0:15]
	s_waitcnt vmcnt(8)
	ds_write_b128 v239, v[84:87] offset:27648
	v_mfma_f32_32x32x16_bf16 v[48:63], v[138:141], v[154:157], v[48:63]
	v_mfma_f32_32x32x16_bf16 v[32:47], v[138:141], v[158:161], v[32:47]
	s_waitcnt vmcnt(7)
	ds_write_b128 v240, v[96:99]
	v_mfma_f32_32x32x16_bf16 v[16:31], v[146:149], v[154:157], v[16:31]
	v_mfma_f32_32x32x16_bf16 v[0:15], v[146:149], v[158:161], v[0:15]
	s_waitcnt vmcnt(6)
	ds_write_b128 v240, v[100:103] offset:9216
	v_mfma_f32_32x32x16_bf16 v[48:63], v[116:119], v[120:123], v[48:63]
	v_mfma_f32_32x32x16_bf16 v[32:47], v[116:119], v[124:127], v[32:47]
	v_mfma_f32_32x32x16_bf16 v[16:31], v[112:115], v[120:123], v[16:31]
	v_mfma_f32_32x32x16_bf16 v[0:15], v[112:115], v[124:127], v[0:15]
	global_load_dwordx4 v[64:67], v[194:195], off offset:640
	global_load_dwordx4 v[68:71], v[198:199], off offset:640
	global_load_dwordx4 v[80:83], v[200:201], off offset:640
	global_load_dwordx4 v[84:87], v[202:203], off offset:640
	global_load_dwordx4 v[96:99], v[196:197], off offset:640
	global_load_dwordx4 v[100:103], v[204:205], off offset:640
	s_waitcnt lgkmcnt(0)
	s_barrier
	ds_read_b128 v[112:115], v237
	ds_read_b128 v[116:119], v237 offset:32
	ds_read_b128 v[120:123], v237 offset:4608
	ds_read_b128 v[124:127], v237 offset:4640
	ds_read_b128 v[130:133], v238 offset:36864
	ds_read_b128 v[134:137], v238 offset:36896
	ds_read_b128 v[138:141], v238 offset:41472
	ds_read_b128 v[142:145], v238 offset:41504
	ds_read_b128 v[146:149], v237 offset:64
	ds_read_b128 v[150:153], v237 offset:96
	ds_read_b128 v[154:157], v237 offset:4672
	ds_read_b128 v[158:161], v237 offset:4704
	ds_read_b128 v[162:165], v238 offset:36928
	ds_read_b128 v[166:169], v238 offset:36960
	ds_read_b128 v[170:173], v238 offset:41536
	ds_read_b128 v[174:177], v238 offset:41568
	s_waitcnt lgkmcnt(0)
	s_barrier
	v_mfma_f32_32x32x16_bf16 v[48:63], v[112:115], v[130:133], v[48:63]
	v_mfma_f32_32x32x16_bf16 v[32:47], v[112:115], v[138:141], v[32:47]
	s_waitcnt vmcnt(11)
	ds_write_b128 v235, v[72:75]
	v_mfma_f32_32x32x16_bf16 v[16:31], v[120:123], v[130:133], v[16:31]
	v_mfma_f32_32x32x16_bf16 v[0:15], v[120:123], v[138:141], v[0:15]
	s_waitcnt vmcnt(10)
	ds_write_b128 v235, v[76:79] offset:9216
	v_mfma_f32_32x32x16_bf16 v[48:63], v[116:119], v[134:137], v[48:63]
	v_mfma_f32_32x32x16_bf16 v[32:47], v[116:119], v[142:145], v[32:47]
	s_waitcnt vmcnt(9)
	ds_write_b128 v235, v[88:91] offset:18432
	v_mfma_f32_32x32x16_bf16 v[16:31], v[124:127], v[134:137], v[16:31]
	v_mfma_f32_32x32x16_bf16 v[0:15], v[124:127], v[142:145], v[0:15]
	s_waitcnt vmcnt(8)
	ds_write_b128 v235, v[92:95] offset:27648
	v_mfma_f32_32x32x16_bf16 v[48:63], v[146:149], v[162:165], v[48:63]
	v_mfma_f32_32x32x16_bf16 v[32:47], v[146:149], v[170:173], v[32:47]
	s_waitcnt vmcnt(7)
	ds_write_b128 v235, v[104:107] offset:36864
	v_mfma_f32_32x32x16_bf16 v[16:31], v[154:157], v[162:165], v[16:31]
	v_mfma_f32_32x32x16_bf16 v[0:15], v[154:157], v[170:173], v[0:15]
	s_waitcnt vmcnt(6)
	ds_write_b128 v235, v[108:111] offset:46080
	v_mfma_f32_32x32x16_bf16 v[48:63], v[150:153], v[166:169], v[48:63]
	v_mfma_f32_32x32x16_bf16 v[32:47], v[150:153], v[174:177], v[32:47]
	v_mfma_f32_32x32x16_bf16 v[16:31], v[158:161], v[166:169], v[16:31]
	v_mfma_f32_32x32x16_bf16 v[0:15], v[158:161], v[174:177], v[0:15]
	global_load_dwordx4 v[72:75], v[194:195], off offset:768
	global_load_dwordx4 v[76:79], v[198:199], off offset:768
	global_load_dwordx4 v[88:91], v[200:201], off offset:768
	global_load_dwordx4 v[92:95], v[202:203], off offset:768
	global_load_dwordx4 v[104:107], v[196:197], off offset:768
	global_load_dwordx4 v[108:111], v[204:205], off offset:768
	s_waitcnt lgkmcnt(0)
	s_barrier
	ds_read_b128 v[162:165], v237 offset:55296
	ds_read_b128 v[130:133], v237 offset:55328
	ds_read_b128 v[170:173], v241
	ds_read_b128 v[134:137], v241 offset:32
	ds_read_b128 v[166:169], v237 offset:59904
	ds_read_b128 v[142:145], v237 offset:59936
	ds_read_b128 v[174:177], v241 offset:4608
	ds_read_b128 v[150:153], v241 offset:4640
	ds_read_b128 v[138:141], v237 offset:55360
	ds_read_b128 v[116:119], v237 offset:55392
	ds_read_b128 v[146:149], v237 offset:59968
	ds_read_b128 v[112:115], v237 offset:60000
	ds_read_b128 v[154:157], v241 offset:64
	ds_read_b128 v[120:123], v241 offset:96
	ds_read_b128 v[158:161], v241 offset:4672
	ds_read_b128 v[124:127], v241 offset:4704
	s_waitcnt lgkmcnt(0)
	s_barrier
	v_mfma_f32_32x32x16_bf16 v[48:63], v[162:165], v[170:173], v[48:63]
	v_mfma_f32_32x32x16_bf16 v[32:47], v[162:165], v[174:177], v[32:47]
	s_waitcnt vmcnt(11)
	ds_write_b128 v235, v[64:67] offset:55296
	v_mfma_f32_32x32x16_bf16 v[16:31], v[166:169], v[170:173], v[16:31]
	v_mfma_f32_32x32x16_bf16 v[0:15], v[166:169], v[174:177], v[0:15]
	s_waitcnt vmcnt(10)
	ds_write_b128 v235, v[68:71] offset:64512
	v_mfma_f32_32x32x16_bf16 v[48:63], v[130:133], v[134:137], v[48:63]
	v_mfma_f32_32x32x16_bf16 v[32:47], v[130:133], v[150:153], v[32:47]
	s_waitcnt vmcnt(9)
	ds_write_b128 v239, v[80:83] offset:18432
	v_mfma_f32_32x32x16_bf16 v[16:31], v[142:145], v[134:137], v[16:31]
	v_mfma_f32_32x32x16_bf16 v[0:15], v[142:145], v[150:153], v[0:15]
	s_waitcnt vmcnt(8)
	ds_write_b128 v239, v[84:87] offset:27648
	v_mfma_f32_32x32x16_bf16 v[48:63], v[138:141], v[154:157], v[48:63]
	v_mfma_f32_32x32x16_bf16 v[32:47], v[138:141], v[158:161], v[32:47]
	s_waitcnt vmcnt(7)
	ds_write_b128 v240, v[96:99]
	v_mfma_f32_32x32x16_bf16 v[16:31], v[146:149], v[154:157], v[16:31]
	v_mfma_f32_32x32x16_bf16 v[0:15], v[146:149], v[158:161], v[0:15]
	s_waitcnt vmcnt(6)
	ds_write_b128 v240, v[100:103] offset:9216
	v_mfma_f32_32x32x16_bf16 v[48:63], v[116:119], v[120:123], v[48:63]
	v_mfma_f32_32x32x16_bf16 v[32:47], v[116:119], v[124:127], v[32:47]
	v_mfma_f32_32x32x16_bf16 v[16:31], v[112:115], v[120:123], v[16:31]
	v_mfma_f32_32x32x16_bf16 v[0:15], v[112:115], v[124:127], v[0:15]
	global_load_dwordx4 v[64:67], v[194:195], off offset:896
	global_load_dwordx4 v[68:71], v[198:199], off offset:896
	global_load_dwordx4 v[80:83], v[200:201], off offset:896
	global_load_dwordx4 v[84:87], v[202:203], off offset:896
	global_load_dwordx4 v[96:99], v[196:197], off offset:896
	global_load_dwordx4 v[100:103], v[204:205], off offset:896
	s_waitcnt lgkmcnt(0)
	s_barrier
	ds_read_b128 v[112:115], v237
	ds_read_b128 v[116:119], v237 offset:32
	ds_read_b128 v[120:123], v237 offset:4608
	ds_read_b128 v[124:127], v237 offset:4640
	ds_read_b128 v[130:133], v238 offset:36864
	ds_read_b128 v[134:137], v238 offset:36896
	ds_read_b128 v[138:141], v238 offset:41472
	ds_read_b128 v[142:145], v238 offset:41504
	ds_read_b128 v[146:149], v237 offset:64
	ds_read_b128 v[150:153], v237 offset:96
	ds_read_b128 v[154:157], v237 offset:4672
	ds_read_b128 v[158:161], v237 offset:4704
	ds_read_b128 v[162:165], v238 offset:36928
	ds_read_b128 v[166:169], v238 offset:36960
	ds_read_b128 v[170:173], v238 offset:41536
	ds_read_b128 v[174:177], v238 offset:41568
	s_waitcnt lgkmcnt(0)
	s_barrier
	v_mfma_f32_32x32x16_bf16 v[48:63], v[112:115], v[130:133], v[48:63]
	v_mfma_f32_32x32x16_bf16 v[32:47], v[112:115], v[138:141], v[32:47]
	s_waitcnt vmcnt(11)
	ds_write_b128 v235, v[72:75]
	v_mfma_f32_32x32x16_bf16 v[16:31], v[120:123], v[130:133], v[16:31]
	v_mfma_f32_32x32x16_bf16 v[0:15], v[120:123], v[138:141], v[0:15]
	s_waitcnt vmcnt(10)
	ds_write_b128 v235, v[76:79] offset:9216
	v_mfma_f32_32x32x16_bf16 v[48:63], v[116:119], v[134:137], v[48:63]
	v_mfma_f32_32x32x16_bf16 v[32:47], v[116:119], v[142:145], v[32:47]
	s_waitcnt vmcnt(9)
	ds_write_b128 v235, v[88:91] offset:18432
	v_mfma_f32_32x32x16_bf16 v[16:31], v[124:127], v[134:137], v[16:31]
	v_mfma_f32_32x32x16_bf16 v[0:15], v[124:127], v[142:145], v[0:15]
	s_waitcnt vmcnt(8)
	ds_write_b128 v235, v[92:95] offset:27648
	v_mfma_f32_32x32x16_bf16 v[48:63], v[146:149], v[162:165], v[48:63]
	v_mfma_f32_32x32x16_bf16 v[32:47], v[146:149], v[170:173], v[32:47]
	s_waitcnt vmcnt(7)
	ds_write_b128 v235, v[104:107] offset:36864
	v_mfma_f32_32x32x16_bf16 v[16:31], v[154:157], v[162:165], v[16:31]
	v_mfma_f32_32x32x16_bf16 v[0:15], v[154:157], v[170:173], v[0:15]
	s_waitcnt vmcnt(6)
	ds_write_b128 v235, v[108:111] offset:46080
	v_mfma_f32_32x32x16_bf16 v[48:63], v[150:153], v[166:169], v[48:63]
	v_mfma_f32_32x32x16_bf16 v[32:47], v[150:153], v[174:177], v[32:47]
	v_mfma_f32_32x32x16_bf16 v[16:31], v[158:161], v[166:169], v[16:31]
	v_mfma_f32_32x32x16_bf16 v[0:15], v[158:161], v[174:177], v[0:15]
	global_load_dwordx4 v[72:75], v[194:195], off offset:1024
	global_load_dwordx4 v[76:79], v[198:199], off offset:1024
	global_load_dwordx4 v[88:91], v[200:201], off offset:1024
	global_load_dwordx4 v[92:95], v[202:203], off offset:1024
	global_load_dwordx4 v[104:107], v[196:197], off offset:1024
	global_load_dwordx4 v[108:111], v[204:205], off offset:1024
	s_waitcnt lgkmcnt(0)
	s_barrier
	ds_read_b128 v[162:165], v237 offset:55296
	ds_read_b128 v[130:133], v237 offset:55328
	ds_read_b128 v[170:173], v241
	ds_read_b128 v[134:137], v241 offset:32
	ds_read_b128 v[166:169], v237 offset:59904
	ds_read_b128 v[142:145], v237 offset:59936
	ds_read_b128 v[174:177], v241 offset:4608
	ds_read_b128 v[150:153], v241 offset:4640
	ds_read_b128 v[138:141], v237 offset:55360
	ds_read_b128 v[116:119], v237 offset:55392
	ds_read_b128 v[146:149], v237 offset:59968
	ds_read_b128 v[112:115], v237 offset:60000
	ds_read_b128 v[154:157], v241 offset:64
	ds_read_b128 v[120:123], v241 offset:96
	ds_read_b128 v[158:161], v241 offset:4672
	ds_read_b128 v[124:127], v241 offset:4704
	s_waitcnt lgkmcnt(0)
	s_barrier
	v_mfma_f32_32x32x16_bf16 v[48:63], v[162:165], v[170:173], v[48:63]
	v_mfma_f32_32x32x16_bf16 v[32:47], v[162:165], v[174:177], v[32:47]
	s_waitcnt vmcnt(11)
	ds_write_b128 v235, v[64:67] offset:55296
	v_mfma_f32_32x32x16_bf16 v[16:31], v[166:169], v[170:173], v[16:31]
	v_mfma_f32_32x32x16_bf16 v[0:15], v[166:169], v[174:177], v[0:15]
	s_waitcnt vmcnt(10)
	ds_write_b128 v235, v[68:71] offset:64512
	v_mfma_f32_32x32x16_bf16 v[48:63], v[130:133], v[134:137], v[48:63]
	v_mfma_f32_32x32x16_bf16 v[32:47], v[130:133], v[150:153], v[32:47]
	s_waitcnt vmcnt(9)
	ds_write_b128 v239, v[80:83] offset:18432
	v_mfma_f32_32x32x16_bf16 v[16:31], v[142:145], v[134:137], v[16:31]
	v_mfma_f32_32x32x16_bf16 v[0:15], v[142:145], v[150:153], v[0:15]
	s_waitcnt vmcnt(8)
	ds_write_b128 v239, v[84:87] offset:27648
	v_mfma_f32_32x32x16_bf16 v[48:63], v[138:141], v[154:157], v[48:63]
	v_mfma_f32_32x32x16_bf16 v[32:47], v[138:141], v[158:161], v[32:47]
	s_waitcnt vmcnt(7)
	ds_write_b128 v240, v[96:99]
	v_mfma_f32_32x32x16_bf16 v[16:31], v[146:149], v[154:157], v[16:31]
	v_mfma_f32_32x32x16_bf16 v[0:15], v[146:149], v[158:161], v[0:15]
	s_waitcnt vmcnt(6)
	ds_write_b128 v240, v[100:103] offset:9216
	v_mfma_f32_32x32x16_bf16 v[48:63], v[116:119], v[120:123], v[48:63]
	v_mfma_f32_32x32x16_bf16 v[32:47], v[116:119], v[124:127], v[32:47]
	v_mfma_f32_32x32x16_bf16 v[16:31], v[112:115], v[120:123], v[16:31]
	v_mfma_f32_32x32x16_bf16 v[0:15], v[112:115], v[124:127], v[0:15]
	global_load_dwordx4 v[64:67], v[194:195], off offset:1152
	global_load_dwordx4 v[68:71], v[198:199], off offset:1152
	global_load_dwordx4 v[80:83], v[200:201], off offset:1152
	global_load_dwordx4 v[84:87], v[202:203], off offset:1152
	global_load_dwordx4 v[96:99], v[196:197], off offset:1152
	global_load_dwordx4 v[100:103], v[204:205], off offset:1152
	s_waitcnt lgkmcnt(0)
	s_barrier
	ds_read_b128 v[112:115], v237
	ds_read_b128 v[116:119], v237 offset:32
	ds_read_b128 v[120:123], v237 offset:4608
	ds_read_b128 v[124:127], v237 offset:4640
	ds_read_b128 v[130:133], v238 offset:36864
	ds_read_b128 v[134:137], v238 offset:36896
	ds_read_b128 v[138:141], v238 offset:41472
	ds_read_b128 v[142:145], v238 offset:41504
	ds_read_b128 v[146:149], v237 offset:64
	ds_read_b128 v[150:153], v237 offset:96
	ds_read_b128 v[154:157], v237 offset:4672
	ds_read_b128 v[158:161], v237 offset:4704
	ds_read_b128 v[162:165], v238 offset:36928
	ds_read_b128 v[166:169], v238 offset:36960
	ds_read_b128 v[170:173], v238 offset:41536
	ds_read_b128 v[174:177], v238 offset:41568
	s_waitcnt lgkmcnt(0)
	s_barrier
	v_mfma_f32_32x32x16_bf16 v[48:63], v[112:115], v[130:133], v[48:63]
	v_mfma_f32_32x32x16_bf16 v[32:47], v[112:115], v[138:141], v[32:47]
	s_waitcnt vmcnt(11)
	ds_write_b128 v235, v[72:75]
	v_mfma_f32_32x32x16_bf16 v[16:31], v[120:123], v[130:133], v[16:31]
	v_mfma_f32_32x32x16_bf16 v[0:15], v[120:123], v[138:141], v[0:15]
	s_waitcnt vmcnt(10)
	ds_write_b128 v235, v[76:79] offset:9216
	v_mfma_f32_32x32x16_bf16 v[48:63], v[116:119], v[134:137], v[48:63]
	v_mfma_f32_32x32x16_bf16 v[32:47], v[116:119], v[142:145], v[32:47]
	s_waitcnt vmcnt(9)
	ds_write_b128 v235, v[88:91] offset:18432
	v_mfma_f32_32x32x16_bf16 v[16:31], v[124:127], v[134:137], v[16:31]
	v_mfma_f32_32x32x16_bf16 v[0:15], v[124:127], v[142:145], v[0:15]
	s_waitcnt vmcnt(8)
	ds_write_b128 v235, v[92:95] offset:27648
	v_mfma_f32_32x32x16_bf16 v[48:63], v[146:149], v[162:165], v[48:63]
	v_mfma_f32_32x32x16_bf16 v[32:47], v[146:149], v[170:173], v[32:47]
	s_waitcnt vmcnt(7)
	ds_write_b128 v235, v[104:107] offset:36864
	v_mfma_f32_32x32x16_bf16 v[16:31], v[154:157], v[162:165], v[16:31]
	v_mfma_f32_32x32x16_bf16 v[0:15], v[154:157], v[170:173], v[0:15]
	s_waitcnt vmcnt(6)
	ds_write_b128 v235, v[108:111] offset:46080
	v_mfma_f32_32x32x16_bf16 v[48:63], v[150:153], v[166:169], v[48:63]
	v_mfma_f32_32x32x16_bf16 v[32:47], v[150:153], v[174:177], v[32:47]
	v_mfma_f32_32x32x16_bf16 v[16:31], v[158:161], v[166:169], v[16:31]
	v_mfma_f32_32x32x16_bf16 v[0:15], v[158:161], v[174:177], v[0:15]
	global_load_dwordx4 v[72:75], v[194:195], off offset:1280
	global_load_dwordx4 v[76:79], v[198:199], off offset:1280
	global_load_dwordx4 v[88:91], v[200:201], off offset:1280
	global_load_dwordx4 v[92:95], v[202:203], off offset:1280
	global_load_dwordx4 v[104:107], v[196:197], off offset:1280
	global_load_dwordx4 v[108:111], v[204:205], off offset:1280
	s_waitcnt lgkmcnt(0)
	s_barrier
	ds_read_b128 v[162:165], v237 offset:55296
	ds_read_b128 v[130:133], v237 offset:55328
	ds_read_b128 v[170:173], v241
	ds_read_b128 v[134:137], v241 offset:32
	ds_read_b128 v[166:169], v237 offset:59904
	ds_read_b128 v[142:145], v237 offset:59936
	ds_read_b128 v[174:177], v241 offset:4608
	ds_read_b128 v[150:153], v241 offset:4640
	ds_read_b128 v[138:141], v237 offset:55360
	ds_read_b128 v[116:119], v237 offset:55392
	ds_read_b128 v[146:149], v237 offset:59968
	ds_read_b128 v[112:115], v237 offset:60000
	ds_read_b128 v[154:157], v241 offset:64
	ds_read_b128 v[120:123], v241 offset:96
	ds_read_b128 v[158:161], v241 offset:4672
	ds_read_b128 v[124:127], v241 offset:4704
	s_waitcnt lgkmcnt(0)
	s_barrier
	v_mfma_f32_32x32x16_bf16 v[48:63], v[162:165], v[170:173], v[48:63]
	v_mfma_f32_32x32x16_bf16 v[32:47], v[162:165], v[174:177], v[32:47]
	s_waitcnt vmcnt(11)
	ds_write_b128 v235, v[64:67] offset:55296
	v_mfma_f32_32x32x16_bf16 v[16:31], v[166:169], v[170:173], v[16:31]
	v_mfma_f32_32x32x16_bf16 v[0:15], v[166:169], v[174:177], v[0:15]
	s_waitcnt vmcnt(10)
	ds_write_b128 v235, v[68:71] offset:64512
	v_mfma_f32_32x32x16_bf16 v[48:63], v[130:133], v[134:137], v[48:63]
	v_mfma_f32_32x32x16_bf16 v[32:47], v[130:133], v[150:153], v[32:47]
	s_waitcnt vmcnt(9)
	ds_write_b128 v239, v[80:83] offset:18432
	v_mfma_f32_32x32x16_bf16 v[16:31], v[142:145], v[134:137], v[16:31]
	v_mfma_f32_32x32x16_bf16 v[0:15], v[142:145], v[150:153], v[0:15]
	s_waitcnt vmcnt(8)
	ds_write_b128 v239, v[84:87] offset:27648
	v_mfma_f32_32x32x16_bf16 v[48:63], v[138:141], v[154:157], v[48:63]
	v_mfma_f32_32x32x16_bf16 v[32:47], v[138:141], v[158:161], v[32:47]
	s_waitcnt vmcnt(7)
	ds_write_b128 v240, v[96:99]
	v_mfma_f32_32x32x16_bf16 v[16:31], v[146:149], v[154:157], v[16:31]
	v_mfma_f32_32x32x16_bf16 v[0:15], v[146:149], v[158:161], v[0:15]
	s_waitcnt vmcnt(6)
	ds_write_b128 v240, v[100:103] offset:9216
	v_mfma_f32_32x32x16_bf16 v[48:63], v[116:119], v[120:123], v[48:63]
	v_mfma_f32_32x32x16_bf16 v[32:47], v[116:119], v[124:127], v[32:47]
	v_mfma_f32_32x32x16_bf16 v[16:31], v[112:115], v[120:123], v[16:31]
	v_mfma_f32_32x32x16_bf16 v[0:15], v[112:115], v[124:127], v[0:15]
	global_load_dwordx4 v[64:67], v[194:195], off offset:1408
	global_load_dwordx4 v[68:71], v[198:199], off offset:1408
	global_load_dwordx4 v[80:83], v[200:201], off offset:1408
	global_load_dwordx4 v[84:87], v[202:203], off offset:1408
	global_load_dwordx4 v[96:99], v[196:197], off offset:1408
	global_load_dwordx4 v[100:103], v[204:205], off offset:1408
	s_waitcnt lgkmcnt(0)
	s_barrier
	ds_read_b128 v[112:115], v237
	ds_read_b128 v[116:119], v237 offset:32
	ds_read_b128 v[120:123], v237 offset:4608
	ds_read_b128 v[124:127], v237 offset:4640
	ds_read_b128 v[130:133], v238 offset:36864
	ds_read_b128 v[134:137], v238 offset:36896
	ds_read_b128 v[138:141], v238 offset:41472
	ds_read_b128 v[142:145], v238 offset:41504
	ds_read_b128 v[146:149], v237 offset:64
	ds_read_b128 v[150:153], v237 offset:96
	ds_read_b128 v[154:157], v237 offset:4672
	ds_read_b128 v[158:161], v237 offset:4704
	ds_read_b128 v[162:165], v238 offset:36928
	ds_read_b128 v[166:169], v238 offset:36960
	ds_read_b128 v[170:173], v238 offset:41536
	ds_read_b128 v[174:177], v238 offset:41568
	s_waitcnt lgkmcnt(0)
	s_barrier
	v_mfma_f32_32x32x16_bf16 v[48:63], v[112:115], v[130:133], v[48:63]
	v_mfma_f32_32x32x16_bf16 v[32:47], v[112:115], v[138:141], v[32:47]
	s_waitcnt vmcnt(11)
	ds_write_b128 v235, v[72:75]
	v_mfma_f32_32x32x16_bf16 v[16:31], v[120:123], v[130:133], v[16:31]
	v_mfma_f32_32x32x16_bf16 v[0:15], v[120:123], v[138:141], v[0:15]
	s_waitcnt vmcnt(10)
	ds_write_b128 v235, v[76:79] offset:9216
	v_mfma_f32_32x32x16_bf16 v[48:63], v[116:119], v[134:137], v[48:63]
	v_mfma_f32_32x32x16_bf16 v[32:47], v[116:119], v[142:145], v[32:47]
	s_waitcnt vmcnt(9)
	ds_write_b128 v235, v[88:91] offset:18432
	v_mfma_f32_32x32x16_bf16 v[16:31], v[124:127], v[134:137], v[16:31]
	v_mfma_f32_32x32x16_bf16 v[0:15], v[124:127], v[142:145], v[0:15]
	s_waitcnt vmcnt(8)
	ds_write_b128 v235, v[92:95] offset:27648
	v_mfma_f32_32x32x16_bf16 v[48:63], v[146:149], v[162:165], v[48:63]
	v_mfma_f32_32x32x16_bf16 v[32:47], v[146:149], v[170:173], v[32:47]
	s_waitcnt vmcnt(7)
	ds_write_b128 v235, v[104:107] offset:36864
	v_mfma_f32_32x32x16_bf16 v[16:31], v[154:157], v[162:165], v[16:31]
	v_mfma_f32_32x32x16_bf16 v[0:15], v[154:157], v[170:173], v[0:15]
	s_waitcnt vmcnt(6)
	ds_write_b128 v235, v[108:111] offset:46080
	v_mfma_f32_32x32x16_bf16 v[48:63], v[150:153], v[166:169], v[48:63]
	v_mfma_f32_32x32x16_bf16 v[32:47], v[150:153], v[174:177], v[32:47]
	v_mfma_f32_32x32x16_bf16 v[16:31], v[158:161], v[166:169], v[16:31]
	v_mfma_f32_32x32x16_bf16 v[0:15], v[158:161], v[174:177], v[0:15]
	global_load_dwordx4 v[72:75], v[194:195], off offset:1536
	global_load_dwordx4 v[76:79], v[198:199], off offset:1536
	global_load_dwordx4 v[88:91], v[200:201], off offset:1536
	global_load_dwordx4 v[92:95], v[202:203], off offset:1536
	global_load_dwordx4 v[104:107], v[196:197], off offset:1536
	global_load_dwordx4 v[108:111], v[204:205], off offset:1536
	s_waitcnt lgkmcnt(0)
	s_barrier
	ds_read_b128 v[162:165], v237 offset:55296
	ds_read_b128 v[130:133], v237 offset:55328
	ds_read_b128 v[170:173], v241
	ds_read_b128 v[134:137], v241 offset:32
	ds_read_b128 v[166:169], v237 offset:59904
	ds_read_b128 v[142:145], v237 offset:59936
	ds_read_b128 v[174:177], v241 offset:4608
	ds_read_b128 v[150:153], v241 offset:4640
	ds_read_b128 v[138:141], v237 offset:55360
	ds_read_b128 v[116:119], v237 offset:55392
	ds_read_b128 v[146:149], v237 offset:59968
	ds_read_b128 v[112:115], v237 offset:60000
	ds_read_b128 v[154:157], v241 offset:64
	ds_read_b128 v[120:123], v241 offset:96
	ds_read_b128 v[158:161], v241 offset:4672
	ds_read_b128 v[124:127], v241 offset:4704
	s_waitcnt lgkmcnt(0)
	s_barrier
	v_mfma_f32_32x32x16_bf16 v[48:63], v[162:165], v[170:173], v[48:63]
	v_mfma_f32_32x32x16_bf16 v[32:47], v[162:165], v[174:177], v[32:47]
	s_waitcnt vmcnt(11)
	ds_write_b128 v235, v[64:67] offset:55296
	v_mfma_f32_32x32x16_bf16 v[16:31], v[166:169], v[170:173], v[16:31]
	v_mfma_f32_32x32x16_bf16 v[0:15], v[166:169], v[174:177], v[0:15]
	s_waitcnt vmcnt(10)
	ds_write_b128 v235, v[68:71] offset:64512
	v_mfma_f32_32x32x16_bf16 v[48:63], v[130:133], v[134:137], v[48:63]
	v_mfma_f32_32x32x16_bf16 v[32:47], v[130:133], v[150:153], v[32:47]
	s_waitcnt vmcnt(9)
	ds_write_b128 v239, v[80:83] offset:18432
	v_mfma_f32_32x32x16_bf16 v[16:31], v[142:145], v[134:137], v[16:31]
	v_mfma_f32_32x32x16_bf16 v[0:15], v[142:145], v[150:153], v[0:15]
	s_waitcnt vmcnt(8)
	ds_write_b128 v239, v[84:87] offset:27648
	v_mfma_f32_32x32x16_bf16 v[48:63], v[138:141], v[154:157], v[48:63]
	v_mfma_f32_32x32x16_bf16 v[32:47], v[138:141], v[158:161], v[32:47]
	s_waitcnt vmcnt(7)
	ds_write_b128 v240, v[96:99]
	v_mfma_f32_32x32x16_bf16 v[16:31], v[146:149], v[154:157], v[16:31]
	v_mfma_f32_32x32x16_bf16 v[0:15], v[146:149], v[158:161], v[0:15]
	s_waitcnt vmcnt(6)
	ds_write_b128 v240, v[100:103] offset:9216
	v_mfma_f32_32x32x16_bf16 v[48:63], v[116:119], v[120:123], v[48:63]
	v_mfma_f32_32x32x16_bf16 v[32:47], v[116:119], v[124:127], v[32:47]
	v_mfma_f32_32x32x16_bf16 v[16:31], v[112:115], v[120:123], v[16:31]
	v_mfma_f32_32x32x16_bf16 v[0:15], v[112:115], v[124:127], v[0:15]
	global_load_dwordx4 v[64:67], v[194:195], off offset:1664
	global_load_dwordx4 v[68:71], v[198:199], off offset:1664
	global_load_dwordx4 v[80:83], v[200:201], off offset:1664
	global_load_dwordx4 v[84:87], v[202:203], off offset:1664
	global_load_dwordx4 v[96:99], v[196:197], off offset:1664
	global_load_dwordx4 v[100:103], v[204:205], off offset:1664
	s_waitcnt lgkmcnt(0)
	s_barrier
	ds_read_b128 v[112:115], v237
	ds_read_b128 v[116:119], v237 offset:32
	ds_read_b128 v[120:123], v237 offset:4608
	ds_read_b128 v[124:127], v237 offset:4640
	ds_read_b128 v[130:133], v238 offset:36864
	ds_read_b128 v[134:137], v238 offset:36896
	ds_read_b128 v[138:141], v238 offset:41472
	ds_read_b128 v[142:145], v238 offset:41504
	ds_read_b128 v[146:149], v237 offset:64
	ds_read_b128 v[150:153], v237 offset:96
	ds_read_b128 v[154:157], v237 offset:4672
	ds_read_b128 v[158:161], v237 offset:4704
	ds_read_b128 v[162:165], v238 offset:36928
	ds_read_b128 v[166:169], v238 offset:36960
	ds_read_b128 v[170:173], v238 offset:41536
	ds_read_b128 v[174:177], v238 offset:41568
	s_waitcnt lgkmcnt(0)
	s_barrier
	v_mfma_f32_32x32x16_bf16 v[48:63], v[112:115], v[130:133], v[48:63]
	v_mfma_f32_32x32x16_bf16 v[32:47], v[112:115], v[138:141], v[32:47]
	s_waitcnt vmcnt(11)
	ds_write_b128 v235, v[72:75]
	v_mfma_f32_32x32x16_bf16 v[16:31], v[120:123], v[130:133], v[16:31]
	v_mfma_f32_32x32x16_bf16 v[0:15], v[120:123], v[138:141], v[0:15]
	s_waitcnt vmcnt(10)
	ds_write_b128 v235, v[76:79] offset:9216
	v_mfma_f32_32x32x16_bf16 v[48:63], v[116:119], v[134:137], v[48:63]
	v_mfma_f32_32x32x16_bf16 v[32:47], v[116:119], v[142:145], v[32:47]
	s_waitcnt vmcnt(9)
	ds_write_b128 v235, v[88:91] offset:18432
	v_mfma_f32_32x32x16_bf16 v[16:31], v[124:127], v[134:137], v[16:31]
	v_mfma_f32_32x32x16_bf16 v[0:15], v[124:127], v[142:145], v[0:15]
	s_waitcnt vmcnt(8)
	ds_write_b128 v235, v[92:95] offset:27648
	v_mfma_f32_32x32x16_bf16 v[48:63], v[146:149], v[162:165], v[48:63]
	v_mfma_f32_32x32x16_bf16 v[32:47], v[146:149], v[170:173], v[32:47]
	s_waitcnt vmcnt(7)
	ds_write_b128 v235, v[104:107] offset:36864
	v_mfma_f32_32x32x16_bf16 v[16:31], v[154:157], v[162:165], v[16:31]
	v_mfma_f32_32x32x16_bf16 v[0:15], v[154:157], v[170:173], v[0:15]
	s_waitcnt vmcnt(6)
	ds_write_b128 v235, v[108:111] offset:46080
	v_mfma_f32_32x32x16_bf16 v[48:63], v[150:153], v[166:169], v[48:63]
	v_mfma_f32_32x32x16_bf16 v[32:47], v[150:153], v[174:177], v[32:47]
	v_mfma_f32_32x32x16_bf16 v[16:31], v[158:161], v[166:169], v[16:31]
	v_mfma_f32_32x32x16_bf16 v[0:15], v[158:161], v[174:177], v[0:15]
	global_load_dwordx4 v[72:75], v[194:195], off offset:1792
	global_load_dwordx4 v[76:79], v[198:199], off offset:1792
	global_load_dwordx4 v[88:91], v[200:201], off offset:1792
	global_load_dwordx4 v[92:95], v[202:203], off offset:1792
	global_load_dwordx4 v[104:107], v[196:197], off offset:1792
	global_load_dwordx4 v[108:111], v[204:205], off offset:1792
	s_waitcnt lgkmcnt(0)
	s_barrier
	ds_read_b128 v[162:165], v237 offset:55296
	ds_read_b128 v[130:133], v237 offset:55328
	ds_read_b128 v[170:173], v241
	ds_read_b128 v[134:137], v241 offset:32
	ds_read_b128 v[166:169], v237 offset:59904
	ds_read_b128 v[142:145], v237 offset:59936
	ds_read_b128 v[174:177], v241 offset:4608
	ds_read_b128 v[150:153], v241 offset:4640
	ds_read_b128 v[138:141], v237 offset:55360
	ds_read_b128 v[116:119], v237 offset:55392
	ds_read_b128 v[146:149], v237 offset:59968
	ds_read_b128 v[112:115], v237 offset:60000
	ds_read_b128 v[154:157], v241 offset:64
	ds_read_b128 v[120:123], v241 offset:96
	ds_read_b128 v[158:161], v241 offset:4672
	ds_read_b128 v[124:127], v241 offset:4704
	s_waitcnt lgkmcnt(0)
	s_barrier
	v_mfma_f32_32x32x16_bf16 v[48:63], v[162:165], v[170:173], v[48:63]
	v_mfma_f32_32x32x16_bf16 v[32:47], v[162:165], v[174:177], v[32:47]
	s_waitcnt vmcnt(11)
	ds_write_b128 v235, v[64:67] offset:55296
	v_mfma_f32_32x32x16_bf16 v[16:31], v[166:169], v[170:173], v[16:31]
	v_mfma_f32_32x32x16_bf16 v[0:15], v[166:169], v[174:177], v[0:15]
	s_waitcnt vmcnt(10)
	ds_write_b128 v235, v[68:71] offset:64512
	v_mfma_f32_32x32x16_bf16 v[48:63], v[130:133], v[134:137], v[48:63]
	v_mfma_f32_32x32x16_bf16 v[32:47], v[130:133], v[150:153], v[32:47]
	s_waitcnt vmcnt(9)
	ds_write_b128 v239, v[80:83] offset:18432
	v_mfma_f32_32x32x16_bf16 v[16:31], v[142:145], v[134:137], v[16:31]
	v_mfma_f32_32x32x16_bf16 v[0:15], v[142:145], v[150:153], v[0:15]
	s_waitcnt vmcnt(8)
	ds_write_b128 v239, v[84:87] offset:27648
	v_mfma_f32_32x32x16_bf16 v[48:63], v[138:141], v[154:157], v[48:63]
	v_mfma_f32_32x32x16_bf16 v[32:47], v[138:141], v[158:161], v[32:47]
	s_waitcnt vmcnt(7)
	ds_write_b128 v240, v[96:99]
	v_mfma_f32_32x32x16_bf16 v[16:31], v[146:149], v[154:157], v[16:31]
	v_mfma_f32_32x32x16_bf16 v[0:15], v[146:149], v[158:161], v[0:15]
	s_waitcnt vmcnt(6)
	ds_write_b128 v240, v[100:103] offset:9216
	v_mfma_f32_32x32x16_bf16 v[48:63], v[116:119], v[120:123], v[48:63]
	v_mfma_f32_32x32x16_bf16 v[32:47], v[116:119], v[124:127], v[32:47]
	v_mfma_f32_32x32x16_bf16 v[16:31], v[112:115], v[120:123], v[16:31]
	v_mfma_f32_32x32x16_bf16 v[0:15], v[112:115], v[124:127], v[0:15]
	global_load_dwordx4 v[64:67], v[194:195], off offset:1920
	global_load_dwordx4 v[68:71], v[198:199], off offset:1920
	global_load_dwordx4 v[80:83], v[200:201], off offset:1920
	global_load_dwordx4 v[84:87], v[202:203], off offset:1920
	global_load_dwordx4 v[96:99], v[196:197], off offset:1920
	global_load_dwordx4 v[100:103], v[204:205], off offset:1920
	s_waitcnt lgkmcnt(0)
	s_barrier
	ds_read_b128 v[112:115], v237
	ds_read_b128 v[116:119], v237 offset:32
	ds_read_b128 v[120:123], v237 offset:4608
	ds_read_b128 v[124:127], v237 offset:4640
	ds_read_b128 v[130:133], v238 offset:36864
	ds_read_b128 v[134:137], v238 offset:36896
	ds_read_b128 v[138:141], v238 offset:41472
	ds_read_b128 v[142:145], v238 offset:41504
	ds_read_b128 v[146:149], v237 offset:64
	ds_read_b128 v[150:153], v237 offset:96
	ds_read_b128 v[154:157], v237 offset:4672
	ds_read_b128 v[158:161], v237 offset:4704
	ds_read_b128 v[162:165], v238 offset:36928
	ds_read_b128 v[166:169], v238 offset:36960
	ds_read_b128 v[170:173], v238 offset:41536
	ds_read_b128 v[174:177], v238 offset:41568
	s_waitcnt lgkmcnt(0)
	s_barrier
	v_mfma_f32_32x32x16_bf16 v[48:63], v[112:115], v[130:133], v[48:63]
	v_mfma_f32_32x32x16_bf16 v[32:47], v[112:115], v[138:141], v[32:47]
	s_waitcnt vmcnt(11)
	ds_write_b128 v235, v[72:75]
	v_mfma_f32_32x32x16_bf16 v[16:31], v[120:123], v[130:133], v[16:31]
	v_mfma_f32_32x32x16_bf16 v[0:15], v[120:123], v[138:141], v[0:15]
	s_waitcnt vmcnt(10)
	ds_write_b128 v235, v[76:79] offset:9216
	v_mfma_f32_32x32x16_bf16 v[48:63], v[116:119], v[134:137], v[48:63]
	v_mfma_f32_32x32x16_bf16 v[32:47], v[116:119], v[142:145], v[32:47]
	s_waitcnt vmcnt(9)
	ds_write_b128 v235, v[88:91] offset:18432
	v_mfma_f32_32x32x16_bf16 v[16:31], v[124:127], v[134:137], v[16:31]
	v_mfma_f32_32x32x16_bf16 v[0:15], v[124:127], v[142:145], v[0:15]
	s_waitcnt vmcnt(8)
	ds_write_b128 v235, v[92:95] offset:27648
	v_mfma_f32_32x32x16_bf16 v[48:63], v[146:149], v[162:165], v[48:63]
	v_mfma_f32_32x32x16_bf16 v[32:47], v[146:149], v[170:173], v[32:47]
	s_waitcnt vmcnt(7)
	ds_write_b128 v235, v[104:107] offset:36864
	v_mfma_f32_32x32x16_bf16 v[16:31], v[154:157], v[162:165], v[16:31]
	v_mfma_f32_32x32x16_bf16 v[0:15], v[154:157], v[170:173], v[0:15]
	s_waitcnt vmcnt(6)
	ds_write_b128 v235, v[108:111] offset:46080
	v_mfma_f32_32x32x16_bf16 v[48:63], v[150:153], v[166:169], v[48:63]
	v_mfma_f32_32x32x16_bf16 v[32:47], v[150:153], v[174:177], v[32:47]
	v_mfma_f32_32x32x16_bf16 v[16:31], v[158:161], v[166:169], v[16:31]
	v_mfma_f32_32x32x16_bf16 v[0:15], v[158:161], v[174:177], v[0:15]
	s_waitcnt lgkmcnt(0)
	s_barrier
	ds_read_b128 v[162:165], v237 offset:55296
	ds_read_b128 v[130:133], v237 offset:55328
	ds_read_b128 v[170:173], v241
	ds_read_b128 v[134:137], v241 offset:32
	ds_read_b128 v[166:169], v237 offset:59904
	ds_read_b128 v[142:145], v237 offset:59936
	ds_read_b128 v[174:177], v241 offset:4608
	ds_read_b128 v[150:153], v241 offset:4640
	ds_read_b128 v[138:141], v237 offset:55360
	ds_read_b128 v[116:119], v237 offset:55392
	ds_read_b128 v[146:149], v237 offset:59968
	ds_read_b128 v[112:115], v237 offset:60000
	ds_read_b128 v[154:157], v241 offset:64
	ds_read_b128 v[120:123], v241 offset:96
	ds_read_b128 v[158:161], v241 offset:4672
	ds_read_b128 v[124:127], v241 offset:4704
	s_waitcnt lgkmcnt(0)
	s_barrier
	v_mfma_f32_32x32x16_bf16 v[48:63], v[162:165], v[170:173], v[48:63]
	v_mfma_f32_32x32x16_bf16 v[32:47], v[162:165], v[174:177], v[32:47]
	s_waitcnt vmcnt(5)
	ds_write_b128 v235, v[64:67] offset:55296
	v_mfma_f32_32x32x16_bf16 v[16:31], v[166:169], v[170:173], v[16:31]
	v_mfma_f32_32x32x16_bf16 v[0:15], v[166:169], v[174:177], v[0:15]
	s_waitcnt vmcnt(4)
	ds_write_b128 v235, v[68:71] offset:64512
	v_mfma_f32_32x32x16_bf16 v[48:63], v[130:133], v[134:137], v[48:63]
	v_mfma_f32_32x32x16_bf16 v[32:47], v[130:133], v[150:153], v[32:47]
	s_waitcnt vmcnt(3)
	ds_write_b128 v239, v[80:83] offset:18432
	v_mfma_f32_32x32x16_bf16 v[16:31], v[142:145], v[134:137], v[16:31]
	v_mfma_f32_32x32x16_bf16 v[0:15], v[142:145], v[150:153], v[0:15]
	s_waitcnt vmcnt(2)
	ds_write_b128 v239, v[84:87] offset:27648
	v_mfma_f32_32x32x16_bf16 v[48:63], v[138:141], v[154:157], v[48:63]
	v_mfma_f32_32x32x16_bf16 v[32:47], v[138:141], v[158:161], v[32:47]
	s_waitcnt vmcnt(1)
	ds_write_b128 v240, v[96:99]
	v_mfma_f32_32x32x16_bf16 v[16:31], v[146:149], v[154:157], v[16:31]
	v_mfma_f32_32x32x16_bf16 v[0:15], v[146:149], v[158:161], v[0:15]
	s_waitcnt vmcnt(0)
	ds_write_b128 v240, v[100:103] offset:9216
	v_mfma_f32_32x32x16_bf16 v[48:63], v[116:119], v[120:123], v[48:63]
	v_mfma_f32_32x32x16_bf16 v[32:47], v[116:119], v[124:127], v[32:47]
	v_mfma_f32_32x32x16_bf16 v[16:31], v[112:115], v[120:123], v[16:31]
	v_mfma_f32_32x32x16_bf16 v[0:15], v[112:115], v[124:127], v[0:15]
	s_waitcnt lgkmcnt(0)
	s_barrier
	ds_read_b128 v[112:115], v237
	ds_read_b128 v[116:119], v237 offset:32
	ds_read_b128 v[120:123], v237 offset:4608
	ds_read_b128 v[124:127], v237 offset:4640
	ds_read_b128 v[130:133], v238 offset:36864
	ds_read_b128 v[134:137], v238 offset:36896
	ds_read_b128 v[138:141], v238 offset:41472
	ds_read_b128 v[142:145], v238 offset:41504
	ds_read_b128 v[146:149], v237 offset:64
	ds_read_b128 v[150:153], v237 offset:96
	ds_read_b128 v[154:157], v237 offset:4672
	ds_read_b128 v[158:161], v237 offset:4704
	ds_read_b128 v[162:165], v238 offset:36928
	ds_read_b128 v[166:169], v238 offset:36960
	ds_read_b128 v[170:173], v238 offset:41536
	ds_read_b128 v[174:177], v238 offset:41568
	s_waitcnt lgkmcnt(0)
	s_barrier
	v_mfma_f32_32x32x16_bf16 v[48:63], v[112:115], v[130:133], v[48:63]
	v_mfma_f32_32x32x16_bf16 v[32:47], v[112:115], v[138:141], v[32:47]
	v_mfma_f32_32x32x16_bf16 v[16:31], v[120:123], v[130:133], v[16:31]
	v_mfma_f32_32x32x16_bf16 v[0:15], v[120:123], v[138:141], v[0:15]
	v_mfma_f32_32x32x16_bf16 v[48:63], v[116:119], v[134:137], v[48:63]
	v_mfma_f32_32x32x16_bf16 v[32:47], v[116:119], v[142:145], v[32:47]
	v_mfma_f32_32x32x16_bf16 v[16:31], v[124:127], v[134:137], v[16:31]
	v_mfma_f32_32x32x16_bf16 v[0:15], v[124:127], v[142:145], v[0:15]
	v_mfma_f32_32x32x16_bf16 v[48:63], v[146:149], v[162:165], v[48:63]
	v_mfma_f32_32x32x16_bf16 v[32:47], v[146:149], v[170:173], v[32:47]
	v_mfma_f32_32x32x16_bf16 v[16:31], v[154:157], v[162:165], v[16:31]
	v_mfma_f32_32x32x16_bf16 v[0:15], v[154:157], v[170:173], v[0:15]
	v_mfma_f32_32x32x16_bf16 v[48:63], v[150:153], v[166:169], v[48:63]
	v_mfma_f32_32x32x16_bf16 v[32:47], v[150:153], v[174:177], v[32:47]
	v_mfma_f32_32x32x16_bf16 v[16:31], v[158:161], v[166:169], v[16:31]
	v_mfma_f32_32x32x16_bf16 v[0:15], v[158:161], v[174:177], v[0:15]
	s_waitcnt lgkmcnt(0)
	s_barrier
	ds_read_b128 v[162:165], v237 offset:55296
	ds_read_b128 v[130:133], v237 offset:55328
	ds_read_b128 v[170:173], v241
	ds_read_b128 v[134:137], v241 offset:32
	ds_read_b128 v[166:169], v237 offset:59904
	ds_read_b128 v[142:145], v237 offset:59936
	ds_read_b128 v[174:177], v241 offset:4608
	ds_read_b128 v[150:153], v241 offset:4640
	ds_read_b128 v[138:141], v237 offset:55360
	ds_read_b128 v[116:119], v237 offset:55392
	ds_read_b128 v[146:149], v237 offset:59968
	ds_read_b128 v[112:115], v237 offset:60000
	ds_read_b128 v[154:157], v241 offset:64
	ds_read_b128 v[120:123], v241 offset:96
	ds_read_b128 v[158:161], v241 offset:4672
	ds_read_b128 v[124:127], v241 offset:4704
	s_waitcnt lgkmcnt(0)
	s_barrier
	v_mfma_f32_32x32x16_bf16 v[48:63], v[162:165], v[170:173], v[48:63]
	v_mfma_f32_32x32x16_bf16 v[32:47], v[162:165], v[174:177], v[32:47]
	v_mfma_f32_32x32x16_bf16 v[16:31], v[166:169], v[170:173], v[16:31]
	v_mfma_f32_32x32x16_bf16 v[0:15], v[166:169], v[174:177], v[0:15]
	v_mfma_f32_32x32x16_bf16 v[48:63], v[130:133], v[134:137], v[48:63]
	v_mfma_f32_32x32x16_bf16 v[32:47], v[130:133], v[150:153], v[32:47]
	v_mfma_f32_32x32x16_bf16 v[16:31], v[142:145], v[134:137], v[16:31]
	v_mfma_f32_32x32x16_bf16 v[0:15], v[142:145], v[150:153], v[0:15]
	v_mfma_f32_32x32x16_bf16 v[48:63], v[138:141], v[154:157], v[48:63]
	v_mfma_f32_32x32x16_bf16 v[32:47], v[138:141], v[158:161], v[32:47]
	v_mfma_f32_32x32x16_bf16 v[16:31], v[146:149], v[154:157], v[16:31]
	v_mfma_f32_32x32x16_bf16 v[0:15], v[146:149], v[158:161], v[0:15]
	v_mfma_f32_32x32x16_bf16 v[48:63], v[116:119], v[120:123], v[48:63]
	v_mfma_f32_32x32x16_bf16 v[32:47], v[116:119], v[124:127], v[32:47]
	v_mfma_f32_32x32x16_bf16 v[16:31], v[112:115], v[120:123], v[16:31]
	v_mfma_f32_32x32x16_bf16 v[0:15], v[112:115], v[124:127], v[0:15]
	s_waitcnt lgkmcnt(0)
	s_barrier
	s_branch .LBB0_207

.LBB0_211:
	s_waitcnt lgkmcnt(13)
	v_mfma_f32_32x32x16_bf16 v[48:63], v[116:119], v[124:127], v[48:63]
	s_waitcnt lgkmcnt(9)
	v_mfma_f32_32x32x16_bf16 v[32:47], v[116:119], v[154:157], v[32:47]
	v_mfma_f32_32x32x16_bf16 v[16:31], v[134:137], v[124:127], v[16:31]
	v_mfma_f32_32x32x16_bf16 v[0:15], v[134:137], v[154:157], v[0:15]
	v_mfma_f32_32x32x16_bf16 v[48:63], v[112:115], v[120:123], v[48:63]
	s_waitcnt lgkmcnt(8)
	v_mfma_f32_32x32x16_bf16 v[32:47], v[112:115], v[142:145], v[32:47]
	v_mfma_f32_32x32x16_bf16 v[16:31], v[130:133], v[120:123], v[16:31]
	v_mfma_f32_32x32x16_bf16 v[0:15], v[130:133], v[142:145], v[0:15]
	s_waitcnt lgkmcnt(3)
	v_mfma_f32_32x32x16_bf16 v[48:63], v[138:141], v[170:173], v[48:63]
	s_waitcnt lgkmcnt(1)
	v_mfma_f32_32x32x16_bf16 v[32:47], v[138:141], v[174:177], v[32:47]
	v_mfma_f32_32x32x16_bf16 v[16:31], v[158:161], v[170:173], v[16:31]
	v_mfma_f32_32x32x16_bf16 v[0:15], v[158:161], v[174:177], v[0:15]
	v_mfma_f32_32x32x16_bf16 v[48:63], v[146:149], v[162:165], v[48:63]
	s_waitcnt lgkmcnt(0)
	v_mfma_f32_32x32x16_bf16 v[32:47], v[146:149], v[166:169], v[32:47]
	v_mfma_f32_32x32x16_bf16 v[16:31], v[150:153], v[162:165], v[16:31]
	v_mfma_f32_32x32x16_bf16 v[0:15], v[150:153], v[166:169], v[0:15]
	s_waitcnt lgkmcnt(0)
	s_barrier
	ds_read_b128 v[116:119], v237 offset:55296
	ds_read_b128 v[112:115], v237 offset:55328
	ds_read_b128 v[124:127], v241
	ds_read_b128 v[120:123], v241 offset:32
	ds_read_b128 v[134:137], v237 offset:59904
	ds_read_b128 v[130:133], v237 offset:59936
	ds_read_b128 v[154:157], v241 offset:4608
	ds_read_b128 v[142:145], v241 offset:4640
	ds_read_b128 v[138:141], v237 offset:55360
	ds_read_b128 v[146:149], v237 offset:55392
	ds_read_b128 v[158:161], v237 offset:59968
	ds_read_b128 v[150:153], v237 offset:60000
	ds_read_b128 v[170:173], v241 offset:64
	ds_read_b128 v[162:165], v241 offset:96
	ds_read_b128 v[174:177], v241 offset:4672
	ds_read_b128 v[166:169], v241 offset:4704
	s_waitcnt lgkmcnt(0)
	s_barrier
	v_mfma_f32_32x32x16_bf16 v[48:63], v[116:119], v[124:127], v[48:63]
	v_mfma_f32_32x32x16_bf16 v[32:47], v[116:119], v[154:157], v[32:47]
	s_waitcnt vmcnt(11)
	ds_write_b128 v235, v[64:67]
	v_mfma_f32_32x32x16_bf16 v[16:31], v[134:137], v[124:127], v[16:31]
	v_mfma_f32_32x32x16_bf16 v[0:15], v[134:137], v[154:157], v[0:15]
	s_waitcnt vmcnt(10)
	ds_write_b128 v235, v[68:71] offset:9216
	v_mfma_f32_32x32x16_bf16 v[48:63], v[112:115], v[120:123], v[48:63]
	v_mfma_f32_32x32x16_bf16 v[32:47], v[112:115], v[142:145], v[32:47]
	s_waitcnt vmcnt(8)
	ds_write_b128 v235, v[84:87] offset:18432
	v_mfma_f32_32x32x16_bf16 v[16:31], v[130:133], v[120:123], v[16:31]
	v_mfma_f32_32x32x16_bf16 v[0:15], v[130:133], v[142:145], v[0:15]
	ds_write_b128 v235, v[72:75] offset:27648
	v_mfma_f32_32x32x16_bf16 v[48:63], v[138:141], v[170:173], v[48:63]
	v_mfma_f32_32x32x16_bf16 v[32:47], v[138:141], v[174:177], v[32:47]
	s_waitcnt vmcnt(7)
	ds_write_b128 v235, v[96:99] offset:36864
	v_mfma_f32_32x32x16_bf16 v[16:31], v[158:161], v[170:173], v[16:31]
	v_mfma_f32_32x32x16_bf16 v[0:15], v[158:161], v[174:177], v[0:15]
	s_waitcnt vmcnt(6)
	ds_write_b128 v235, v[100:103] offset:46080
	v_mfma_f32_32x32x16_bf16 v[48:63], v[146:149], v[162:165], v[48:63]
	v_mfma_f32_32x32x16_bf16 v[32:47], v[146:149], v[166:169], v[32:47]
	v_mfma_f32_32x32x16_bf16 v[16:31], v[150:153], v[162:165], v[16:31]
	v_mfma_f32_32x32x16_bf16 v[0:15], v[150:153], v[166:169], v[0:15]
	global_load_dwordx4 v[64:67], v[194:195], off offset:512
	global_load_dwordx4 v[68:71], v[198:199], off offset:512
	global_load_dwordx4 v[84:87], v[200:201], off offset:512
	global_load_dwordx4 v[72:75], v[202:203], off offset:512
	global_load_dwordx4 v[96:99], v[196:197], off offset:512
	global_load_dwordx4 v[100:103], v[204:205], off offset:512
	s_waitcnt lgkmcnt(0)
	s_barrier
	ds_read_b128 v[116:119], v237
	ds_read_b128 v[112:115], v237 offset:32
	ds_read_b128 v[124:127], v238 offset:36864
	ds_read_b128 v[120:123], v238 offset:36896
	ds_read_b128 v[134:137], v237 offset:4608
	ds_read_b128 v[130:133], v237 offset:4640
	ds_read_b128 v[154:157], v238 offset:41472
	ds_read_b128 v[142:145], v238 offset:41504
	ds_read_b128 v[138:141], v237 offset:64
	ds_read_b128 v[146:149], v237 offset:96
	ds_read_b128 v[158:161], v237 offset:4672
	ds_read_b128 v[150:153], v237 offset:4704
	ds_read_b128 v[170:173], v238 offset:36928
	ds_read_b128 v[162:165], v238 offset:36960
	ds_read_b128 v[174:177], v238 offset:41536
	ds_read_b128 v[166:169], v238 offset:41568
	s_waitcnt lgkmcnt(0)
	s_barrier
	v_mfma_f32_32x32x16_bf16 v[48:63], v[116:119], v[124:127], v[48:63]
	v_mfma_f32_32x32x16_bf16 v[32:47], v[116:119], v[154:157], v[32:47]
	s_waitcnt vmcnt(11)
	ds_write_b128 v235, v[76:79] offset:55296
	v_mfma_f32_32x32x16_bf16 v[16:31], v[134:137], v[124:127], v[16:31]
	v_mfma_f32_32x32x16_bf16 v[0:15], v[134:137], v[154:157], v[0:15]
	s_waitcnt vmcnt(10)
	ds_write_b128 v235, v[80:83] offset:64512
	v_mfma_f32_32x32x16_bf16 v[48:63], v[112:115], v[120:123], v[48:63]
	v_mfma_f32_32x32x16_bf16 v[32:47], v[112:115], v[142:145], v[32:47]
	s_waitcnt vmcnt(9)
	ds_write_b128 v239, v[88:91] offset:18432
	v_mfma_f32_32x32x16_bf16 v[16:31], v[130:133], v[120:123], v[16:31]
	v_mfma_f32_32x32x16_bf16 v[0:15], v[130:133], v[142:145], v[0:15]
	s_waitcnt vmcnt(8)
	ds_write_b128 v239, v[92:95] offset:27648
	v_mfma_f32_32x32x16_bf16 v[48:63], v[138:141], v[170:173], v[48:63]
	v_mfma_f32_32x32x16_bf16 v[32:47], v[138:141], v[174:177], v[32:47]
	s_waitcnt vmcnt(7)
	ds_write_b128 v240, v[104:107]
	v_mfma_f32_32x32x16_bf16 v[16:31], v[158:161], v[170:173], v[16:31]
	v_mfma_f32_32x32x16_bf16 v[0:15], v[158:161], v[174:177], v[0:15]
	s_waitcnt vmcnt(6)
	ds_write_b128 v240, v[108:111] offset:9216
	v_mfma_f32_32x32x16_bf16 v[48:63], v[146:149], v[162:165], v[48:63]
	v_mfma_f32_32x32x16_bf16 v[32:47], v[146:149], v[166:169], v[32:47]
	v_mfma_f32_32x32x16_bf16 v[16:31], v[150:153], v[162:165], v[16:31]
	v_mfma_f32_32x32x16_bf16 v[0:15], v[150:153], v[166:169], v[0:15]
	global_load_dwordx4 v[76:79], v[194:195], off offset:640
	global_load_dwordx4 v[80:83], v[198:199], off offset:640
	global_load_dwordx4 v[88:91], v[200:201], off offset:640
	global_load_dwordx4 v[92:95], v[202:203], off offset:640
	global_load_dwordx4 v[104:107], v[196:197], off offset:640
	global_load_dwordx4 v[108:111], v[204:205], off offset:640
	s_waitcnt lgkmcnt(0)
	s_barrier
	ds_read_b128 v[116:119], v237 offset:55296
	ds_read_b128 v[112:115], v237 offset:55328
	ds_read_b128 v[124:127], v241
	ds_read_b128 v[120:123], v241 offset:32
	ds_read_b128 v[134:137], v237 offset:59904
	ds_read_b128 v[130:133], v237 offset:59936
	ds_read_b128 v[154:157], v241 offset:4608
	ds_read_b128 v[142:145], v241 offset:4640
	ds_read_b128 v[138:141], v237 offset:55360
	ds_read_b128 v[146:149], v237 offset:55392
	ds_read_b128 v[158:161], v237 offset:59968
	ds_read_b128 v[150:153], v237 offset:60000
	ds_read_b128 v[170:173], v241 offset:64
	ds_read_b128 v[162:165], v241 offset:96
	ds_read_b128 v[174:177], v241 offset:4672
	ds_read_b128 v[166:169], v241 offset:4704
	s_waitcnt lgkmcnt(0)
	s_barrier
	v_mfma_f32_32x32x16_bf16 v[48:63], v[116:119], v[124:127], v[48:63]
	v_mfma_f32_32x32x16_bf16 v[32:47], v[116:119], v[154:157], v[32:47]
	s_waitcnt vmcnt(11)
	ds_write_b128 v235, v[64:67]
	v_mfma_f32_32x32x16_bf16 v[16:31], v[134:137], v[124:127], v[16:31]
	v_mfma_f32_32x32x16_bf16 v[0:15], v[134:137], v[154:157], v[0:15]
	s_waitcnt vmcnt(10)
	ds_write_b128 v235, v[68:71] offset:9216
	v_mfma_f32_32x32x16_bf16 v[48:63], v[112:115], v[120:123], v[48:63]
	v_mfma_f32_32x32x16_bf16 v[32:47], v[112:115], v[142:145], v[32:47]
	s_waitcnt vmcnt(9)
	ds_write_b128 v235, v[84:87] offset:18432
	v_mfma_f32_32x32x16_bf16 v[16:31], v[130:133], v[120:123], v[16:31]
	v_mfma_f32_32x32x16_bf16 v[0:15], v[130:133], v[142:145], v[0:15]
	s_waitcnt vmcnt(8)
	ds_write_b128 v235, v[72:75] offset:27648
	v_mfma_f32_32x32x16_bf16 v[48:63], v[138:141], v[170:173], v[48:63]
	v_mfma_f32_32x32x16_bf16 v[32:47], v[138:141], v[174:177], v[32:47]
	s_waitcnt vmcnt(7)
	ds_write_b128 v235, v[96:99] offset:36864
	v_mfma_f32_32x32x16_bf16 v[16:31], v[158:161], v[170:173], v[16:31]
	v_mfma_f32_32x32x16_bf16 v[0:15], v[158:161], v[174:177], v[0:15]
	s_waitcnt vmcnt(6)
	ds_write_b128 v235, v[100:103] offset:46080
	v_mfma_f32_32x32x16_bf16 v[48:63], v[146:149], v[162:165], v[48:63]
	v_mfma_f32_32x32x16_bf16 v[32:47], v[146:149], v[166:169], v[32:47]
	v_mfma_f32_32x32x16_bf16 v[16:31], v[150:153], v[162:165], v[16:31]
	v_mfma_f32_32x32x16_bf16 v[0:15], v[150:153], v[166:169], v[0:15]
	global_load_dwordx4 v[64:67], v[194:195], off offset:768
	global_load_dwordx4 v[68:71], v[198:199], off offset:768
	global_load_dwordx4 v[84:87], v[200:201], off offset:768
	global_load_dwordx4 v[72:75], v[202:203], off offset:768
	global_load_dwordx4 v[96:99], v[196:197], off offset:768
	global_load_dwordx4 v[100:103], v[204:205], off offset:768
	s_waitcnt lgkmcnt(0)
	s_barrier
	ds_read_b128 v[116:119], v237
	ds_read_b128 v[112:115], v237 offset:32
	ds_read_b128 v[124:127], v238 offset:36864
	ds_read_b128 v[120:123], v238 offset:36896
	ds_read_b128 v[134:137], v237 offset:4608
	ds_read_b128 v[130:133], v237 offset:4640
	ds_read_b128 v[154:157], v238 offset:41472
	ds_read_b128 v[142:145], v238 offset:41504
	ds_read_b128 v[138:141], v237 offset:64
	ds_read_b128 v[146:149], v237 offset:96
	ds_read_b128 v[158:161], v237 offset:4672
	ds_read_b128 v[150:153], v237 offset:4704
	ds_read_b128 v[170:173], v238 offset:36928
	ds_read_b128 v[162:165], v238 offset:36960
	ds_read_b128 v[174:177], v238 offset:41536
	ds_read_b128 v[166:169], v238 offset:41568
	s_waitcnt lgkmcnt(0)
	s_barrier
	v_mfma_f32_32x32x16_bf16 v[48:63], v[116:119], v[124:127], v[48:63]
	v_mfma_f32_32x32x16_bf16 v[32:47], v[116:119], v[154:157], v[32:47]
	s_waitcnt vmcnt(11)
	ds_write_b128 v235, v[76:79] offset:55296
	v_mfma_f32_32x32x16_bf16 v[16:31], v[134:137], v[124:127], v[16:31]
	v_mfma_f32_32x32x16_bf16 v[0:15], v[134:137], v[154:157], v[0:15]
	s_waitcnt vmcnt(10)
	ds_write_b128 v235, v[80:83] offset:64512
	v_mfma_f32_32x32x16_bf16 v[48:63], v[112:115], v[120:123], v[48:63]
	v_mfma_f32_32x32x16_bf16 v[32:47], v[112:115], v[142:145], v[32:47]
	s_waitcnt vmcnt(9)
	ds_write_b128 v239, v[88:91] offset:18432
	v_mfma_f32_32x32x16_bf16 v[16:31], v[130:133], v[120:123], v[16:31]
	v_mfma_f32_32x32x16_bf16 v[0:15], v[130:133], v[142:145], v[0:15]
	s_waitcnt vmcnt(8)
	ds_write_b128 v239, v[92:95] offset:27648
	v_mfma_f32_32x32x16_bf16 v[48:63], v[138:141], v[170:173], v[48:63]
	v_mfma_f32_32x32x16_bf16 v[32:47], v[138:141], v[174:177], v[32:47]
	s_waitcnt vmcnt(7)
	ds_write_b128 v240, v[104:107]
	v_mfma_f32_32x32x16_bf16 v[16:31], v[158:161], v[170:173], v[16:31]
	v_mfma_f32_32x32x16_bf16 v[0:15], v[158:161], v[174:177], v[0:15]
	s_waitcnt vmcnt(6)
	ds_write_b128 v240, v[108:111] offset:9216
	v_mfma_f32_32x32x16_bf16 v[48:63], v[146:149], v[162:165], v[48:63]
	v_mfma_f32_32x32x16_bf16 v[32:47], v[146:149], v[166:169], v[32:47]
	v_mfma_f32_32x32x16_bf16 v[16:31], v[150:153], v[162:165], v[16:31]
	v_mfma_f32_32x32x16_bf16 v[0:15], v[150:153], v[166:169], v[0:15]
	global_load_dwordx4 v[76:79], v[194:195], off offset:896
	global_load_dwordx4 v[80:83], v[198:199], off offset:896
	global_load_dwordx4 v[88:91], v[200:201], off offset:896
	global_load_dwordx4 v[92:95], v[202:203], off offset:896
	global_load_dwordx4 v[104:107], v[196:197], off offset:896
	global_load_dwordx4 v[108:111], v[204:205], off offset:896
	s_waitcnt lgkmcnt(0)
	s_barrier
	ds_read_b128 v[116:119], v237 offset:55296
	ds_read_b128 v[112:115], v237 offset:55328
	ds_read_b128 v[124:127], v241
	ds_read_b128 v[120:123], v241 offset:32
	ds_read_b128 v[134:137], v237 offset:59904
	ds_read_b128 v[130:133], v237 offset:59936
	ds_read_b128 v[154:157], v241 offset:4608
	ds_read_b128 v[142:145], v241 offset:4640
	ds_read_b128 v[138:141], v237 offset:55360
	ds_read_b128 v[146:149], v237 offset:55392
	ds_read_b128 v[158:161], v237 offset:59968
	ds_read_b128 v[150:153], v237 offset:60000
	ds_read_b128 v[170:173], v241 offset:64
	ds_read_b128 v[162:165], v241 offset:96
	ds_read_b128 v[174:177], v241 offset:4672
	ds_read_b128 v[166:169], v241 offset:4704
	s_waitcnt lgkmcnt(0)
	s_barrier
	v_mfma_f32_32x32x16_bf16 v[48:63], v[116:119], v[124:127], v[48:63]
	v_mfma_f32_32x32x16_bf16 v[32:47], v[116:119], v[154:157], v[32:47]
	s_waitcnt vmcnt(11)
	ds_write_b128 v235, v[64:67]
	v_mfma_f32_32x32x16_bf16 v[16:31], v[134:137], v[124:127], v[16:31]
	v_mfma_f32_32x32x16_bf16 v[0:15], v[134:137], v[154:157], v[0:15]
	s_waitcnt vmcnt(10)
	ds_write_b128 v235, v[68:71] offset:9216
	v_mfma_f32_32x32x16_bf16 v[48:63], v[112:115], v[120:123], v[48:63]
	v_mfma_f32_32x32x16_bf16 v[32:47], v[112:115], v[142:145], v[32:47]
	s_waitcnt vmcnt(9)
	ds_write_b128 v235, v[84:87] offset:18432
	v_mfma_f32_32x32x16_bf16 v[16:31], v[130:133], v[120:123], v[16:31]
	v_mfma_f32_32x32x16_bf16 v[0:15], v[130:133], v[142:145], v[0:15]
	s_waitcnt vmcnt(8)
	ds_write_b128 v235, v[72:75] offset:27648
	v_mfma_f32_32x32x16_bf16 v[48:63], v[138:141], v[170:173], v[48:63]
	v_mfma_f32_32x32x16_bf16 v[32:47], v[138:141], v[174:177], v[32:47]
	s_waitcnt vmcnt(7)
	ds_write_b128 v235, v[96:99] offset:36864
	v_mfma_f32_32x32x16_bf16 v[16:31], v[158:161], v[170:173], v[16:31]
	v_mfma_f32_32x32x16_bf16 v[0:15], v[158:161], v[174:177], v[0:15]
	s_waitcnt vmcnt(6)
	ds_write_b128 v235, v[100:103] offset:46080
	v_mfma_f32_32x32x16_bf16 v[48:63], v[146:149], v[162:165], v[48:63]
	v_mfma_f32_32x32x16_bf16 v[32:47], v[146:149], v[166:169], v[32:47]
	v_mfma_f32_32x32x16_bf16 v[16:31], v[150:153], v[162:165], v[16:31]
	v_mfma_f32_32x32x16_bf16 v[0:15], v[150:153], v[166:169], v[0:15]
	global_load_dwordx4 v[64:67], v[194:195], off offset:1024
	global_load_dwordx4 v[68:71], v[198:199], off offset:1024
	global_load_dwordx4 v[84:87], v[200:201], off offset:1024
	global_load_dwordx4 v[72:75], v[202:203], off offset:1024
	global_load_dwordx4 v[96:99], v[196:197], off offset:1024
	global_load_dwordx4 v[100:103], v[204:205], off offset:1024
	s_waitcnt lgkmcnt(0)
	s_barrier
	ds_read_b128 v[116:119], v237
	ds_read_b128 v[112:115], v237 offset:32
	ds_read_b128 v[124:127], v238 offset:36864
	ds_read_b128 v[120:123], v238 offset:36896
	ds_read_b128 v[134:137], v237 offset:4608
	ds_read_b128 v[130:133], v237 offset:4640
	ds_read_b128 v[154:157], v238 offset:41472
	ds_read_b128 v[142:145], v238 offset:41504
	ds_read_b128 v[138:141], v237 offset:64
	ds_read_b128 v[146:149], v237 offset:96
	ds_read_b128 v[158:161], v237 offset:4672
	ds_read_b128 v[150:153], v237 offset:4704
	ds_read_b128 v[170:173], v238 offset:36928
	ds_read_b128 v[162:165], v238 offset:36960
	ds_read_b128 v[174:177], v238 offset:41536
	ds_read_b128 v[166:169], v238 offset:41568
	s_waitcnt lgkmcnt(0)
	s_barrier
	v_mfma_f32_32x32x16_bf16 v[48:63], v[116:119], v[124:127], v[48:63]
	v_mfma_f32_32x32x16_bf16 v[32:47], v[116:119], v[154:157], v[32:47]
	s_waitcnt vmcnt(11)
	ds_write_b128 v235, v[76:79] offset:55296
	v_mfma_f32_32x32x16_bf16 v[16:31], v[134:137], v[124:127], v[16:31]
	v_mfma_f32_32x32x16_bf16 v[0:15], v[134:137], v[154:157], v[0:15]
	s_waitcnt vmcnt(10)
	ds_write_b128 v235, v[80:83] offset:64512
	v_mfma_f32_32x32x16_bf16 v[48:63], v[112:115], v[120:123], v[48:63]
	v_mfma_f32_32x32x16_bf16 v[32:47], v[112:115], v[142:145], v[32:47]
	s_waitcnt vmcnt(9)
	ds_write_b128 v239, v[88:91] offset:18432
	v_mfma_f32_32x32x16_bf16 v[16:31], v[130:133], v[120:123], v[16:31]
	v_mfma_f32_32x32x16_bf16 v[0:15], v[130:133], v[142:145], v[0:15]
	s_waitcnt vmcnt(8)
	ds_write_b128 v239, v[92:95] offset:27648
	v_mfma_f32_32x32x16_bf16 v[48:63], v[138:141], v[170:173], v[48:63]
	v_mfma_f32_32x32x16_bf16 v[32:47], v[138:141], v[174:177], v[32:47]
	s_waitcnt vmcnt(7)
	ds_write_b128 v240, v[104:107]
	v_mfma_f32_32x32x16_bf16 v[16:31], v[158:161], v[170:173], v[16:31]
	v_mfma_f32_32x32x16_bf16 v[0:15], v[158:161], v[174:177], v[0:15]
	s_waitcnt vmcnt(6)
	ds_write_b128 v240, v[108:111] offset:9216
	v_mfma_f32_32x32x16_bf16 v[48:63], v[146:149], v[162:165], v[48:63]
	v_mfma_f32_32x32x16_bf16 v[32:47], v[146:149], v[166:169], v[32:47]
	v_mfma_f32_32x32x16_bf16 v[16:31], v[150:153], v[162:165], v[16:31]
	v_mfma_f32_32x32x16_bf16 v[0:15], v[150:153], v[166:169], v[0:15]
	global_load_dwordx4 v[76:79], v[194:195], off offset:1152
	global_load_dwordx4 v[80:83], v[198:199], off offset:1152
	global_load_dwordx4 v[88:91], v[200:201], off offset:1152
	global_load_dwordx4 v[92:95], v[202:203], off offset:1152
	global_load_dwordx4 v[104:107], v[196:197], off offset:1152
	global_load_dwordx4 v[108:111], v[204:205], off offset:1152
	s_waitcnt lgkmcnt(0)
	s_barrier
	ds_read_b128 v[116:119], v237 offset:55296
	ds_read_b128 v[112:115], v237 offset:55328
	ds_read_b128 v[124:127], v241
	ds_read_b128 v[120:123], v241 offset:32
	ds_read_b128 v[134:137], v237 offset:59904
	ds_read_b128 v[130:133], v237 offset:59936
	ds_read_b128 v[154:157], v241 offset:4608
	ds_read_b128 v[142:145], v241 offset:4640
	ds_read_b128 v[138:141], v237 offset:55360
	ds_read_b128 v[146:149], v237 offset:55392
	ds_read_b128 v[158:161], v237 offset:59968
	ds_read_b128 v[150:153], v237 offset:60000
	ds_read_b128 v[170:173], v241 offset:64
	ds_read_b128 v[162:165], v241 offset:96
	ds_read_b128 v[174:177], v241 offset:4672
	ds_read_b128 v[166:169], v241 offset:4704
	s_waitcnt lgkmcnt(0)
	s_barrier
	v_mfma_f32_32x32x16_bf16 v[48:63], v[116:119], v[124:127], v[48:63]
	v_mfma_f32_32x32x16_bf16 v[32:47], v[116:119], v[154:157], v[32:47]
	s_waitcnt vmcnt(11)
	ds_write_b128 v235, v[64:67]
	v_mfma_f32_32x32x16_bf16 v[16:31], v[134:137], v[124:127], v[16:31]
	v_mfma_f32_32x32x16_bf16 v[0:15], v[134:137], v[154:157], v[0:15]
	s_waitcnt vmcnt(10)
	ds_write_b128 v235, v[68:71] offset:9216
	v_mfma_f32_32x32x16_bf16 v[48:63], v[112:115], v[120:123], v[48:63]
	v_mfma_f32_32x32x16_bf16 v[32:47], v[112:115], v[142:145], v[32:47]
	s_waitcnt vmcnt(9)
	ds_write_b128 v235, v[84:87] offset:18432
	v_mfma_f32_32x32x16_bf16 v[16:31], v[130:133], v[120:123], v[16:31]
	v_mfma_f32_32x32x16_bf16 v[0:15], v[130:133], v[142:145], v[0:15]
	s_waitcnt vmcnt(8)
	ds_write_b128 v235, v[72:75] offset:27648
	v_mfma_f32_32x32x16_bf16 v[48:63], v[138:141], v[170:173], v[48:63]
	v_mfma_f32_32x32x16_bf16 v[32:47], v[138:141], v[174:177], v[32:47]
	s_waitcnt vmcnt(7)
	ds_write_b128 v235, v[96:99] offset:36864
	v_mfma_f32_32x32x16_bf16 v[16:31], v[158:161], v[170:173], v[16:31]
	v_mfma_f32_32x32x16_bf16 v[0:15], v[158:161], v[174:177], v[0:15]
	s_waitcnt vmcnt(6)
	ds_write_b128 v235, v[100:103] offset:46080
	v_mfma_f32_32x32x16_bf16 v[48:63], v[146:149], v[162:165], v[48:63]
	v_mfma_f32_32x32x16_bf16 v[32:47], v[146:149], v[166:169], v[32:47]
	v_mfma_f32_32x32x16_bf16 v[16:31], v[150:153], v[162:165], v[16:31]
	v_mfma_f32_32x32x16_bf16 v[0:15], v[150:153], v[166:169], v[0:15]
	global_load_dwordx4 v[64:67], v[194:195], off offset:1280
	global_load_dwordx4 v[68:71], v[198:199], off offset:1280
	global_load_dwordx4 v[84:87], v[200:201], off offset:1280
	global_load_dwordx4 v[72:75], v[202:203], off offset:1280
	global_load_dwordx4 v[96:99], v[196:197], off offset:1280
	global_load_dwordx4 v[100:103], v[204:205], off offset:1280
	s_waitcnt lgkmcnt(0)
	s_barrier
	ds_read_b128 v[116:119], v237
	ds_read_b128 v[112:115], v237 offset:32
	ds_read_b128 v[124:127], v238 offset:36864
	ds_read_b128 v[120:123], v238 offset:36896
	ds_read_b128 v[134:137], v237 offset:4608
	ds_read_b128 v[130:133], v237 offset:4640
	ds_read_b128 v[154:157], v238 offset:41472
	ds_read_b128 v[142:145], v238 offset:41504
	ds_read_b128 v[138:141], v237 offset:64
	ds_read_b128 v[146:149], v237 offset:96
	ds_read_b128 v[158:161], v237 offset:4672
	ds_read_b128 v[150:153], v237 offset:4704
	ds_read_b128 v[170:173], v238 offset:36928
	ds_read_b128 v[162:165], v238 offset:36960
	ds_read_b128 v[174:177], v238 offset:41536
	ds_read_b128 v[166:169], v238 offset:41568
	s_waitcnt lgkmcnt(0)
	s_barrier
	v_mfma_f32_32x32x16_bf16 v[48:63], v[116:119], v[124:127], v[48:63]
	v_mfma_f32_32x32x16_bf16 v[32:47], v[116:119], v[154:157], v[32:47]
	s_waitcnt vmcnt(11)
	ds_write_b128 v235, v[76:79] offset:55296
	v_mfma_f32_32x32x16_bf16 v[16:31], v[134:137], v[124:127], v[16:31]
	v_mfma_f32_32x32x16_bf16 v[0:15], v[134:137], v[154:157], v[0:15]
	s_waitcnt vmcnt(10)
	ds_write_b128 v235, v[80:83] offset:64512
	v_mfma_f32_32x32x16_bf16 v[48:63], v[112:115], v[120:123], v[48:63]
	v_mfma_f32_32x32x16_bf16 v[32:47], v[112:115], v[142:145], v[32:47]
	s_waitcnt vmcnt(9)
	ds_write_b128 v239, v[88:91] offset:18432
	v_mfma_f32_32x32x16_bf16 v[16:31], v[130:133], v[120:123], v[16:31]
	v_mfma_f32_32x32x16_bf16 v[0:15], v[130:133], v[142:145], v[0:15]
	s_waitcnt vmcnt(8)
	ds_write_b128 v239, v[92:95] offset:27648
	v_mfma_f32_32x32x16_bf16 v[48:63], v[138:141], v[170:173], v[48:63]
	v_mfma_f32_32x32x16_bf16 v[32:47], v[138:141], v[174:177], v[32:47]
	s_waitcnt vmcnt(7)
	ds_write_b128 v240, v[104:107]
	v_mfma_f32_32x32x16_bf16 v[16:31], v[158:161], v[170:173], v[16:31]
	v_mfma_f32_32x32x16_bf16 v[0:15], v[158:161], v[174:177], v[0:15]
	s_waitcnt vmcnt(6)
	ds_write_b128 v240, v[108:111] offset:9216
	v_mfma_f32_32x32x16_bf16 v[48:63], v[146:149], v[162:165], v[48:63]
	v_mfma_f32_32x32x16_bf16 v[32:47], v[146:149], v[166:169], v[32:47]
	v_mfma_f32_32x32x16_bf16 v[16:31], v[150:153], v[162:165], v[16:31]
	v_mfma_f32_32x32x16_bf16 v[0:15], v[150:153], v[166:169], v[0:15]
	global_load_dwordx4 v[76:79], v[194:195], off offset:1408
	global_load_dwordx4 v[80:83], v[198:199], off offset:1408
	global_load_dwordx4 v[88:91], v[200:201], off offset:1408
	global_load_dwordx4 v[92:95], v[202:203], off offset:1408
	global_load_dwordx4 v[104:107], v[196:197], off offset:1408
	global_load_dwordx4 v[108:111], v[204:205], off offset:1408
	s_waitcnt lgkmcnt(0)
	s_barrier
	ds_read_b128 v[116:119], v237 offset:55296
	ds_read_b128 v[112:115], v237 offset:55328
	ds_read_b128 v[124:127], v241
	ds_read_b128 v[120:123], v241 offset:32
	ds_read_b128 v[134:137], v237 offset:59904
	ds_read_b128 v[130:133], v237 offset:59936
	ds_read_b128 v[154:157], v241 offset:4608
	ds_read_b128 v[142:145], v241 offset:4640
	ds_read_b128 v[138:141], v237 offset:55360
	ds_read_b128 v[146:149], v237 offset:55392
	ds_read_b128 v[158:161], v237 offset:59968
	ds_read_b128 v[150:153], v237 offset:60000
	ds_read_b128 v[170:173], v241 offset:64
	ds_read_b128 v[162:165], v241 offset:96
	ds_read_b128 v[174:177], v241 offset:4672
	ds_read_b128 v[166:169], v241 offset:4704
	s_waitcnt lgkmcnt(0)
	s_barrier
	v_mfma_f32_32x32x16_bf16 v[48:63], v[116:119], v[124:127], v[48:63]
	v_mfma_f32_32x32x16_bf16 v[32:47], v[116:119], v[154:157], v[32:47]
	s_waitcnt vmcnt(11)
	ds_write_b128 v235, v[64:67]
	v_mfma_f32_32x32x16_bf16 v[16:31], v[134:137], v[124:127], v[16:31]
	v_mfma_f32_32x32x16_bf16 v[0:15], v[134:137], v[154:157], v[0:15]
	s_waitcnt vmcnt(10)
	ds_write_b128 v235, v[68:71] offset:9216
	v_mfma_f32_32x32x16_bf16 v[48:63], v[112:115], v[120:123], v[48:63]
	v_mfma_f32_32x32x16_bf16 v[32:47], v[112:115], v[142:145], v[32:47]
	s_waitcnt vmcnt(9)
	ds_write_b128 v235, v[84:87] offset:18432
	v_mfma_f32_32x32x16_bf16 v[16:31], v[130:133], v[120:123], v[16:31]
	v_mfma_f32_32x32x16_bf16 v[0:15], v[130:133], v[142:145], v[0:15]
	s_waitcnt vmcnt(8)
	ds_write_b128 v235, v[72:75] offset:27648
	v_mfma_f32_32x32x16_bf16 v[48:63], v[138:141], v[170:173], v[48:63]
	v_mfma_f32_32x32x16_bf16 v[32:47], v[138:141], v[174:177], v[32:47]
	s_waitcnt vmcnt(7)
	ds_write_b128 v235, v[96:99] offset:36864
	v_mfma_f32_32x32x16_bf16 v[16:31], v[158:161], v[170:173], v[16:31]
	v_mfma_f32_32x32x16_bf16 v[0:15], v[158:161], v[174:177], v[0:15]
	s_waitcnt vmcnt(6)
	ds_write_b128 v235, v[100:103] offset:46080
	v_mfma_f32_32x32x16_bf16 v[48:63], v[146:149], v[162:165], v[48:63]
	v_mfma_f32_32x32x16_bf16 v[32:47], v[146:149], v[166:169], v[32:47]
	v_mfma_f32_32x32x16_bf16 v[16:31], v[150:153], v[162:165], v[16:31]
	v_mfma_f32_32x32x16_bf16 v[0:15], v[150:153], v[166:169], v[0:15]
	global_load_dwordx4 v[64:67], v[194:195], off offset:1536
	global_load_dwordx4 v[68:71], v[198:199], off offset:1536
	global_load_dwordx4 v[84:87], v[200:201], off offset:1536
	global_load_dwordx4 v[72:75], v[202:203], off offset:1536
	global_load_dwordx4 v[96:99], v[196:197], off offset:1536
	global_load_dwordx4 v[100:103], v[204:205], off offset:1536
	s_waitcnt lgkmcnt(0)
	s_barrier
	ds_read_b128 v[116:119], v237
	ds_read_b128 v[112:115], v237 offset:32
	ds_read_b128 v[124:127], v238 offset:36864
	ds_read_b128 v[120:123], v238 offset:36896
	ds_read_b128 v[134:137], v237 offset:4608
	ds_read_b128 v[130:133], v237 offset:4640
	ds_read_b128 v[154:157], v238 offset:41472
	ds_read_b128 v[142:145], v238 offset:41504
	ds_read_b128 v[138:141], v237 offset:64
	ds_read_b128 v[146:149], v237 offset:96
	ds_read_b128 v[158:161], v237 offset:4672
	ds_read_b128 v[150:153], v237 offset:4704
	ds_read_b128 v[170:173], v238 offset:36928
	ds_read_b128 v[162:165], v238 offset:36960
	ds_read_b128 v[174:177], v238 offset:41536
	ds_read_b128 v[166:169], v238 offset:41568
	s_waitcnt lgkmcnt(0)
	s_barrier
	v_mfma_f32_32x32x16_bf16 v[48:63], v[116:119], v[124:127], v[48:63]
	v_mfma_f32_32x32x16_bf16 v[32:47], v[116:119], v[154:157], v[32:47]
	s_waitcnt vmcnt(11)
	ds_write_b128 v235, v[76:79] offset:55296
	v_mfma_f32_32x32x16_bf16 v[16:31], v[134:137], v[124:127], v[16:31]
	v_mfma_f32_32x32x16_bf16 v[0:15], v[134:137], v[154:157], v[0:15]
	s_waitcnt vmcnt(10)
	ds_write_b128 v235, v[80:83] offset:64512
	v_mfma_f32_32x32x16_bf16 v[48:63], v[112:115], v[120:123], v[48:63]
	v_mfma_f32_32x32x16_bf16 v[32:47], v[112:115], v[142:145], v[32:47]
	s_waitcnt vmcnt(9)
	ds_write_b128 v239, v[88:91] offset:18432
	v_mfma_f32_32x32x16_bf16 v[16:31], v[130:133], v[120:123], v[16:31]
	v_mfma_f32_32x32x16_bf16 v[0:15], v[130:133], v[142:145], v[0:15]
	s_waitcnt vmcnt(8)
	ds_write_b128 v239, v[92:95] offset:27648
	v_mfma_f32_32x32x16_bf16 v[48:63], v[138:141], v[170:173], v[48:63]
	v_mfma_f32_32x32x16_bf16 v[32:47], v[138:141], v[174:177], v[32:47]
	s_waitcnt vmcnt(7)
	ds_write_b128 v240, v[104:107]
	v_mfma_f32_32x32x16_bf16 v[16:31], v[158:161], v[170:173], v[16:31]
	v_mfma_f32_32x32x16_bf16 v[0:15], v[158:161], v[174:177], v[0:15]
	s_waitcnt vmcnt(6)
	ds_write_b128 v240, v[108:111] offset:9216
	v_mfma_f32_32x32x16_bf16 v[48:63], v[146:149], v[162:165], v[48:63]
	v_mfma_f32_32x32x16_bf16 v[32:47], v[146:149], v[166:169], v[32:47]
	v_mfma_f32_32x32x16_bf16 v[16:31], v[150:153], v[162:165], v[16:31]
	v_mfma_f32_32x32x16_bf16 v[0:15], v[150:153], v[166:169], v[0:15]
	global_load_dwordx4 v[76:79], v[194:195], off offset:1664
	global_load_dwordx4 v[80:83], v[198:199], off offset:1664
	global_load_dwordx4 v[88:91], v[200:201], off offset:1664
	global_load_dwordx4 v[92:95], v[202:203], off offset:1664
	global_load_dwordx4 v[104:107], v[196:197], off offset:1664
	global_load_dwordx4 v[108:111], v[204:205], off offset:1664
	s_waitcnt lgkmcnt(0)
	s_barrier
	ds_read_b128 v[116:119], v237 offset:55296
	ds_read_b128 v[112:115], v237 offset:55328
	ds_read_b128 v[124:127], v241
	ds_read_b128 v[120:123], v241 offset:32
	ds_read_b128 v[134:137], v237 offset:59904
	ds_read_b128 v[130:133], v237 offset:59936
	ds_read_b128 v[154:157], v241 offset:4608
	ds_read_b128 v[142:145], v241 offset:4640
	ds_read_b128 v[138:141], v237 offset:55360
	ds_read_b128 v[146:149], v237 offset:55392
	ds_read_b128 v[158:161], v237 offset:59968
	ds_read_b128 v[150:153], v237 offset:60000
	ds_read_b128 v[170:173], v241 offset:64
	ds_read_b128 v[162:165], v241 offset:96
	ds_read_b128 v[174:177], v241 offset:4672
	ds_read_b128 v[166:169], v241 offset:4704
	s_waitcnt lgkmcnt(0)
	s_barrier
	v_mfma_f32_32x32x16_bf16 v[48:63], v[116:119], v[124:127], v[48:63]
	v_mfma_f32_32x32x16_bf16 v[32:47], v[116:119], v[154:157], v[32:47]
	s_waitcnt vmcnt(11)
	ds_write_b128 v235, v[64:67]
	v_mfma_f32_32x32x16_bf16 v[16:31], v[134:137], v[124:127], v[16:31]
	v_mfma_f32_32x32x16_bf16 v[0:15], v[134:137], v[154:157], v[0:15]
	s_waitcnt vmcnt(10)
	ds_write_b128 v235, v[68:71] offset:9216
	v_mfma_f32_32x32x16_bf16 v[48:63], v[112:115], v[120:123], v[48:63]
	v_mfma_f32_32x32x16_bf16 v[32:47], v[112:115], v[142:145], v[32:47]
	s_waitcnt vmcnt(9)
	ds_write_b128 v235, v[84:87] offset:18432
	v_mfma_f32_32x32x16_bf16 v[16:31], v[130:133], v[120:123], v[16:31]
	v_mfma_f32_32x32x16_bf16 v[0:15], v[130:133], v[142:145], v[0:15]
	s_waitcnt vmcnt(8)
	ds_write_b128 v235, v[72:75] offset:27648
	v_mfma_f32_32x32x16_bf16 v[48:63], v[138:141], v[170:173], v[48:63]
	v_mfma_f32_32x32x16_bf16 v[32:47], v[138:141], v[174:177], v[32:47]
	s_waitcnt vmcnt(7)
	ds_write_b128 v235, v[96:99] offset:36864
	v_mfma_f32_32x32x16_bf16 v[16:31], v[158:161], v[170:173], v[16:31]
	v_mfma_f32_32x32x16_bf16 v[0:15], v[158:161], v[174:177], v[0:15]
	s_waitcnt vmcnt(6)
	ds_write_b128 v235, v[100:103] offset:46080
	v_mfma_f32_32x32x16_bf16 v[48:63], v[146:149], v[162:165], v[48:63]
	v_mfma_f32_32x32x16_bf16 v[32:47], v[146:149], v[166:169], v[32:47]
	v_mfma_f32_32x32x16_bf16 v[16:31], v[150:153], v[162:165], v[16:31]
	v_mfma_f32_32x32x16_bf16 v[0:15], v[150:153], v[166:169], v[0:15]
	global_load_dwordx4 v[64:67], v[194:195], off offset:1792
	global_load_dwordx4 v[68:71], v[198:199], off offset:1792
	global_load_dwordx4 v[84:87], v[200:201], off offset:1792
	global_load_dwordx4 v[72:75], v[202:203], off offset:1792
	global_load_dwordx4 v[96:99], v[196:197], off offset:1792
	global_load_dwordx4 v[100:103], v[204:205], off offset:1792
	s_waitcnt lgkmcnt(0)
	s_barrier
	ds_read_b128 v[116:119], v237
	ds_read_b128 v[112:115], v237 offset:32
	ds_read_b128 v[124:127], v238 offset:36864
	ds_read_b128 v[120:123], v238 offset:36896
	ds_read_b128 v[134:137], v237 offset:4608
	ds_read_b128 v[130:133], v237 offset:4640
	ds_read_b128 v[154:157], v238 offset:41472
	ds_read_b128 v[142:145], v238 offset:41504
	ds_read_b128 v[138:141], v237 offset:64
	ds_read_b128 v[146:149], v237 offset:96
	ds_read_b128 v[158:161], v237 offset:4672
	ds_read_b128 v[150:153], v237 offset:4704
	ds_read_b128 v[170:173], v238 offset:36928
	ds_read_b128 v[162:165], v238 offset:36960
	ds_read_b128 v[174:177], v238 offset:41536
	ds_read_b128 v[166:169], v238 offset:41568
	s_waitcnt lgkmcnt(0)
	s_barrier
	v_mfma_f32_32x32x16_bf16 v[48:63], v[116:119], v[124:127], v[48:63]
	v_mfma_f32_32x32x16_bf16 v[32:47], v[116:119], v[154:157], v[32:47]
	s_waitcnt vmcnt(11)
	ds_write_b128 v235, v[76:79] offset:55296
	v_mfma_f32_32x32x16_bf16 v[16:31], v[134:137], v[124:127], v[16:31]
	v_mfma_f32_32x32x16_bf16 v[0:15], v[134:137], v[154:157], v[0:15]
	s_waitcnt vmcnt(10)
	ds_write_b128 v235, v[80:83] offset:64512
	v_mfma_f32_32x32x16_bf16 v[48:63], v[112:115], v[120:123], v[48:63]
	v_mfma_f32_32x32x16_bf16 v[32:47], v[112:115], v[142:145], v[32:47]
	s_waitcnt vmcnt(9)
	ds_write_b128 v239, v[88:91] offset:18432
	v_mfma_f32_32x32x16_bf16 v[16:31], v[130:133], v[120:123], v[16:31]
	v_mfma_f32_32x32x16_bf16 v[0:15], v[130:133], v[142:145], v[0:15]
	s_waitcnt vmcnt(8)
	ds_write_b128 v239, v[92:95] offset:27648
	v_mfma_f32_32x32x16_bf16 v[48:63], v[138:141], v[170:173], v[48:63]
	v_mfma_f32_32x32x16_bf16 v[32:47], v[138:141], v[174:177], v[32:47]
	s_waitcnt vmcnt(7)
	ds_write_b128 v240, v[104:107]
	v_mfma_f32_32x32x16_bf16 v[16:31], v[158:161], v[170:173], v[16:31]
	v_mfma_f32_32x32x16_bf16 v[0:15], v[158:161], v[174:177], v[0:15]
	s_waitcnt vmcnt(6)
	ds_write_b128 v240, v[108:111] offset:9216
	v_mfma_f32_32x32x16_bf16 v[48:63], v[146:149], v[162:165], v[48:63]
	v_mfma_f32_32x32x16_bf16 v[32:47], v[146:149], v[166:169], v[32:47]
	v_mfma_f32_32x32x16_bf16 v[16:31], v[150:153], v[162:165], v[16:31]
	v_mfma_f32_32x32x16_bf16 v[0:15], v[150:153], v[166:169], v[0:15]
	global_load_dwordx4 v[76:79], v[194:195], off offset:1920
	global_load_dwordx4 v[80:83], v[198:199], off offset:1920
	global_load_dwordx4 v[88:91], v[200:201], off offset:1920
	global_load_dwordx4 v[92:95], v[202:203], off offset:1920
	global_load_dwordx4 v[104:107], v[196:197], off offset:1920
	global_load_dwordx4 v[108:111], v[204:205], off offset:1920
	s_waitcnt lgkmcnt(0)
	s_barrier
	ds_read_b128 v[116:119], v237 offset:55296
	ds_read_b128 v[112:115], v237 offset:55328
	ds_read_b128 v[124:127], v241
	ds_read_b128 v[120:123], v241 offset:32
	ds_read_b128 v[134:137], v237 offset:59904
	ds_read_b128 v[130:133], v237 offset:59936
	ds_read_b128 v[154:157], v241 offset:4608
	ds_read_b128 v[142:145], v241 offset:4640
	ds_read_b128 v[138:141], v237 offset:55360
	ds_read_b128 v[146:149], v237 offset:55392
	ds_read_b128 v[158:161], v237 offset:59968
	ds_read_b128 v[150:153], v237 offset:60000
	ds_read_b128 v[170:173], v241 offset:64
	ds_read_b128 v[162:165], v241 offset:96
	ds_read_b128 v[174:177], v241 offset:4672
	ds_read_b128 v[166:169], v241 offset:4704
	s_waitcnt lgkmcnt(0)
	s_barrier
	v_mfma_f32_32x32x16_bf16 v[48:63], v[116:119], v[124:127], v[48:63]
	v_mfma_f32_32x32x16_bf16 v[32:47], v[116:119], v[154:157], v[32:47]
	s_waitcnt vmcnt(11)
	ds_write_b128 v235, v[64:67]
	v_mfma_f32_32x32x16_bf16 v[16:31], v[134:137], v[124:127], v[16:31]
	v_mfma_f32_32x32x16_bf16 v[0:15], v[134:137], v[154:157], v[0:15]
	s_waitcnt vmcnt(10)
	ds_write_b128 v235, v[68:71] offset:9216
	v_mfma_f32_32x32x16_bf16 v[48:63], v[112:115], v[120:123], v[48:63]
	v_mfma_f32_32x32x16_bf16 v[32:47], v[112:115], v[142:145], v[32:47]
	s_waitcnt vmcnt(9)
	ds_write_b128 v235, v[84:87] offset:18432
	v_mfma_f32_32x32x16_bf16 v[16:31], v[130:133], v[120:123], v[16:31]
	v_mfma_f32_32x32x16_bf16 v[0:15], v[130:133], v[142:145], v[0:15]
	s_waitcnt vmcnt(8)
	ds_write_b128 v235, v[72:75] offset:27648
	v_mfma_f32_32x32x16_bf16 v[48:63], v[138:141], v[170:173], v[48:63]
	v_mfma_f32_32x32x16_bf16 v[32:47], v[138:141], v[174:177], v[32:47]
	s_waitcnt vmcnt(7)
	ds_write_b128 v235, v[96:99] offset:36864
	v_mfma_f32_32x32x16_bf16 v[16:31], v[158:161], v[170:173], v[16:31]
	v_mfma_f32_32x32x16_bf16 v[0:15], v[158:161], v[174:177], v[0:15]
	s_waitcnt vmcnt(6)
	ds_write_b128 v235, v[100:103] offset:46080
	v_mfma_f32_32x32x16_bf16 v[48:63], v[146:149], v[162:165], v[48:63]
	v_mfma_f32_32x32x16_bf16 v[32:47], v[146:149], v[166:169], v[32:47]
	v_mfma_f32_32x32x16_bf16 v[16:31], v[150:153], v[162:165], v[16:31]
	v_mfma_f32_32x32x16_bf16 v[0:15], v[150:153], v[166:169], v[0:15]
	s_waitcnt lgkmcnt(0)
	s_barrier
	ds_read_b128 v[116:119], v237
	ds_read_b128 v[112:115], v237 offset:32
	ds_read_b128 v[124:127], v238 offset:36864
	ds_read_b128 v[120:123], v238 offset:36896
	ds_read_b128 v[134:137], v237 offset:4608
	ds_read_b128 v[130:133], v237 offset:4640
	ds_read_b128 v[154:157], v238 offset:41472
	ds_read_b128 v[142:145], v238 offset:41504
	ds_read_b128 v[138:141], v237 offset:64
	ds_read_b128 v[146:149], v237 offset:96
	ds_read_b128 v[158:161], v237 offset:4672
	ds_read_b128 v[150:153], v237 offset:4704
	ds_read_b128 v[170:173], v238 offset:36928
	ds_read_b128 v[162:165], v238 offset:36960
	ds_read_b128 v[174:177], v238 offset:41536
	ds_read_b128 v[166:169], v238 offset:41568
	s_waitcnt lgkmcnt(0)
	s_barrier
	v_mfma_f32_32x32x16_bf16 v[48:63], v[116:119], v[124:127], v[48:63]
	v_mfma_f32_32x32x16_bf16 v[32:47], v[116:119], v[154:157], v[32:47]
	s_waitcnt vmcnt(5)
	ds_write_b128 v235, v[76:79] offset:55296
	v_mfma_f32_32x32x16_bf16 v[16:31], v[134:137], v[124:127], v[16:31]
	v_mfma_f32_32x32x16_bf16 v[0:15], v[134:137], v[154:157], v[0:15]
	s_waitcnt vmcnt(4)
	ds_write_b128 v235, v[80:83] offset:64512
	v_mfma_f32_32x32x16_bf16 v[48:63], v[112:115], v[120:123], v[48:63]
	v_mfma_f32_32x32x16_bf16 v[32:47], v[112:115], v[142:145], v[32:47]
	s_waitcnt vmcnt(3)
	ds_write_b128 v239, v[88:91] offset:18432
	v_mfma_f32_32x32x16_bf16 v[16:31], v[130:133], v[120:123], v[16:31]
	v_mfma_f32_32x32x16_bf16 v[0:15], v[130:133], v[142:145], v[0:15]
	s_waitcnt vmcnt(2)
	ds_write_b128 v239, v[92:95] offset:27648
	v_mfma_f32_32x32x16_bf16 v[48:63], v[138:141], v[170:173], v[48:63]
	v_mfma_f32_32x32x16_bf16 v[32:47], v[138:141], v[174:177], v[32:47]
	s_waitcnt vmcnt(1)
	ds_write_b128 v240, v[104:107]
	v_mfma_f32_32x32x16_bf16 v[16:31], v[158:161], v[170:173], v[16:31]
	v_mfma_f32_32x32x16_bf16 v[0:15], v[158:161], v[174:177], v[0:15]
	s_waitcnt vmcnt(0)
	ds_write_b128 v240, v[108:111] offset:9216
	v_mfma_f32_32x32x16_bf16 v[48:63], v[146:149], v[162:165], v[48:63]
	v_mfma_f32_32x32x16_bf16 v[32:47], v[146:149], v[166:169], v[32:47]
	v_mfma_f32_32x32x16_bf16 v[16:31], v[150:153], v[162:165], v[16:31]
	v_mfma_f32_32x32x16_bf16 v[0:15], v[150:153], v[166:169], v[0:15]
	s_waitcnt lgkmcnt(0)
	s_barrier
	ds_read_b128 v[116:119], v237 offset:55296
	ds_read_b128 v[112:115], v237 offset:55328
	ds_read_b128 v[124:127], v241
	ds_read_b128 v[120:123], v241 offset:32
	ds_read_b128 v[134:137], v237 offset:59904
	ds_read_b128 v[130:133], v237 offset:59936
	ds_read_b128 v[154:157], v241 offset:4608
	ds_read_b128 v[142:145], v241 offset:4640
	ds_read_b128 v[138:141], v237 offset:55360
	ds_read_b128 v[146:149], v237 offset:55392
	ds_read_b128 v[158:161], v237 offset:59968
	ds_read_b128 v[150:153], v237 offset:60000
	ds_read_b128 v[170:173], v241 offset:64
	ds_read_b128 v[162:165], v241 offset:96
	ds_read_b128 v[174:177], v241 offset:4672
	ds_read_b128 v[166:169], v241 offset:4704
	s_waitcnt lgkmcnt(0)
	s_barrier
	v_mfma_f32_32x32x16_bf16 v[48:63], v[116:119], v[124:127], v[48:63]
	v_mfma_f32_32x32x16_bf16 v[32:47], v[116:119], v[154:157], v[32:47]
	v_mfma_f32_32x32x16_bf16 v[16:31], v[134:137], v[124:127], v[16:31]
	v_mfma_f32_32x32x16_bf16 v[0:15], v[134:137], v[154:157], v[0:15]
	v_mfma_f32_32x32x16_bf16 v[48:63], v[112:115], v[120:123], v[48:63]
	v_mfma_f32_32x32x16_bf16 v[32:47], v[112:115], v[142:145], v[32:47]
	v_mfma_f32_32x32x16_bf16 v[16:31], v[130:133], v[120:123], v[16:31]
	v_mfma_f32_32x32x16_bf16 v[0:15], v[130:133], v[142:145], v[0:15]
	v_mfma_f32_32x32x16_bf16 v[48:63], v[138:141], v[170:173], v[48:63]
	v_mfma_f32_32x32x16_bf16 v[32:47], v[138:141], v[174:177], v[32:47]
	v_mfma_f32_32x32x16_bf16 v[16:31], v[158:161], v[170:173], v[16:31]
	v_mfma_f32_32x32x16_bf16 v[0:15], v[158:161], v[174:177], v[0:15]
	v_mfma_f32_32x32x16_bf16 v[48:63], v[146:149], v[162:165], v[48:63]
	v_mfma_f32_32x32x16_bf16 v[32:47], v[146:149], v[166:169], v[32:47]
	v_mfma_f32_32x32x16_bf16 v[16:31], v[150:153], v[162:165], v[16:31]
	v_mfma_f32_32x32x16_bf16 v[0:15], v[150:153], v[166:169], v[0:15]
	s_waitcnt lgkmcnt(0)
	s_barrier
	s_waitcnt lgkmcnt(0)
	s_barrier
	s_branch .LBB0_191

.LBB0_1228:
	ds_read_b128 v[112:115], v203
	ds_read_b128 v[116:119], v203 offset:32
	ds_read_b128 v[120:123], v203 offset:4608
	ds_read_b128 v[124:127], v203 offset:4640
	ds_read_b128 v[130:133], v204 offset:36864
	ds_read_b128 v[134:137], v204 offset:36896
	ds_read_b128 v[138:141], v204 offset:41472
	ds_read_b128 v[142:145], v204 offset:41504
	ds_read_b128 v[146:149], v203 offset:64
	ds_read_b128 v[150:153], v203 offset:96
	ds_read_b128 v[154:157], v203 offset:4672
	ds_read_b128 v[158:161], v203 offset:4704
	ds_read_b128 v[162:165], v204 offset:36928
	ds_read_b128 v[166:169], v204 offset:36960
	ds_read_b128 v[170:173], v204 offset:41536
	ds_read_b128 v[174:177], v204 offset:41568
	s_waitcnt vmcnt(11)
	ds_write_b128 v201, v[64:67] offset:55296
	s_waitcnt vmcnt(10)
	ds_write_b128 v201, v[68:71] offset:64512
	s_waitcnt vmcnt(9)
	ds_write_b128 v205, v[80:83] offset:18432
	s_waitcnt vmcnt(8)
	ds_write_b128 v205, v[84:87] offset:27648
	s_waitcnt vmcnt(7)
	ds_write_b128 v234, v[96:99]
	s_waitcnt vmcnt(6)
	ds_write_b128 v234, v[100:103] offset:9216
	global_load_dwordx4 v[64:67], v[182:183], off offset:384
	global_load_dwordx4 v[68:71], v[186:187], off offset:384
	global_load_dwordx4 v[80:83], v[188:189], off offset:384
	global_load_dwordx4 v[84:87], v[190:191], off offset:384
	global_load_dwordx4 v[96:99], v[184:185], off offset:384
	global_load_dwordx4 v[100:103], v[192:193], off offset:384
	s_waitcnt lgkmcnt(0)
	s_barrier
	v_mfma_f32_32x32x16_bf16 v[48:63], v[112:115], v[130:133], v[48:63]
	v_mfma_f32_32x32x16_bf16 v[32:47], v[112:115], v[138:141], v[32:47]
	s_waitcnt vmcnt(11)
	ds_write_b128 v201, v[72:75]
	v_mfma_f32_32x32x16_bf16 v[16:31], v[120:123], v[130:133], v[16:31]
	v_mfma_f32_32x32x16_bf16 v[0:15], v[120:123], v[138:141], v[0:15]
	s_waitcnt vmcnt(10)
	ds_write_b128 v201, v[76:79] offset:9216
	v_mfma_f32_32x32x16_bf16 v[48:63], v[116:119], v[134:137], v[48:63]
	v_mfma_f32_32x32x16_bf16 v[32:47], v[116:119], v[142:145], v[32:47]
	s_waitcnt vmcnt(9)
	ds_write_b128 v201, v[88:91] offset:18432
	v_mfma_f32_32x32x16_bf16 v[16:31], v[124:127], v[134:137], v[16:31]
	v_mfma_f32_32x32x16_bf16 v[0:15], v[124:127], v[142:145], v[0:15]
	s_waitcnt vmcnt(8)
	ds_write_b128 v201, v[92:95] offset:27648
	v_mfma_f32_32x32x16_bf16 v[48:63], v[146:149], v[162:165], v[48:63]
	v_mfma_f32_32x32x16_bf16 v[32:47], v[146:149], v[170:173], v[32:47]
	s_waitcnt vmcnt(7)
	ds_write_b128 v201, v[104:107] offset:36864
	v_mfma_f32_32x32x16_bf16 v[16:31], v[154:157], v[162:165], v[16:31]
	v_mfma_f32_32x32x16_bf16 v[0:15], v[154:157], v[170:173], v[0:15]
	s_waitcnt vmcnt(6)
	ds_write_b128 v201, v[108:111] offset:46080
	v_mfma_f32_32x32x16_bf16 v[48:63], v[150:153], v[166:169], v[48:63]
	v_mfma_f32_32x32x16_bf16 v[32:47], v[150:153], v[174:177], v[32:47]
	v_mfma_f32_32x32x16_bf16 v[16:31], v[158:161], v[166:169], v[16:31]
	v_mfma_f32_32x32x16_bf16 v[0:15], v[158:161], v[174:177], v[0:15]
	global_load_dwordx4 v[72:75], v[182:183], off offset:512
	global_load_dwordx4 v[76:79], v[186:187], off offset:512
	global_load_dwordx4 v[88:91], v[188:189], off offset:512
	global_load_dwordx4 v[92:95], v[190:191], off offset:512
	global_load_dwordx4 v[104:107], v[184:185], off offset:512
	global_load_dwordx4 v[108:111], v[192:193], off offset:512
	s_waitcnt lgkmcnt(0)
	s_barrier
	ds_read_b128 v[162:165], v203 offset:55296
	ds_read_b128 v[130:133], v203 offset:55328
	ds_read_b128 v[170:173], v235
	ds_read_b128 v[134:137], v235 offset:32
	ds_read_b128 v[166:169], v203 offset:59904
	ds_read_b128 v[142:145], v203 offset:59936
	ds_read_b128 v[174:177], v235 offset:4608
	ds_read_b128 v[150:153], v235 offset:4640
	ds_read_b128 v[138:141], v203 offset:55360
	ds_read_b128 v[116:119], v203 offset:55392
	ds_read_b128 v[146:149], v203 offset:59968
	ds_read_b128 v[112:115], v203 offset:60000
	ds_read_b128 v[154:157], v235 offset:64
	ds_read_b128 v[120:123], v235 offset:96
	ds_read_b128 v[158:161], v235 offset:4672
	ds_read_b128 v[124:127], v235 offset:4704
	s_waitcnt lgkmcnt(0)
	s_barrier
	v_mfma_f32_32x32x16_bf16 v[48:63], v[162:165], v[170:173], v[48:63]
	v_mfma_f32_32x32x16_bf16 v[32:47], v[162:165], v[174:177], v[32:47]
	s_waitcnt vmcnt(11)
	ds_write_b128 v201, v[64:67] offset:55296
	v_mfma_f32_32x32x16_bf16 v[16:31], v[166:169], v[170:173], v[16:31]
	v_mfma_f32_32x32x16_bf16 v[0:15], v[166:169], v[174:177], v[0:15]
	s_waitcnt vmcnt(10)
	ds_write_b128 v201, v[68:71] offset:64512
	v_mfma_f32_32x32x16_bf16 v[48:63], v[130:133], v[134:137], v[48:63]
	v_mfma_f32_32x32x16_bf16 v[32:47], v[130:133], v[150:153], v[32:47]
	s_waitcnt vmcnt(9)
	ds_write_b128 v205, v[80:83] offset:18432
	v_mfma_f32_32x32x16_bf16 v[16:31], v[142:145], v[134:137], v[16:31]
	v_mfma_f32_32x32x16_bf16 v[0:15], v[142:145], v[150:153], v[0:15]
	s_waitcnt vmcnt(8)
	ds_write_b128 v205, v[84:87] offset:27648
	v_mfma_f32_32x32x16_bf16 v[48:63], v[138:141], v[154:157], v[48:63]
	v_mfma_f32_32x32x16_bf16 v[32:47], v[138:141], v[158:161], v[32:47]
	s_waitcnt vmcnt(7)
	ds_write_b128 v234, v[96:99]
	v_mfma_f32_32x32x16_bf16 v[16:31], v[146:149], v[154:157], v[16:31]
	v_mfma_f32_32x32x16_bf16 v[0:15], v[146:149], v[158:161], v[0:15]
	s_waitcnt vmcnt(6)
	ds_write_b128 v234, v[100:103] offset:9216
	v_mfma_f32_32x32x16_bf16 v[48:63], v[116:119], v[120:123], v[48:63]
	v_mfma_f32_32x32x16_bf16 v[32:47], v[116:119], v[124:127], v[32:47]
	v_mfma_f32_32x32x16_bf16 v[16:31], v[112:115], v[120:123], v[16:31]
	v_mfma_f32_32x32x16_bf16 v[0:15], v[112:115], v[124:127], v[0:15]
	global_load_dwordx4 v[64:67], v[182:183], off offset:640
	global_load_dwordx4 v[68:71], v[186:187], off offset:640
	global_load_dwordx4 v[80:83], v[188:189], off offset:640
	global_load_dwordx4 v[84:87], v[190:191], off offset:640
	global_load_dwordx4 v[96:99], v[184:185], off offset:640
	global_load_dwordx4 v[100:103], v[192:193], off offset:640
	s_waitcnt lgkmcnt(0)
	s_barrier
	ds_read_b128 v[112:115], v203
	ds_read_b128 v[116:119], v203 offset:32
	ds_read_b128 v[120:123], v203 offset:4608
	ds_read_b128 v[124:127], v203 offset:4640
	ds_read_b128 v[130:133], v204 offset:36864
	ds_read_b128 v[134:137], v204 offset:36896
	ds_read_b128 v[138:141], v204 offset:41472
	ds_read_b128 v[142:145], v204 offset:41504
	ds_read_b128 v[146:149], v203 offset:64
	ds_read_b128 v[150:153], v203 offset:96
	ds_read_b128 v[154:157], v203 offset:4672
	ds_read_b128 v[158:161], v203 offset:4704
	ds_read_b128 v[162:165], v204 offset:36928
	ds_read_b128 v[166:169], v204 offset:36960
	ds_read_b128 v[170:173], v204 offset:41536
	ds_read_b128 v[174:177], v204 offset:41568
	s_waitcnt lgkmcnt(0)
	s_barrier
	v_mfma_f32_32x32x16_bf16 v[48:63], v[112:115], v[130:133], v[48:63]
	v_mfma_f32_32x32x16_bf16 v[32:47], v[112:115], v[138:141], v[32:47]
	s_waitcnt vmcnt(11)
	ds_write_b128 v201, v[72:75]
	v_mfma_f32_32x32x16_bf16 v[16:31], v[120:123], v[130:133], v[16:31]
	v_mfma_f32_32x32x16_bf16 v[0:15], v[120:123], v[138:141], v[0:15]
	s_waitcnt vmcnt(10)
	ds_write_b128 v201, v[76:79] offset:9216
	v_mfma_f32_32x32x16_bf16 v[48:63], v[116:119], v[134:137], v[48:63]
	v_mfma_f32_32x32x16_bf16 v[32:47], v[116:119], v[142:145], v[32:47]
	s_waitcnt vmcnt(9)
	ds_write_b128 v201, v[88:91] offset:18432
	v_mfma_f32_32x32x16_bf16 v[16:31], v[124:127], v[134:137], v[16:31]
	v_mfma_f32_32x32x16_bf16 v[0:15], v[124:127], v[142:145], v[0:15]
	s_waitcnt vmcnt(8)
	ds_write_b128 v201, v[92:95] offset:27648
	v_mfma_f32_32x32x16_bf16 v[48:63], v[146:149], v[162:165], v[48:63]
	v_mfma_f32_32x32x16_bf16 v[32:47], v[146:149], v[170:173], v[32:47]
	s_waitcnt vmcnt(7)
	ds_write_b128 v201, v[104:107] offset:36864
	v_mfma_f32_32x32x16_bf16 v[16:31], v[154:157], v[162:165], v[16:31]
	v_mfma_f32_32x32x16_bf16 v[0:15], v[154:157], v[170:173], v[0:15]
	s_waitcnt vmcnt(6)
	ds_write_b128 v201, v[108:111] offset:46080
	v_mfma_f32_32x32x16_bf16 v[48:63], v[150:153], v[166:169], v[48:63]
	v_mfma_f32_32x32x16_bf16 v[32:47], v[150:153], v[174:177], v[32:47]
	v_mfma_f32_32x32x16_bf16 v[16:31], v[158:161], v[166:169], v[16:31]
	v_mfma_f32_32x32x16_bf16 v[0:15], v[158:161], v[174:177], v[0:15]
	global_load_dwordx4 v[72:75], v[182:183], off offset:768
	global_load_dwordx4 v[76:79], v[186:187], off offset:768
	global_load_dwordx4 v[88:91], v[188:189], off offset:768
	global_load_dwordx4 v[92:95], v[190:191], off offset:768
	global_load_dwordx4 v[104:107], v[184:185], off offset:768
	global_load_dwordx4 v[108:111], v[192:193], off offset:768
	s_waitcnt lgkmcnt(0)
	s_barrier
	ds_read_b128 v[162:165], v203 offset:55296
	ds_read_b128 v[130:133], v203 offset:55328
	ds_read_b128 v[170:173], v235
	ds_read_b128 v[134:137], v235 offset:32
	ds_read_b128 v[166:169], v203 offset:59904
	ds_read_b128 v[142:145], v203 offset:59936
	ds_read_b128 v[174:177], v235 offset:4608
	ds_read_b128 v[150:153], v235 offset:4640
	ds_read_b128 v[138:141], v203 offset:55360
	ds_read_b128 v[116:119], v203 offset:55392
	ds_read_b128 v[146:149], v203 offset:59968
	ds_read_b128 v[112:115], v203 offset:60000
	ds_read_b128 v[154:157], v235 offset:64
	ds_read_b128 v[120:123], v235 offset:96
	ds_read_b128 v[158:161], v235 offset:4672
	ds_read_b128 v[124:127], v235 offset:4704
	s_waitcnt lgkmcnt(0)
	s_barrier
	v_mfma_f32_32x32x16_bf16 v[48:63], v[162:165], v[170:173], v[48:63]
	v_mfma_f32_32x32x16_bf16 v[32:47], v[162:165], v[174:177], v[32:47]
	s_waitcnt vmcnt(11)
	ds_write_b128 v201, v[64:67] offset:55296
	v_mfma_f32_32x32x16_bf16 v[16:31], v[166:169], v[170:173], v[16:31]
	v_mfma_f32_32x32x16_bf16 v[0:15], v[166:169], v[174:177], v[0:15]
	s_waitcnt vmcnt(10)
	ds_write_b128 v201, v[68:71] offset:64512
	v_mfma_f32_32x32x16_bf16 v[48:63], v[130:133], v[134:137], v[48:63]
	v_mfma_f32_32x32x16_bf16 v[32:47], v[130:133], v[150:153], v[32:47]
	s_waitcnt vmcnt(9)
	ds_write_b128 v205, v[80:83] offset:18432
	v_mfma_f32_32x32x16_bf16 v[16:31], v[142:145], v[134:137], v[16:31]
	v_mfma_f32_32x32x16_bf16 v[0:15], v[142:145], v[150:153], v[0:15]
	s_waitcnt vmcnt(8)
	ds_write_b128 v205, v[84:87] offset:27648
	v_mfma_f32_32x32x16_bf16 v[48:63], v[138:141], v[154:157], v[48:63]
	v_mfma_f32_32x32x16_bf16 v[32:47], v[138:141], v[158:161], v[32:47]
	s_waitcnt vmcnt(7)
	ds_write_b128 v234, v[96:99]
	v_mfma_f32_32x32x16_bf16 v[16:31], v[146:149], v[154:157], v[16:31]
	v_mfma_f32_32x32x16_bf16 v[0:15], v[146:149], v[158:161], v[0:15]
	s_waitcnt vmcnt(6)
	ds_write_b128 v234, v[100:103] offset:9216
	v_mfma_f32_32x32x16_bf16 v[48:63], v[116:119], v[120:123], v[48:63]
	v_mfma_f32_32x32x16_bf16 v[32:47], v[116:119], v[124:127], v[32:47]
	v_mfma_f32_32x32x16_bf16 v[16:31], v[112:115], v[120:123], v[16:31]
	v_mfma_f32_32x32x16_bf16 v[0:15], v[112:115], v[124:127], v[0:15]
	global_load_dwordx4 v[64:67], v[182:183], off offset:896
	global_load_dwordx4 v[68:71], v[186:187], off offset:896
	global_load_dwordx4 v[80:83], v[188:189], off offset:896
	global_load_dwordx4 v[84:87], v[190:191], off offset:896
	global_load_dwordx4 v[96:99], v[184:185], off offset:896
	global_load_dwordx4 v[100:103], v[192:193], off offset:896
	s_waitcnt lgkmcnt(0)
	s_barrier
	ds_read_b128 v[112:115], v203
	ds_read_b128 v[116:119], v203 offset:32
	ds_read_b128 v[120:123], v203 offset:4608
	ds_read_b128 v[124:127], v203 offset:4640
	ds_read_b128 v[130:133], v204 offset:36864
	ds_read_b128 v[134:137], v204 offset:36896
	ds_read_b128 v[138:141], v204 offset:41472
	ds_read_b128 v[142:145], v204 offset:41504
	ds_read_b128 v[146:149], v203 offset:64
	ds_read_b128 v[150:153], v203 offset:96
	ds_read_b128 v[154:157], v203 offset:4672
	ds_read_b128 v[158:161], v203 offset:4704
	ds_read_b128 v[162:165], v204 offset:36928
	ds_read_b128 v[166:169], v204 offset:36960
	ds_read_b128 v[170:173], v204 offset:41536
	ds_read_b128 v[174:177], v204 offset:41568
	s_waitcnt lgkmcnt(0)
	s_barrier
	v_mfma_f32_32x32x16_bf16 v[48:63], v[112:115], v[130:133], v[48:63]
	v_mfma_f32_32x32x16_bf16 v[32:47], v[112:115], v[138:141], v[32:47]
	s_waitcnt vmcnt(11)
	ds_write_b128 v201, v[72:75]
	v_mfma_f32_32x32x16_bf16 v[16:31], v[120:123], v[130:133], v[16:31]
	v_mfma_f32_32x32x16_bf16 v[0:15], v[120:123], v[138:141], v[0:15]
	s_waitcnt vmcnt(10)
	ds_write_b128 v201, v[76:79] offset:9216
	v_mfma_f32_32x32x16_bf16 v[48:63], v[116:119], v[134:137], v[48:63]
	v_mfma_f32_32x32x16_bf16 v[32:47], v[116:119], v[142:145], v[32:47]
	s_waitcnt vmcnt(9)
	ds_write_b128 v201, v[88:91] offset:18432
	v_mfma_f32_32x32x16_bf16 v[16:31], v[124:127], v[134:137], v[16:31]
	v_mfma_f32_32x32x16_bf16 v[0:15], v[124:127], v[142:145], v[0:15]
	s_waitcnt vmcnt(8)
	ds_write_b128 v201, v[92:95] offset:27648
	v_mfma_f32_32x32x16_bf16 v[48:63], v[146:149], v[162:165], v[48:63]
	v_mfma_f32_32x32x16_bf16 v[32:47], v[146:149], v[170:173], v[32:47]
	s_waitcnt vmcnt(7)
	ds_write_b128 v201, v[104:107] offset:36864
	v_mfma_f32_32x32x16_bf16 v[16:31], v[154:157], v[162:165], v[16:31]
	v_mfma_f32_32x32x16_bf16 v[0:15], v[154:157], v[170:173], v[0:15]
	s_waitcnt vmcnt(6)
	ds_write_b128 v201, v[108:111] offset:46080
	v_mfma_f32_32x32x16_bf16 v[48:63], v[150:153], v[166:169], v[48:63]
	v_mfma_f32_32x32x16_bf16 v[32:47], v[150:153], v[174:177], v[32:47]
	v_mfma_f32_32x32x16_bf16 v[16:31], v[158:161], v[166:169], v[16:31]
	v_mfma_f32_32x32x16_bf16 v[0:15], v[158:161], v[174:177], v[0:15]
	global_load_dwordx4 v[72:75], v[182:183], off offset:1024
	global_load_dwordx4 v[76:79], v[186:187], off offset:1024
	global_load_dwordx4 v[88:91], v[188:189], off offset:1024
	global_load_dwordx4 v[92:95], v[190:191], off offset:1024
	global_load_dwordx4 v[104:107], v[184:185], off offset:1024
	global_load_dwordx4 v[108:111], v[192:193], off offset:1024
	s_waitcnt lgkmcnt(0)
	s_barrier
	ds_read_b128 v[162:165], v203 offset:55296
	ds_read_b128 v[130:133], v203 offset:55328
	ds_read_b128 v[170:173], v235
	ds_read_b128 v[134:137], v235 offset:32
	ds_read_b128 v[166:169], v203 offset:59904
	ds_read_b128 v[142:145], v203 offset:59936
	ds_read_b128 v[174:177], v235 offset:4608
	ds_read_b128 v[150:153], v235 offset:4640
	ds_read_b128 v[138:141], v203 offset:55360
	ds_read_b128 v[116:119], v203 offset:55392
	ds_read_b128 v[146:149], v203 offset:59968
	ds_read_b128 v[112:115], v203 offset:60000
	ds_read_b128 v[154:157], v235 offset:64
	ds_read_b128 v[120:123], v235 offset:96
	ds_read_b128 v[158:161], v235 offset:4672
	ds_read_b128 v[124:127], v235 offset:4704
	s_waitcnt lgkmcnt(0)
	s_barrier
	v_mfma_f32_32x32x16_bf16 v[48:63], v[162:165], v[170:173], v[48:63]
	v_mfma_f32_32x32x16_bf16 v[32:47], v[162:165], v[174:177], v[32:47]
	s_waitcnt vmcnt(11)
	ds_write_b128 v201, v[64:67] offset:55296
	v_mfma_f32_32x32x16_bf16 v[16:31], v[166:169], v[170:173], v[16:31]
	v_mfma_f32_32x32x16_bf16 v[0:15], v[166:169], v[174:177], v[0:15]
	s_waitcnt vmcnt(10)
	ds_write_b128 v201, v[68:71] offset:64512
	v_mfma_f32_32x32x16_bf16 v[48:63], v[130:133], v[134:137], v[48:63]
	v_mfma_f32_32x32x16_bf16 v[32:47], v[130:133], v[150:153], v[32:47]
	s_waitcnt vmcnt(9)
	ds_write_b128 v205, v[80:83] offset:18432
	v_mfma_f32_32x32x16_bf16 v[16:31], v[142:145], v[134:137], v[16:31]
	v_mfma_f32_32x32x16_bf16 v[0:15], v[142:145], v[150:153], v[0:15]
	s_waitcnt vmcnt(8)
	ds_write_b128 v205, v[84:87] offset:27648
	v_mfma_f32_32x32x16_bf16 v[48:63], v[138:141], v[154:157], v[48:63]
	v_mfma_f32_32x32x16_bf16 v[32:47], v[138:141], v[158:161], v[32:47]
	s_waitcnt vmcnt(7)
	ds_write_b128 v234, v[96:99]
	v_mfma_f32_32x32x16_bf16 v[16:31], v[146:149], v[154:157], v[16:31]
	v_mfma_f32_32x32x16_bf16 v[0:15], v[146:149], v[158:161], v[0:15]
	s_waitcnt vmcnt(6)
	ds_write_b128 v234, v[100:103] offset:9216
	v_mfma_f32_32x32x16_bf16 v[48:63], v[116:119], v[120:123], v[48:63]
	v_mfma_f32_32x32x16_bf16 v[32:47], v[116:119], v[124:127], v[32:47]
	v_mfma_f32_32x32x16_bf16 v[16:31], v[112:115], v[120:123], v[16:31]
	v_mfma_f32_32x32x16_bf16 v[0:15], v[112:115], v[124:127], v[0:15]
	global_load_dwordx4 v[64:67], v[182:183], off offset:1152
	global_load_dwordx4 v[68:71], v[186:187], off offset:1152
	global_load_dwordx4 v[80:83], v[188:189], off offset:1152
	global_load_dwordx4 v[84:87], v[190:191], off offset:1152
	global_load_dwordx4 v[96:99], v[184:185], off offset:1152
	global_load_dwordx4 v[100:103], v[192:193], off offset:1152
	s_waitcnt lgkmcnt(0)
	s_barrier
	ds_read_b128 v[112:115], v203
	ds_read_b128 v[116:119], v203 offset:32
	ds_read_b128 v[120:123], v203 offset:4608
	ds_read_b128 v[124:127], v203 offset:4640
	ds_read_b128 v[130:133], v204 offset:36864
	ds_read_b128 v[134:137], v204 offset:36896
	ds_read_b128 v[138:141], v204 offset:41472
	ds_read_b128 v[142:145], v204 offset:41504
	ds_read_b128 v[146:149], v203 offset:64
	ds_read_b128 v[150:153], v203 offset:96
	ds_read_b128 v[154:157], v203 offset:4672
	ds_read_b128 v[158:161], v203 offset:4704
	ds_read_b128 v[162:165], v204 offset:36928
	ds_read_b128 v[166:169], v204 offset:36960
	ds_read_b128 v[170:173], v204 offset:41536
	ds_read_b128 v[174:177], v204 offset:41568
	s_waitcnt lgkmcnt(0)
	s_barrier
	v_mfma_f32_32x32x16_bf16 v[48:63], v[112:115], v[130:133], v[48:63]
	v_mfma_f32_32x32x16_bf16 v[32:47], v[112:115], v[138:141], v[32:47]
	s_waitcnt vmcnt(11)
	ds_write_b128 v201, v[72:75]
	v_mfma_f32_32x32x16_bf16 v[16:31], v[120:123], v[130:133], v[16:31]
	v_mfma_f32_32x32x16_bf16 v[0:15], v[120:123], v[138:141], v[0:15]
	s_waitcnt vmcnt(10)
	ds_write_b128 v201, v[76:79] offset:9216
	v_mfma_f32_32x32x16_bf16 v[48:63], v[116:119], v[134:137], v[48:63]
	v_mfma_f32_32x32x16_bf16 v[32:47], v[116:119], v[142:145], v[32:47]
	s_waitcnt vmcnt(9)
	ds_write_b128 v201, v[88:91] offset:18432
	v_mfma_f32_32x32x16_bf16 v[16:31], v[124:127], v[134:137], v[16:31]
	v_mfma_f32_32x32x16_bf16 v[0:15], v[124:127], v[142:145], v[0:15]
	s_waitcnt vmcnt(8)
	ds_write_b128 v201, v[92:95] offset:27648
	v_mfma_f32_32x32x16_bf16 v[48:63], v[146:149], v[162:165], v[48:63]
	v_mfma_f32_32x32x16_bf16 v[32:47], v[146:149], v[170:173], v[32:47]
	s_waitcnt vmcnt(7)
	ds_write_b128 v201, v[104:107] offset:36864
	v_mfma_f32_32x32x16_bf16 v[16:31], v[154:157], v[162:165], v[16:31]
	v_mfma_f32_32x32x16_bf16 v[0:15], v[154:157], v[170:173], v[0:15]
	s_waitcnt vmcnt(6)
	ds_write_b128 v201, v[108:111] offset:46080
	v_mfma_f32_32x32x16_bf16 v[48:63], v[150:153], v[166:169], v[48:63]
	v_mfma_f32_32x32x16_bf16 v[32:47], v[150:153], v[174:177], v[32:47]
	v_mfma_f32_32x32x16_bf16 v[16:31], v[158:161], v[166:169], v[16:31]
	v_mfma_f32_32x32x16_bf16 v[0:15], v[158:161], v[174:177], v[0:15]
	global_load_dwordx4 v[72:75], v[182:183], off offset:1280
	global_load_dwordx4 v[76:79], v[186:187], off offset:1280
	global_load_dwordx4 v[88:91], v[188:189], off offset:1280
	global_load_dwordx4 v[92:95], v[190:191], off offset:1280
	global_load_dwordx4 v[104:107], v[184:185], off offset:1280
	global_load_dwordx4 v[108:111], v[192:193], off offset:1280
	s_waitcnt lgkmcnt(0)
	s_barrier
	ds_read_b128 v[162:165], v203 offset:55296
	ds_read_b128 v[130:133], v203 offset:55328
	ds_read_b128 v[170:173], v235
	ds_read_b128 v[134:137], v235 offset:32
	ds_read_b128 v[166:169], v203 offset:59904
	ds_read_b128 v[142:145], v203 offset:59936
	ds_read_b128 v[174:177], v235 offset:4608
	ds_read_b128 v[150:153], v235 offset:4640
	ds_read_b128 v[138:141], v203 offset:55360
	ds_read_b128 v[116:119], v203 offset:55392
	ds_read_b128 v[146:149], v203 offset:59968
	ds_read_b128 v[112:115], v203 offset:60000
	ds_read_b128 v[154:157], v235 offset:64
	ds_read_b128 v[120:123], v235 offset:96
	ds_read_b128 v[158:161], v235 offset:4672
	ds_read_b128 v[124:127], v235 offset:4704
	s_waitcnt lgkmcnt(0)
	s_barrier
	v_mfma_f32_32x32x16_bf16 v[48:63], v[162:165], v[170:173], v[48:63]
	v_mfma_f32_32x32x16_bf16 v[32:47], v[162:165], v[174:177], v[32:47]
	s_waitcnt vmcnt(11)
	ds_write_b128 v201, v[64:67] offset:55296
	v_mfma_f32_32x32x16_bf16 v[16:31], v[166:169], v[170:173], v[16:31]
	v_mfma_f32_32x32x16_bf16 v[0:15], v[166:169], v[174:177], v[0:15]
	s_waitcnt vmcnt(10)
	ds_write_b128 v201, v[68:71] offset:64512
	v_mfma_f32_32x32x16_bf16 v[48:63], v[130:133], v[134:137], v[48:63]
	v_mfma_f32_32x32x16_bf16 v[32:47], v[130:133], v[150:153], v[32:47]
	s_waitcnt vmcnt(9)
	ds_write_b128 v205, v[80:83] offset:18432
	v_mfma_f32_32x32x16_bf16 v[16:31], v[142:145], v[134:137], v[16:31]
	v_mfma_f32_32x32x16_bf16 v[0:15], v[142:145], v[150:153], v[0:15]
	s_waitcnt vmcnt(8)
	ds_write_b128 v205, v[84:87] offset:27648
	v_mfma_f32_32x32x16_bf16 v[48:63], v[138:141], v[154:157], v[48:63]
	v_mfma_f32_32x32x16_bf16 v[32:47], v[138:141], v[158:161], v[32:47]
	s_waitcnt vmcnt(7)
	ds_write_b128 v234, v[96:99]
	v_mfma_f32_32x32x16_bf16 v[16:31], v[146:149], v[154:157], v[16:31]
	v_mfma_f32_32x32x16_bf16 v[0:15], v[146:149], v[158:161], v[0:15]
	s_waitcnt vmcnt(6)
	ds_write_b128 v234, v[100:103] offset:9216
	v_mfma_f32_32x32x16_bf16 v[48:63], v[116:119], v[120:123], v[48:63]
	v_mfma_f32_32x32x16_bf16 v[32:47], v[116:119], v[124:127], v[32:47]
	v_mfma_f32_32x32x16_bf16 v[16:31], v[112:115], v[120:123], v[16:31]
	v_mfma_f32_32x32x16_bf16 v[0:15], v[112:115], v[124:127], v[0:15]
	global_load_dwordx4 v[64:67], v[182:183], off offset:1408
	global_load_dwordx4 v[68:71], v[186:187], off offset:1408
	global_load_dwordx4 v[80:83], v[188:189], off offset:1408
	global_load_dwordx4 v[84:87], v[190:191], off offset:1408
	global_load_dwordx4 v[96:99], v[184:185], off offset:1408
	global_load_dwordx4 v[100:103], v[192:193], off offset:1408
	s_waitcnt lgkmcnt(0)
	s_barrier
	ds_read_b128 v[112:115], v203
	ds_read_b128 v[116:119], v203 offset:32
	ds_read_b128 v[120:123], v203 offset:4608
	ds_read_b128 v[124:127], v203 offset:4640
	ds_read_b128 v[130:133], v204 offset:36864
	ds_read_b128 v[134:137], v204 offset:36896
	ds_read_b128 v[138:141], v204 offset:41472
	ds_read_b128 v[142:145], v204 offset:41504
	ds_read_b128 v[146:149], v203 offset:64
	ds_read_b128 v[150:153], v203 offset:96
	ds_read_b128 v[154:157], v203 offset:4672
	ds_read_b128 v[158:161], v203 offset:4704
	ds_read_b128 v[162:165], v204 offset:36928
	ds_read_b128 v[166:169], v204 offset:36960
	ds_read_b128 v[170:173], v204 offset:41536
	ds_read_b128 v[174:177], v204 offset:41568
	s_waitcnt lgkmcnt(0)
	s_barrier
	v_mfma_f32_32x32x16_bf16 v[48:63], v[112:115], v[130:133], v[48:63]
	v_mfma_f32_32x32x16_bf16 v[32:47], v[112:115], v[138:141], v[32:47]
	s_waitcnt vmcnt(11)
	ds_write_b128 v201, v[72:75]
	v_mfma_f32_32x32x16_bf16 v[16:31], v[120:123], v[130:133], v[16:31]
	v_mfma_f32_32x32x16_bf16 v[0:15], v[120:123], v[138:141], v[0:15]
	s_waitcnt vmcnt(10)
	ds_write_b128 v201, v[76:79] offset:9216
	v_mfma_f32_32x32x16_bf16 v[48:63], v[116:119], v[134:137], v[48:63]
	v_mfma_f32_32x32x16_bf16 v[32:47], v[116:119], v[142:145], v[32:47]
	s_waitcnt vmcnt(9)
	ds_write_b128 v201, v[88:91] offset:18432
	v_mfma_f32_32x32x16_bf16 v[16:31], v[124:127], v[134:137], v[16:31]
	v_mfma_f32_32x32x16_bf16 v[0:15], v[124:127], v[142:145], v[0:15]
	s_waitcnt vmcnt(8)
	ds_write_b128 v201, v[92:95] offset:27648
	v_mfma_f32_32x32x16_bf16 v[48:63], v[146:149], v[162:165], v[48:63]
	v_mfma_f32_32x32x16_bf16 v[32:47], v[146:149], v[170:173], v[32:47]
	s_waitcnt vmcnt(7)
	ds_write_b128 v201, v[104:107] offset:36864
	v_mfma_f32_32x32x16_bf16 v[16:31], v[154:157], v[162:165], v[16:31]
	v_mfma_f32_32x32x16_bf16 v[0:15], v[154:157], v[170:173], v[0:15]
	s_waitcnt vmcnt(6)
	ds_write_b128 v201, v[108:111] offset:46080
	v_mfma_f32_32x32x16_bf16 v[48:63], v[150:153], v[166:169], v[48:63]
	v_mfma_f32_32x32x16_bf16 v[32:47], v[150:153], v[174:177], v[32:47]
	v_mfma_f32_32x32x16_bf16 v[16:31], v[158:161], v[166:169], v[16:31]
	v_mfma_f32_32x32x16_bf16 v[0:15], v[158:161], v[174:177], v[0:15]
	global_load_dwordx4 v[72:75], v[182:183], off offset:1536
	global_load_dwordx4 v[76:79], v[186:187], off offset:1536
	global_load_dwordx4 v[88:91], v[188:189], off offset:1536
	global_load_dwordx4 v[92:95], v[190:191], off offset:1536
	global_load_dwordx4 v[104:107], v[184:185], off offset:1536
	global_load_dwordx4 v[108:111], v[192:193], off offset:1536
	s_waitcnt lgkmcnt(0)
	s_barrier
	ds_read_b128 v[162:165], v203 offset:55296
	ds_read_b128 v[130:133], v203 offset:55328
	ds_read_b128 v[170:173], v235
	ds_read_b128 v[134:137], v235 offset:32
	ds_read_b128 v[166:169], v203 offset:59904
	ds_read_b128 v[142:145], v203 offset:59936
	ds_read_b128 v[174:177], v235 offset:4608
	ds_read_b128 v[150:153], v235 offset:4640
	ds_read_b128 v[138:141], v203 offset:55360
	ds_read_b128 v[116:119], v203 offset:55392
	ds_read_b128 v[146:149], v203 offset:59968
	ds_read_b128 v[112:115], v203 offset:60000
	ds_read_b128 v[154:157], v235 offset:64
	ds_read_b128 v[120:123], v235 offset:96
	ds_read_b128 v[158:161], v235 offset:4672
	ds_read_b128 v[124:127], v235 offset:4704
	s_waitcnt lgkmcnt(0)
	s_barrier
	v_mfma_f32_32x32x16_bf16 v[48:63], v[162:165], v[170:173], v[48:63]
	v_mfma_f32_32x32x16_bf16 v[32:47], v[162:165], v[174:177], v[32:47]
	s_waitcnt vmcnt(11)
	ds_write_b128 v201, v[64:67] offset:55296
	v_mfma_f32_32x32x16_bf16 v[16:31], v[166:169], v[170:173], v[16:31]
	v_mfma_f32_32x32x16_bf16 v[0:15], v[166:169], v[174:177], v[0:15]
	s_waitcnt vmcnt(10)
	ds_write_b128 v201, v[68:71] offset:64512
	v_mfma_f32_32x32x16_bf16 v[48:63], v[130:133], v[134:137], v[48:63]
	v_mfma_f32_32x32x16_bf16 v[32:47], v[130:133], v[150:153], v[32:47]
	s_waitcnt vmcnt(9)
	ds_write_b128 v205, v[80:83] offset:18432
	v_mfma_f32_32x32x16_bf16 v[16:31], v[142:145], v[134:137], v[16:31]
	v_mfma_f32_32x32x16_bf16 v[0:15], v[142:145], v[150:153], v[0:15]
	s_waitcnt vmcnt(8)
	ds_write_b128 v205, v[84:87] offset:27648
	v_mfma_f32_32x32x16_bf16 v[48:63], v[138:141], v[154:157], v[48:63]
	v_mfma_f32_32x32x16_bf16 v[32:47], v[138:141], v[158:161], v[32:47]
	s_waitcnt vmcnt(7)
	ds_write_b128 v234, v[96:99]
	v_mfma_f32_32x32x16_bf16 v[16:31], v[146:149], v[154:157], v[16:31]
	v_mfma_f32_32x32x16_bf16 v[0:15], v[146:149], v[158:161], v[0:15]
	s_waitcnt vmcnt(6)
	ds_write_b128 v234, v[100:103] offset:9216
	v_mfma_f32_32x32x16_bf16 v[48:63], v[116:119], v[120:123], v[48:63]
	v_mfma_f32_32x32x16_bf16 v[32:47], v[116:119], v[124:127], v[32:47]
	v_mfma_f32_32x32x16_bf16 v[16:31], v[112:115], v[120:123], v[16:31]
	v_mfma_f32_32x32x16_bf16 v[0:15], v[112:115], v[124:127], v[0:15]
	global_load_dwordx4 v[64:67], v[182:183], off offset:1664
	global_load_dwordx4 v[68:71], v[186:187], off offset:1664
	global_load_dwordx4 v[80:83], v[188:189], off offset:1664
	global_load_dwordx4 v[84:87], v[190:191], off offset:1664
	global_load_dwordx4 v[96:99], v[184:185], off offset:1664
	global_load_dwordx4 v[100:103], v[192:193], off offset:1664
	s_waitcnt lgkmcnt(0)
	s_barrier
	ds_read_b128 v[112:115], v203
	ds_read_b128 v[116:119], v203 offset:32
	ds_read_b128 v[120:123], v203 offset:4608
	ds_read_b128 v[124:127], v203 offset:4640
	ds_read_b128 v[130:133], v204 offset:36864
	ds_read_b128 v[134:137], v204 offset:36896
	ds_read_b128 v[138:141], v204 offset:41472
	ds_read_b128 v[142:145], v204 offset:41504
	ds_read_b128 v[146:149], v203 offset:64
	ds_read_b128 v[150:153], v203 offset:96
	ds_read_b128 v[154:157], v203 offset:4672
	ds_read_b128 v[158:161], v203 offset:4704
	ds_read_b128 v[162:165], v204 offset:36928
	ds_read_b128 v[166:169], v204 offset:36960
	ds_read_b128 v[170:173], v204 offset:41536
	ds_read_b128 v[174:177], v204 offset:41568
	s_waitcnt lgkmcnt(0)
	s_barrier
	v_mfma_f32_32x32x16_bf16 v[48:63], v[112:115], v[130:133], v[48:63]
	v_mfma_f32_32x32x16_bf16 v[32:47], v[112:115], v[138:141], v[32:47]
	s_waitcnt vmcnt(11)
	ds_write_b128 v201, v[72:75]
	v_mfma_f32_32x32x16_bf16 v[16:31], v[120:123], v[130:133], v[16:31]
	v_mfma_f32_32x32x16_bf16 v[0:15], v[120:123], v[138:141], v[0:15]
	s_waitcnt vmcnt(10)
	ds_write_b128 v201, v[76:79] offset:9216
	v_mfma_f32_32x32x16_bf16 v[48:63], v[116:119], v[134:137], v[48:63]
	v_mfma_f32_32x32x16_bf16 v[32:47], v[116:119], v[142:145], v[32:47]
	s_waitcnt vmcnt(9)
	ds_write_b128 v201, v[88:91] offset:18432
	v_mfma_f32_32x32x16_bf16 v[16:31], v[124:127], v[134:137], v[16:31]
	v_mfma_f32_32x32x16_bf16 v[0:15], v[124:127], v[142:145], v[0:15]
	s_waitcnt vmcnt(8)
	ds_write_b128 v201, v[92:95] offset:27648
	v_mfma_f32_32x32x16_bf16 v[48:63], v[146:149], v[162:165], v[48:63]
	v_mfma_f32_32x32x16_bf16 v[32:47], v[146:149], v[170:173], v[32:47]
	s_waitcnt vmcnt(7)
	ds_write_b128 v201, v[104:107] offset:36864
	v_mfma_f32_32x32x16_bf16 v[16:31], v[154:157], v[162:165], v[16:31]
	v_mfma_f32_32x32x16_bf16 v[0:15], v[154:157], v[170:173], v[0:15]
	s_waitcnt vmcnt(6)
	ds_write_b128 v201, v[108:111] offset:46080
	v_mfma_f32_32x32x16_bf16 v[48:63], v[150:153], v[166:169], v[48:63]
	v_mfma_f32_32x32x16_bf16 v[32:47], v[150:153], v[174:177], v[32:47]
	v_mfma_f32_32x32x16_bf16 v[16:31], v[158:161], v[166:169], v[16:31]
	v_mfma_f32_32x32x16_bf16 v[0:15], v[158:161], v[174:177], v[0:15]
	global_load_dwordx4 v[72:75], v[182:183], off offset:1792
	global_load_dwordx4 v[76:79], v[186:187], off offset:1792
	global_load_dwordx4 v[88:91], v[188:189], off offset:1792
	global_load_dwordx4 v[92:95], v[190:191], off offset:1792
	global_load_dwordx4 v[104:107], v[184:185], off offset:1792
	global_load_dwordx4 v[108:111], v[192:193], off offset:1792
	s_waitcnt lgkmcnt(0)
	s_barrier
	ds_read_b128 v[162:165], v203 offset:55296
	ds_read_b128 v[130:133], v203 offset:55328
	ds_read_b128 v[170:173], v235
	ds_read_b128 v[134:137], v235 offset:32
	ds_read_b128 v[166:169], v203 offset:59904
	ds_read_b128 v[142:145], v203 offset:59936
	ds_read_b128 v[174:177], v235 offset:4608
	ds_read_b128 v[150:153], v235 offset:4640
	ds_read_b128 v[138:141], v203 offset:55360
	ds_read_b128 v[116:119], v203 offset:55392
	ds_read_b128 v[146:149], v203 offset:59968
	ds_read_b128 v[112:115], v203 offset:60000
	ds_read_b128 v[154:157], v235 offset:64
	ds_read_b128 v[120:123], v235 offset:96
	ds_read_b128 v[158:161], v235 offset:4672
	ds_read_b128 v[124:127], v235 offset:4704
	s_waitcnt lgkmcnt(0)
	s_barrier
	v_mfma_f32_32x32x16_bf16 v[48:63], v[162:165], v[170:173], v[48:63]
	v_mfma_f32_32x32x16_bf16 v[32:47], v[162:165], v[174:177], v[32:47]
	s_waitcnt vmcnt(11)
	ds_write_b128 v201, v[64:67] offset:55296
	v_mfma_f32_32x32x16_bf16 v[16:31], v[166:169], v[170:173], v[16:31]
	v_mfma_f32_32x32x16_bf16 v[0:15], v[166:169], v[174:177], v[0:15]
	s_waitcnt vmcnt(10)
	ds_write_b128 v201, v[68:71] offset:64512
	v_mfma_f32_32x32x16_bf16 v[48:63], v[130:133], v[134:137], v[48:63]
	v_mfma_f32_32x32x16_bf16 v[32:47], v[130:133], v[150:153], v[32:47]
	s_waitcnt vmcnt(9)
	ds_write_b128 v205, v[80:83] offset:18432
	v_mfma_f32_32x32x16_bf16 v[16:31], v[142:145], v[134:137], v[16:31]
	v_mfma_f32_32x32x16_bf16 v[0:15], v[142:145], v[150:153], v[0:15]
	s_waitcnt vmcnt(8)
	ds_write_b128 v205, v[84:87] offset:27648
	v_mfma_f32_32x32x16_bf16 v[48:63], v[138:141], v[154:157], v[48:63]
	v_mfma_f32_32x32x16_bf16 v[32:47], v[138:141], v[158:161], v[32:47]
	s_waitcnt vmcnt(7)
	ds_write_b128 v234, v[96:99]
	v_mfma_f32_32x32x16_bf16 v[16:31], v[146:149], v[154:157], v[16:31]
	v_mfma_f32_32x32x16_bf16 v[0:15], v[146:149], v[158:161], v[0:15]
	s_waitcnt vmcnt(6)
	ds_write_b128 v234, v[100:103] offset:9216
	v_mfma_f32_32x32x16_bf16 v[48:63], v[116:119], v[120:123], v[48:63]
	v_mfma_f32_32x32x16_bf16 v[32:47], v[116:119], v[124:127], v[32:47]
	v_mfma_f32_32x32x16_bf16 v[16:31], v[112:115], v[120:123], v[16:31]
	v_mfma_f32_32x32x16_bf16 v[0:15], v[112:115], v[124:127], v[0:15]
	global_load_dwordx4 v[64:67], v[182:183], off offset:1920
	global_load_dwordx4 v[68:71], v[186:187], off offset:1920
	global_load_dwordx4 v[80:83], v[188:189], off offset:1920
	global_load_dwordx4 v[84:87], v[190:191], off offset:1920
	global_load_dwordx4 v[96:99], v[184:185], off offset:1920
	global_load_dwordx4 v[100:103], v[192:193], off offset:1920
	s_waitcnt lgkmcnt(0)
	s_barrier
	ds_read_b128 v[112:115], v203
	ds_read_b128 v[116:119], v203 offset:32
	ds_read_b128 v[120:123], v203 offset:4608
	ds_read_b128 v[124:127], v203 offset:4640
	ds_read_b128 v[130:133], v204 offset:36864
	ds_read_b128 v[134:137], v204 offset:36896
	ds_read_b128 v[138:141], v204 offset:41472
	ds_read_b128 v[142:145], v204 offset:41504
	ds_read_b128 v[146:149], v203 offset:64
	ds_read_b128 v[150:153], v203 offset:96
	ds_read_b128 v[154:157], v203 offset:4672
	ds_read_b128 v[158:161], v203 offset:4704
	ds_read_b128 v[162:165], v204 offset:36928
	ds_read_b128 v[166:169], v204 offset:36960
	ds_read_b128 v[170:173], v204 offset:41536
	ds_read_b128 v[174:177], v204 offset:41568
	s_waitcnt lgkmcnt(0)
	s_barrier
	v_mfma_f32_32x32x16_bf16 v[48:63], v[112:115], v[130:133], v[48:63]
	v_mfma_f32_32x32x16_bf16 v[32:47], v[112:115], v[138:141], v[32:47]
	s_waitcnt vmcnt(11)
	ds_write_b128 v201, v[72:75]
	v_mfma_f32_32x32x16_bf16 v[16:31], v[120:123], v[130:133], v[16:31]
	v_mfma_f32_32x32x16_bf16 v[0:15], v[120:123], v[138:141], v[0:15]
	s_waitcnt vmcnt(10)
	ds_write_b128 v201, v[76:79] offset:9216
	v_mfma_f32_32x32x16_bf16 v[48:63], v[116:119], v[134:137], v[48:63]
	v_mfma_f32_32x32x16_bf16 v[32:47], v[116:119], v[142:145], v[32:47]
	s_waitcnt vmcnt(9)
	ds_write_b128 v201, v[88:91] offset:18432
	v_mfma_f32_32x32x16_bf16 v[16:31], v[124:127], v[134:137], v[16:31]
	v_mfma_f32_32x32x16_bf16 v[0:15], v[124:127], v[142:145], v[0:15]
	s_waitcnt vmcnt(8)
	ds_write_b128 v201, v[92:95] offset:27648
	v_mfma_f32_32x32x16_bf16 v[48:63], v[146:149], v[162:165], v[48:63]
	v_mfma_f32_32x32x16_bf16 v[32:47], v[146:149], v[170:173], v[32:47]
	s_waitcnt vmcnt(7)
	ds_write_b128 v201, v[104:107] offset:36864
	v_mfma_f32_32x32x16_bf16 v[16:31], v[154:157], v[162:165], v[16:31]
	v_mfma_f32_32x32x16_bf16 v[0:15], v[154:157], v[170:173], v[0:15]
	s_waitcnt vmcnt(6)
	ds_write_b128 v201, v[108:111] offset:46080
	v_mfma_f32_32x32x16_bf16 v[48:63], v[150:153], v[166:169], v[48:63]
	v_mfma_f32_32x32x16_bf16 v[32:47], v[150:153], v[174:177], v[32:47]
	v_mfma_f32_32x32x16_bf16 v[16:31], v[158:161], v[166:169], v[16:31]
	v_mfma_f32_32x32x16_bf16 v[0:15], v[158:161], v[174:177], v[0:15]
	s_waitcnt lgkmcnt(0)
	s_barrier
	ds_read_b128 v[162:165], v203 offset:55296
	ds_read_b128 v[130:133], v203 offset:55328
	ds_read_b128 v[170:173], v235
	ds_read_b128 v[134:137], v235 offset:32
	ds_read_b128 v[166:169], v203 offset:59904
	ds_read_b128 v[142:145], v203 offset:59936
	ds_read_b128 v[174:177], v235 offset:4608
	ds_read_b128 v[150:153], v235 offset:4640
	ds_read_b128 v[138:141], v203 offset:55360
	ds_read_b128 v[116:119], v203 offset:55392
	ds_read_b128 v[146:149], v203 offset:59968
	ds_read_b128 v[112:115], v203 offset:60000
	ds_read_b128 v[154:157], v235 offset:64
	ds_read_b128 v[120:123], v235 offset:96
	ds_read_b128 v[158:161], v235 offset:4672
	ds_read_b128 v[124:127], v235 offset:4704
	s_waitcnt lgkmcnt(0)
	s_barrier
	v_mfma_f32_32x32x16_bf16 v[48:63], v[162:165], v[170:173], v[48:63]
	v_mfma_f32_32x32x16_bf16 v[32:47], v[162:165], v[174:177], v[32:47]
	s_waitcnt vmcnt(5)
	ds_write_b128 v201, v[64:67] offset:55296
	v_mfma_f32_32x32x16_bf16 v[16:31], v[166:169], v[170:173], v[16:31]
	v_mfma_f32_32x32x16_bf16 v[0:15], v[166:169], v[174:177], v[0:15]
	s_waitcnt vmcnt(4)
	ds_write_b128 v201, v[68:71] offset:64512
	v_mfma_f32_32x32x16_bf16 v[48:63], v[130:133], v[134:137], v[48:63]
	v_mfma_f32_32x32x16_bf16 v[32:47], v[130:133], v[150:153], v[32:47]
	s_waitcnt vmcnt(3)
	ds_write_b128 v205, v[80:83] offset:18432
	v_mfma_f32_32x32x16_bf16 v[16:31], v[142:145], v[134:137], v[16:31]
	v_mfma_f32_32x32x16_bf16 v[0:15], v[142:145], v[150:153], v[0:15]
	s_waitcnt vmcnt(2)
	ds_write_b128 v205, v[84:87] offset:27648
	v_mfma_f32_32x32x16_bf16 v[48:63], v[138:141], v[154:157], v[48:63]
	v_mfma_f32_32x32x16_bf16 v[32:47], v[138:141], v[158:161], v[32:47]
	s_waitcnt vmcnt(1)
	ds_write_b128 v234, v[96:99]
	v_mfma_f32_32x32x16_bf16 v[16:31], v[146:149], v[154:157], v[16:31]
	v_mfma_f32_32x32x16_bf16 v[0:15], v[146:149], v[158:161], v[0:15]
	s_waitcnt vmcnt(0)
	ds_write_b128 v234, v[100:103] offset:9216
	v_mfma_f32_32x32x16_bf16 v[48:63], v[116:119], v[120:123], v[48:63]
	v_mfma_f32_32x32x16_bf16 v[32:47], v[116:119], v[124:127], v[32:47]
	v_mfma_f32_32x32x16_bf16 v[16:31], v[112:115], v[120:123], v[16:31]
	v_mfma_f32_32x32x16_bf16 v[0:15], v[112:115], v[124:127], v[0:15]
	s_waitcnt lgkmcnt(0)
	s_barrier
	ds_read_b128 v[112:115], v203
	ds_read_b128 v[116:119], v203 offset:32
	ds_read_b128 v[120:123], v203 offset:4608
	ds_read_b128 v[124:127], v203 offset:4640
	ds_read_b128 v[130:133], v204 offset:36864
	ds_read_b128 v[134:137], v204 offset:36896
	ds_read_b128 v[138:141], v204 offset:41472
	ds_read_b128 v[142:145], v204 offset:41504
	ds_read_b128 v[146:149], v203 offset:64
	ds_read_b128 v[150:153], v203 offset:96
	ds_read_b128 v[154:157], v203 offset:4672
	ds_read_b128 v[158:161], v203 offset:4704
	ds_read_b128 v[162:165], v204 offset:36928
	ds_read_b128 v[166:169], v204 offset:36960
	ds_read_b128 v[170:173], v204 offset:41536
	ds_read_b128 v[174:177], v204 offset:41568
	s_waitcnt lgkmcnt(0)
	s_barrier
	v_mfma_f32_32x32x16_bf16 v[48:63], v[112:115], v[130:133], v[48:63]
	v_mfma_f32_32x32x16_bf16 v[32:47], v[112:115], v[138:141], v[32:47]
	v_mfma_f32_32x32x16_bf16 v[16:31], v[120:123], v[130:133], v[16:31]
	v_mfma_f32_32x32x16_bf16 v[0:15], v[120:123], v[138:141], v[0:15]
	v_mfma_f32_32x32x16_bf16 v[48:63], v[116:119], v[134:137], v[48:63]
	v_mfma_f32_32x32x16_bf16 v[32:47], v[116:119], v[142:145], v[32:47]
	v_mfma_f32_32x32x16_bf16 v[16:31], v[124:127], v[134:137], v[16:31]
	v_mfma_f32_32x32x16_bf16 v[0:15], v[124:127], v[142:145], v[0:15]
	v_mfma_f32_32x32x16_bf16 v[48:63], v[146:149], v[162:165], v[48:63]
	v_mfma_f32_32x32x16_bf16 v[32:47], v[146:149], v[170:173], v[32:47]
	v_mfma_f32_32x32x16_bf16 v[16:31], v[154:157], v[162:165], v[16:31]
	v_mfma_f32_32x32x16_bf16 v[0:15], v[154:157], v[170:173], v[0:15]
	v_mfma_f32_32x32x16_bf16 v[48:63], v[150:153], v[166:169], v[48:63]
	v_mfma_f32_32x32x16_bf16 v[32:47], v[150:153], v[174:177], v[32:47]
	v_mfma_f32_32x32x16_bf16 v[16:31], v[158:161], v[166:169], v[16:31]
	v_mfma_f32_32x32x16_bf16 v[0:15], v[158:161], v[174:177], v[0:15]
	s_waitcnt lgkmcnt(0)
	s_barrier
	ds_read_b128 v[162:165], v203 offset:55296
	ds_read_b128 v[130:133], v203 offset:55328
	ds_read_b128 v[170:173], v235
	ds_read_b128 v[134:137], v235 offset:32
	ds_read_b128 v[166:169], v203 offset:59904
	ds_read_b128 v[142:145], v203 offset:59936
	ds_read_b128 v[174:177], v235 offset:4608
	ds_read_b128 v[150:153], v235 offset:4640
	ds_read_b128 v[138:141], v203 offset:55360
	ds_read_b128 v[116:119], v203 offset:55392
	ds_read_b128 v[146:149], v203 offset:59968
	ds_read_b128 v[112:115], v203 offset:60000
	ds_read_b128 v[154:157], v235 offset:64
	ds_read_b128 v[120:123], v235 offset:96
	ds_read_b128 v[158:161], v235 offset:4672
	ds_read_b128 v[124:127], v235 offset:4704
	s_waitcnt lgkmcnt(0)
	s_barrier
	v_mfma_f32_32x32x16_bf16 v[48:63], v[162:165], v[170:173], v[48:63]
	v_mfma_f32_32x32x16_bf16 v[32:47], v[162:165], v[174:177], v[32:47]
	v_mfma_f32_32x32x16_bf16 v[16:31], v[166:169], v[170:173], v[16:31]
	v_mfma_f32_32x32x16_bf16 v[0:15], v[166:169], v[174:177], v[0:15]
	v_mfma_f32_32x32x16_bf16 v[48:63], v[130:133], v[134:137], v[48:63]
	v_mfma_f32_32x32x16_bf16 v[32:47], v[130:133], v[150:153], v[32:47]
	v_mfma_f32_32x32x16_bf16 v[16:31], v[142:145], v[134:137], v[16:31]
	v_mfma_f32_32x32x16_bf16 v[0:15], v[142:145], v[150:153], v[0:15]
	v_mfma_f32_32x32x16_bf16 v[48:63], v[138:141], v[154:157], v[48:63]
	v_mfma_f32_32x32x16_bf16 v[32:47], v[138:141], v[158:161], v[32:47]
	v_mfma_f32_32x32x16_bf16 v[16:31], v[146:149], v[154:157], v[16:31]
	v_mfma_f32_32x32x16_bf16 v[0:15], v[146:149], v[158:161], v[0:15]
	v_mfma_f32_32x32x16_bf16 v[48:63], v[116:119], v[120:123], v[48:63]
	v_mfma_f32_32x32x16_bf16 v[32:47], v[116:119], v[124:127], v[32:47]
	v_mfma_f32_32x32x16_bf16 v[16:31], v[112:115], v[120:123], v[16:31]
	v_mfma_f32_32x32x16_bf16 v[0:15], v[112:115], v[124:127], v[0:15]
	s_waitcnt lgkmcnt(0)
	s_barrier
	s_branch .LBB0_1230

.LBB0_1234:
	s_waitcnt lgkmcnt(13)
	v_mfma_f32_32x32x16_bf16 v[48:63], v[116:119], v[124:127], v[48:63]
	s_waitcnt lgkmcnt(9)
	v_mfma_f32_32x32x16_bf16 v[32:47], v[116:119], v[154:157], v[32:47]
	v_mfma_f32_32x32x16_bf16 v[16:31], v[134:137], v[124:127], v[16:31]
	v_mfma_f32_32x32x16_bf16 v[0:15], v[134:137], v[154:157], v[0:15]
	v_mfma_f32_32x32x16_bf16 v[48:63], v[112:115], v[120:123], v[48:63]
	s_waitcnt lgkmcnt(8)
	v_mfma_f32_32x32x16_bf16 v[32:47], v[112:115], v[142:145], v[32:47]
	v_mfma_f32_32x32x16_bf16 v[16:31], v[130:133], v[120:123], v[16:31]
	v_mfma_f32_32x32x16_bf16 v[0:15], v[130:133], v[142:145], v[0:15]
	s_waitcnt lgkmcnt(3)
	v_mfma_f32_32x32x16_bf16 v[48:63], v[138:141], v[170:173], v[48:63]
	s_waitcnt lgkmcnt(1)
	v_mfma_f32_32x32x16_bf16 v[32:47], v[138:141], v[174:177], v[32:47]
	v_mfma_f32_32x32x16_bf16 v[16:31], v[158:161], v[170:173], v[16:31]
	v_mfma_f32_32x32x16_bf16 v[0:15], v[158:161], v[174:177], v[0:15]
	v_mfma_f32_32x32x16_bf16 v[48:63], v[146:149], v[162:165], v[48:63]
	s_waitcnt lgkmcnt(0)
	v_mfma_f32_32x32x16_bf16 v[32:47], v[146:149], v[166:169], v[32:47]
	v_mfma_f32_32x32x16_bf16 v[16:31], v[150:153], v[162:165], v[16:31]
	v_mfma_f32_32x32x16_bf16 v[0:15], v[150:153], v[166:169], v[0:15]
	s_waitcnt lgkmcnt(0)
	s_barrier
	ds_read_b128 v[116:119], v203 offset:55296
	ds_read_b128 v[112:115], v203 offset:55328
	ds_read_b128 v[124:127], v235
	ds_read_b128 v[120:123], v235 offset:32
	ds_read_b128 v[134:137], v203 offset:59904
	ds_read_b128 v[130:133], v203 offset:59936
	ds_read_b128 v[154:157], v235 offset:4608
	ds_read_b128 v[142:145], v235 offset:4640
	ds_read_b128 v[138:141], v203 offset:55360
	ds_read_b128 v[146:149], v203 offset:55392
	ds_read_b128 v[158:161], v203 offset:59968
	ds_read_b128 v[150:153], v203 offset:60000
	ds_read_b128 v[170:173], v235 offset:64
	ds_read_b128 v[162:165], v235 offset:96
	ds_read_b128 v[174:177], v235 offset:4672
	ds_read_b128 v[166:169], v235 offset:4704
	s_waitcnt lgkmcnt(0)
	s_barrier
	v_mfma_f32_32x32x16_bf16 v[48:63], v[116:119], v[124:127], v[48:63]
	v_mfma_f32_32x32x16_bf16 v[32:47], v[116:119], v[154:157], v[32:47]
	s_waitcnt vmcnt(11)
	ds_write_b128 v201, v[64:67]
	v_mfma_f32_32x32x16_bf16 v[16:31], v[134:137], v[124:127], v[16:31]
	v_mfma_f32_32x32x16_bf16 v[0:15], v[134:137], v[154:157], v[0:15]
	s_waitcnt vmcnt(10)
	ds_write_b128 v201, v[68:71] offset:9216
	v_mfma_f32_32x32x16_bf16 v[48:63], v[112:115], v[120:123], v[48:63]
	v_mfma_f32_32x32x16_bf16 v[32:47], v[112:115], v[142:145], v[32:47]
	s_waitcnt vmcnt(8)
	ds_write_b128 v201, v[84:87] offset:18432
	v_mfma_f32_32x32x16_bf16 v[16:31], v[130:133], v[120:123], v[16:31]
	v_mfma_f32_32x32x16_bf16 v[0:15], v[130:133], v[142:145], v[0:15]
	ds_write_b128 v201, v[72:75] offset:27648
	v_mfma_f32_32x32x16_bf16 v[48:63], v[138:141], v[170:173], v[48:63]
	v_mfma_f32_32x32x16_bf16 v[32:47], v[138:141], v[174:177], v[32:47]
	s_waitcnt vmcnt(7)
	ds_write_b128 v201, v[96:99] offset:36864
	v_mfma_f32_32x32x16_bf16 v[16:31], v[158:161], v[170:173], v[16:31]
	v_mfma_f32_32x32x16_bf16 v[0:15], v[158:161], v[174:177], v[0:15]
	s_waitcnt vmcnt(6)
	ds_write_b128 v201, v[100:103] offset:46080
	v_mfma_f32_32x32x16_bf16 v[48:63], v[146:149], v[162:165], v[48:63]
	v_mfma_f32_32x32x16_bf16 v[32:47], v[146:149], v[166:169], v[32:47]
	v_mfma_f32_32x32x16_bf16 v[16:31], v[150:153], v[162:165], v[16:31]
	v_mfma_f32_32x32x16_bf16 v[0:15], v[150:153], v[166:169], v[0:15]
	global_load_dwordx4 v[64:67], v[182:183], off offset:512
	global_load_dwordx4 v[68:71], v[186:187], off offset:512
	global_load_dwordx4 v[84:87], v[188:189], off offset:512
	global_load_dwordx4 v[72:75], v[190:191], off offset:512
	global_load_dwordx4 v[96:99], v[184:185], off offset:512
	global_load_dwordx4 v[100:103], v[192:193], off offset:512
	s_waitcnt lgkmcnt(0)
	s_barrier
	ds_read_b128 v[116:119], v203
	ds_read_b128 v[112:115], v203 offset:32
	ds_read_b128 v[124:127], v204 offset:36864
	ds_read_b128 v[120:123], v204 offset:36896
	ds_read_b128 v[134:137], v203 offset:4608
	ds_read_b128 v[130:133], v203 offset:4640
	ds_read_b128 v[154:157], v204 offset:41472
	ds_read_b128 v[142:145], v204 offset:41504
	ds_read_b128 v[138:141], v203 offset:64
	ds_read_b128 v[146:149], v203 offset:96
	ds_read_b128 v[158:161], v203 offset:4672
	ds_read_b128 v[150:153], v203 offset:4704
	ds_read_b128 v[170:173], v204 offset:36928
	ds_read_b128 v[162:165], v204 offset:36960
	ds_read_b128 v[174:177], v204 offset:41536
	ds_read_b128 v[166:169], v204 offset:41568
	s_waitcnt lgkmcnt(0)
	s_barrier
	v_mfma_f32_32x32x16_bf16 v[48:63], v[116:119], v[124:127], v[48:63]
	v_mfma_f32_32x32x16_bf16 v[32:47], v[116:119], v[154:157], v[32:47]
	s_waitcnt vmcnt(11)
	ds_write_b128 v201, v[76:79] offset:55296
	v_mfma_f32_32x32x16_bf16 v[16:31], v[134:137], v[124:127], v[16:31]
	v_mfma_f32_32x32x16_bf16 v[0:15], v[134:137], v[154:157], v[0:15]
	s_waitcnt vmcnt(10)
	ds_write_b128 v201, v[80:83] offset:64512
	v_mfma_f32_32x32x16_bf16 v[48:63], v[112:115], v[120:123], v[48:63]
	v_mfma_f32_32x32x16_bf16 v[32:47], v[112:115], v[142:145], v[32:47]
	s_waitcnt vmcnt(9)
	ds_write_b128 v205, v[88:91] offset:18432
	v_mfma_f32_32x32x16_bf16 v[16:31], v[130:133], v[120:123], v[16:31]
	v_mfma_f32_32x32x16_bf16 v[0:15], v[130:133], v[142:145], v[0:15]
	s_waitcnt vmcnt(8)
	ds_write_b128 v205, v[92:95] offset:27648
	v_mfma_f32_32x32x16_bf16 v[48:63], v[138:141], v[170:173], v[48:63]
	v_mfma_f32_32x32x16_bf16 v[32:47], v[138:141], v[174:177], v[32:47]
	s_waitcnt vmcnt(7)
	ds_write_b128 v234, v[104:107]
	v_mfma_f32_32x32x16_bf16 v[16:31], v[158:161], v[170:173], v[16:31]
	v_mfma_f32_32x32x16_bf16 v[0:15], v[158:161], v[174:177], v[0:15]
	s_waitcnt vmcnt(6)
	ds_write_b128 v234, v[108:111] offset:9216
	v_mfma_f32_32x32x16_bf16 v[48:63], v[146:149], v[162:165], v[48:63]
	v_mfma_f32_32x32x16_bf16 v[32:47], v[146:149], v[166:169], v[32:47]
	v_mfma_f32_32x32x16_bf16 v[16:31], v[150:153], v[162:165], v[16:31]
	v_mfma_f32_32x32x16_bf16 v[0:15], v[150:153], v[166:169], v[0:15]
	global_load_dwordx4 v[76:79], v[182:183], off offset:640
	global_load_dwordx4 v[80:83], v[186:187], off offset:640
	global_load_dwordx4 v[88:91], v[188:189], off offset:640
	global_load_dwordx4 v[92:95], v[190:191], off offset:640
	global_load_dwordx4 v[104:107], v[184:185], off offset:640
	global_load_dwordx4 v[108:111], v[192:193], off offset:640
	s_waitcnt lgkmcnt(0)
	s_barrier
	ds_read_b128 v[116:119], v203 offset:55296
	ds_read_b128 v[112:115], v203 offset:55328
	ds_read_b128 v[124:127], v235
	ds_read_b128 v[120:123], v235 offset:32
	ds_read_b128 v[134:137], v203 offset:59904
	ds_read_b128 v[130:133], v203 offset:59936
	ds_read_b128 v[154:157], v235 offset:4608
	ds_read_b128 v[142:145], v235 offset:4640
	ds_read_b128 v[138:141], v203 offset:55360
	ds_read_b128 v[146:149], v203 offset:55392
	ds_read_b128 v[158:161], v203 offset:59968
	ds_read_b128 v[150:153], v203 offset:60000
	ds_read_b128 v[170:173], v235 offset:64
	ds_read_b128 v[162:165], v235 offset:96
	ds_read_b128 v[174:177], v235 offset:4672
	ds_read_b128 v[166:169], v235 offset:4704
	s_waitcnt lgkmcnt(0)
	s_barrier
	v_mfma_f32_32x32x16_bf16 v[48:63], v[116:119], v[124:127], v[48:63]
	v_mfma_f32_32x32x16_bf16 v[32:47], v[116:119], v[154:157], v[32:47]
	s_waitcnt vmcnt(11)
	ds_write_b128 v201, v[64:67]
	v_mfma_f32_32x32x16_bf16 v[16:31], v[134:137], v[124:127], v[16:31]
	v_mfma_f32_32x32x16_bf16 v[0:15], v[134:137], v[154:157], v[0:15]
	s_waitcnt vmcnt(10)
	ds_write_b128 v201, v[68:71] offset:9216
	v_mfma_f32_32x32x16_bf16 v[48:63], v[112:115], v[120:123], v[48:63]
	v_mfma_f32_32x32x16_bf16 v[32:47], v[112:115], v[142:145], v[32:47]
	s_waitcnt vmcnt(9)
	ds_write_b128 v201, v[84:87] offset:18432
	v_mfma_f32_32x32x16_bf16 v[16:31], v[130:133], v[120:123], v[16:31]
	v_mfma_f32_32x32x16_bf16 v[0:15], v[130:133], v[142:145], v[0:15]
	s_waitcnt vmcnt(8)
	ds_write_b128 v201, v[72:75] offset:27648
	v_mfma_f32_32x32x16_bf16 v[48:63], v[138:141], v[170:173], v[48:63]
	v_mfma_f32_32x32x16_bf16 v[32:47], v[138:141], v[174:177], v[32:47]
	s_waitcnt vmcnt(7)
	ds_write_b128 v201, v[96:99] offset:36864
	v_mfma_f32_32x32x16_bf16 v[16:31], v[158:161], v[170:173], v[16:31]
	v_mfma_f32_32x32x16_bf16 v[0:15], v[158:161], v[174:177], v[0:15]
	s_waitcnt vmcnt(6)
	ds_write_b128 v201, v[100:103] offset:46080
	v_mfma_f32_32x32x16_bf16 v[48:63], v[146:149], v[162:165], v[48:63]
	v_mfma_f32_32x32x16_bf16 v[32:47], v[146:149], v[166:169], v[32:47]
	v_mfma_f32_32x32x16_bf16 v[16:31], v[150:153], v[162:165], v[16:31]
	v_mfma_f32_32x32x16_bf16 v[0:15], v[150:153], v[166:169], v[0:15]
	global_load_dwordx4 v[64:67], v[182:183], off offset:768
	global_load_dwordx4 v[68:71], v[186:187], off offset:768
	global_load_dwordx4 v[84:87], v[188:189], off offset:768
	global_load_dwordx4 v[72:75], v[190:191], off offset:768
	global_load_dwordx4 v[96:99], v[184:185], off offset:768
	global_load_dwordx4 v[100:103], v[192:193], off offset:768
	s_waitcnt lgkmcnt(0)
	s_barrier
	ds_read_b128 v[116:119], v203
	ds_read_b128 v[112:115], v203 offset:32
	ds_read_b128 v[124:127], v204 offset:36864
	ds_read_b128 v[120:123], v204 offset:36896
	ds_read_b128 v[134:137], v203 offset:4608
	ds_read_b128 v[130:133], v203 offset:4640
	ds_read_b128 v[154:157], v204 offset:41472
	ds_read_b128 v[142:145], v204 offset:41504
	ds_read_b128 v[138:141], v203 offset:64
	ds_read_b128 v[146:149], v203 offset:96
	ds_read_b128 v[158:161], v203 offset:4672
	ds_read_b128 v[150:153], v203 offset:4704
	ds_read_b128 v[170:173], v204 offset:36928
	ds_read_b128 v[162:165], v204 offset:36960
	ds_read_b128 v[174:177], v204 offset:41536
	ds_read_b128 v[166:169], v204 offset:41568
	s_waitcnt lgkmcnt(0)
	s_barrier
	v_mfma_f32_32x32x16_bf16 v[48:63], v[116:119], v[124:127], v[48:63]
	v_mfma_f32_32x32x16_bf16 v[32:47], v[116:119], v[154:157], v[32:47]
	s_waitcnt vmcnt(11)
	ds_write_b128 v201, v[76:79] offset:55296
	v_mfma_f32_32x32x16_bf16 v[16:31], v[134:137], v[124:127], v[16:31]
	v_mfma_f32_32x32x16_bf16 v[0:15], v[134:137], v[154:157], v[0:15]
	s_waitcnt vmcnt(10)
	ds_write_b128 v201, v[80:83] offset:64512
	v_mfma_f32_32x32x16_bf16 v[48:63], v[112:115], v[120:123], v[48:63]
	v_mfma_f32_32x32x16_bf16 v[32:47], v[112:115], v[142:145], v[32:47]
	s_waitcnt vmcnt(9)
	ds_write_b128 v205, v[88:91] offset:18432
	v_mfma_f32_32x32x16_bf16 v[16:31], v[130:133], v[120:123], v[16:31]
	v_mfma_f32_32x32x16_bf16 v[0:15], v[130:133], v[142:145], v[0:15]
	s_waitcnt vmcnt(8)
	ds_write_b128 v205, v[92:95] offset:27648
	v_mfma_f32_32x32x16_bf16 v[48:63], v[138:141], v[170:173], v[48:63]
	v_mfma_f32_32x32x16_bf16 v[32:47], v[138:141], v[174:177], v[32:47]
	s_waitcnt vmcnt(7)
	ds_write_b128 v234, v[104:107]
	v_mfma_f32_32x32x16_bf16 v[16:31], v[158:161], v[170:173], v[16:31]
	v_mfma_f32_32x32x16_bf16 v[0:15], v[158:161], v[174:177], v[0:15]
	s_waitcnt vmcnt(6)
	ds_write_b128 v234, v[108:111] offset:9216
	v_mfma_f32_32x32x16_bf16 v[48:63], v[146:149], v[162:165], v[48:63]
	v_mfma_f32_32x32x16_bf16 v[32:47], v[146:149], v[166:169], v[32:47]
	v_mfma_f32_32x32x16_bf16 v[16:31], v[150:153], v[162:165], v[16:31]
	v_mfma_f32_32x32x16_bf16 v[0:15], v[150:153], v[166:169], v[0:15]
	global_load_dwordx4 v[76:79], v[182:183], off offset:896
	global_load_dwordx4 v[80:83], v[186:187], off offset:896
	global_load_dwordx4 v[88:91], v[188:189], off offset:896
	global_load_dwordx4 v[92:95], v[190:191], off offset:896
	global_load_dwordx4 v[104:107], v[184:185], off offset:896
	global_load_dwordx4 v[108:111], v[192:193], off offset:896
	s_waitcnt lgkmcnt(0)
	s_barrier
	ds_read_b128 v[116:119], v203 offset:55296
	ds_read_b128 v[112:115], v203 offset:55328
	ds_read_b128 v[124:127], v235
	ds_read_b128 v[120:123], v235 offset:32
	ds_read_b128 v[134:137], v203 offset:59904
	ds_read_b128 v[130:133], v203 offset:59936
	ds_read_b128 v[154:157], v235 offset:4608
	ds_read_b128 v[142:145], v235 offset:4640
	ds_read_b128 v[138:141], v203 offset:55360
	ds_read_b128 v[146:149], v203 offset:55392
	ds_read_b128 v[158:161], v203 offset:59968
	ds_read_b128 v[150:153], v203 offset:60000
	ds_read_b128 v[170:173], v235 offset:64
	ds_read_b128 v[162:165], v235 offset:96
	ds_read_b128 v[174:177], v235 offset:4672
	ds_read_b128 v[166:169], v235 offset:4704
	s_waitcnt lgkmcnt(0)
	s_barrier
	v_mfma_f32_32x32x16_bf16 v[48:63], v[116:119], v[124:127], v[48:63]
	v_mfma_f32_32x32x16_bf16 v[32:47], v[116:119], v[154:157], v[32:47]
	s_waitcnt vmcnt(11)
	ds_write_b128 v201, v[64:67]
	v_mfma_f32_32x32x16_bf16 v[16:31], v[134:137], v[124:127], v[16:31]
	v_mfma_f32_32x32x16_bf16 v[0:15], v[134:137], v[154:157], v[0:15]
	s_waitcnt vmcnt(10)
	ds_write_b128 v201, v[68:71] offset:9216
	v_mfma_f32_32x32x16_bf16 v[48:63], v[112:115], v[120:123], v[48:63]
	v_mfma_f32_32x32x16_bf16 v[32:47], v[112:115], v[142:145], v[32:47]
	s_waitcnt vmcnt(9)
	ds_write_b128 v201, v[84:87] offset:18432
	v_mfma_f32_32x32x16_bf16 v[16:31], v[130:133], v[120:123], v[16:31]
	v_mfma_f32_32x32x16_bf16 v[0:15], v[130:133], v[142:145], v[0:15]
	s_waitcnt vmcnt(8)
	ds_write_b128 v201, v[72:75] offset:27648
	v_mfma_f32_32x32x16_bf16 v[48:63], v[138:141], v[170:173], v[48:63]
	v_mfma_f32_32x32x16_bf16 v[32:47], v[138:141], v[174:177], v[32:47]
	s_waitcnt vmcnt(7)
	ds_write_b128 v201, v[96:99] offset:36864
	v_mfma_f32_32x32x16_bf16 v[16:31], v[158:161], v[170:173], v[16:31]
	v_mfma_f32_32x32x16_bf16 v[0:15], v[158:161], v[174:177], v[0:15]
	s_waitcnt vmcnt(6)
	ds_write_b128 v201, v[100:103] offset:46080
	v_mfma_f32_32x32x16_bf16 v[48:63], v[146:149], v[162:165], v[48:63]
	v_mfma_f32_32x32x16_bf16 v[32:47], v[146:149], v[166:169], v[32:47]
	v_mfma_f32_32x32x16_bf16 v[16:31], v[150:153], v[162:165], v[16:31]
	v_mfma_f32_32x32x16_bf16 v[0:15], v[150:153], v[166:169], v[0:15]
	global_load_dwordx4 v[64:67], v[182:183], off offset:1024
	global_load_dwordx4 v[68:71], v[186:187], off offset:1024
	global_load_dwordx4 v[84:87], v[188:189], off offset:1024
	global_load_dwordx4 v[72:75], v[190:191], off offset:1024
	global_load_dwordx4 v[96:99], v[184:185], off offset:1024
	global_load_dwordx4 v[100:103], v[192:193], off offset:1024
	s_waitcnt lgkmcnt(0)
	s_barrier
	ds_read_b128 v[116:119], v203
	ds_read_b128 v[112:115], v203 offset:32
	ds_read_b128 v[124:127], v204 offset:36864
	ds_read_b128 v[120:123], v204 offset:36896
	ds_read_b128 v[134:137], v203 offset:4608
	ds_read_b128 v[130:133], v203 offset:4640
	ds_read_b128 v[154:157], v204 offset:41472
	ds_read_b128 v[142:145], v204 offset:41504
	ds_read_b128 v[138:141], v203 offset:64
	ds_read_b128 v[146:149], v203 offset:96
	ds_read_b128 v[158:161], v203 offset:4672
	ds_read_b128 v[150:153], v203 offset:4704
	ds_read_b128 v[170:173], v204 offset:36928
	ds_read_b128 v[162:165], v204 offset:36960
	ds_read_b128 v[174:177], v204 offset:41536
	ds_read_b128 v[166:169], v204 offset:41568
	s_waitcnt lgkmcnt(0)
	s_barrier
	v_mfma_f32_32x32x16_bf16 v[48:63], v[116:119], v[124:127], v[48:63]
	v_mfma_f32_32x32x16_bf16 v[32:47], v[116:119], v[154:157], v[32:47]
	s_waitcnt vmcnt(11)
	ds_write_b128 v201, v[76:79] offset:55296
	v_mfma_f32_32x32x16_bf16 v[16:31], v[134:137], v[124:127], v[16:31]
	v_mfma_f32_32x32x16_bf16 v[0:15], v[134:137], v[154:157], v[0:15]
	s_waitcnt vmcnt(10)
	ds_write_b128 v201, v[80:83] offset:64512
	v_mfma_f32_32x32x16_bf16 v[48:63], v[112:115], v[120:123], v[48:63]
	v_mfma_f32_32x32x16_bf16 v[32:47], v[112:115], v[142:145], v[32:47]
	s_waitcnt vmcnt(9)
	ds_write_b128 v205, v[88:91] offset:18432
	v_mfma_f32_32x32x16_bf16 v[16:31], v[130:133], v[120:123], v[16:31]
	v_mfma_f32_32x32x16_bf16 v[0:15], v[130:133], v[142:145], v[0:15]
	s_waitcnt vmcnt(8)
	ds_write_b128 v205, v[92:95] offset:27648
	v_mfma_f32_32x32x16_bf16 v[48:63], v[138:141], v[170:173], v[48:63]
	v_mfma_f32_32x32x16_bf16 v[32:47], v[138:141], v[174:177], v[32:47]
	s_waitcnt vmcnt(7)
	ds_write_b128 v234, v[104:107]
	v_mfma_f32_32x32x16_bf16 v[16:31], v[158:161], v[170:173], v[16:31]
	v_mfma_f32_32x32x16_bf16 v[0:15], v[158:161], v[174:177], v[0:15]
	s_waitcnt vmcnt(6)
	ds_write_b128 v234, v[108:111] offset:9216
	v_mfma_f32_32x32x16_bf16 v[48:63], v[146:149], v[162:165], v[48:63]
	v_mfma_f32_32x32x16_bf16 v[32:47], v[146:149], v[166:169], v[32:47]
	v_mfma_f32_32x32x16_bf16 v[16:31], v[150:153], v[162:165], v[16:31]
	v_mfma_f32_32x32x16_bf16 v[0:15], v[150:153], v[166:169], v[0:15]
	global_load_dwordx4 v[76:79], v[182:183], off offset:1152
	global_load_dwordx4 v[80:83], v[186:187], off offset:1152
	global_load_dwordx4 v[88:91], v[188:189], off offset:1152
	global_load_dwordx4 v[92:95], v[190:191], off offset:1152
	global_load_dwordx4 v[104:107], v[184:185], off offset:1152
	global_load_dwordx4 v[108:111], v[192:193], off offset:1152
	s_waitcnt lgkmcnt(0)
	s_barrier
	ds_read_b128 v[116:119], v203 offset:55296
	ds_read_b128 v[112:115], v203 offset:55328
	ds_read_b128 v[124:127], v235
	ds_read_b128 v[120:123], v235 offset:32
	ds_read_b128 v[134:137], v203 offset:59904
	ds_read_b128 v[130:133], v203 offset:59936
	ds_read_b128 v[154:157], v235 offset:4608
	ds_read_b128 v[142:145], v235 offset:4640
	ds_read_b128 v[138:141], v203 offset:55360
	ds_read_b128 v[146:149], v203 offset:55392
	ds_read_b128 v[158:161], v203 offset:59968
	ds_read_b128 v[150:153], v203 offset:60000
	ds_read_b128 v[170:173], v235 offset:64
	ds_read_b128 v[162:165], v235 offset:96
	ds_read_b128 v[174:177], v235 offset:4672
	ds_read_b128 v[166:169], v235 offset:4704
	s_waitcnt lgkmcnt(0)
	s_barrier
	v_mfma_f32_32x32x16_bf16 v[48:63], v[116:119], v[124:127], v[48:63]
	v_mfma_f32_32x32x16_bf16 v[32:47], v[116:119], v[154:157], v[32:47]
	s_waitcnt vmcnt(11)
	ds_write_b128 v201, v[64:67]
	v_mfma_f32_32x32x16_bf16 v[16:31], v[134:137], v[124:127], v[16:31]
	v_mfma_f32_32x32x16_bf16 v[0:15], v[134:137], v[154:157], v[0:15]
	s_waitcnt vmcnt(10)
	ds_write_b128 v201, v[68:71] offset:9216
	v_mfma_f32_32x32x16_bf16 v[48:63], v[112:115], v[120:123], v[48:63]
	v_mfma_f32_32x32x16_bf16 v[32:47], v[112:115], v[142:145], v[32:47]
	s_waitcnt vmcnt(9)
	ds_write_b128 v201, v[84:87] offset:18432
	v_mfma_f32_32x32x16_bf16 v[16:31], v[130:133], v[120:123], v[16:31]
	v_mfma_f32_32x32x16_bf16 v[0:15], v[130:133], v[142:145], v[0:15]
	s_waitcnt vmcnt(8)
	ds_write_b128 v201, v[72:75] offset:27648
	v_mfma_f32_32x32x16_bf16 v[48:63], v[138:141], v[170:173], v[48:63]
	v_mfma_f32_32x32x16_bf16 v[32:47], v[138:141], v[174:177], v[32:47]
	s_waitcnt vmcnt(7)
	ds_write_b128 v201, v[96:99] offset:36864
	v_mfma_f32_32x32x16_bf16 v[16:31], v[158:161], v[170:173], v[16:31]
	v_mfma_f32_32x32x16_bf16 v[0:15], v[158:161], v[174:177], v[0:15]
	s_waitcnt vmcnt(6)
	ds_write_b128 v201, v[100:103] offset:46080
	v_mfma_f32_32x32x16_bf16 v[48:63], v[146:149], v[162:165], v[48:63]
	v_mfma_f32_32x32x16_bf16 v[32:47], v[146:149], v[166:169], v[32:47]
	v_mfma_f32_32x32x16_bf16 v[16:31], v[150:153], v[162:165], v[16:31]
	v_mfma_f32_32x32x16_bf16 v[0:15], v[150:153], v[166:169], v[0:15]
	global_load_dwordx4 v[64:67], v[182:183], off offset:1280
	global_load_dwordx4 v[68:71], v[186:187], off offset:1280
	global_load_dwordx4 v[84:87], v[188:189], off offset:1280
	global_load_dwordx4 v[72:75], v[190:191], off offset:1280
	global_load_dwordx4 v[96:99], v[184:185], off offset:1280
	global_load_dwordx4 v[100:103], v[192:193], off offset:1280
	s_waitcnt lgkmcnt(0)
	s_barrier
	ds_read_b128 v[116:119], v203
	ds_read_b128 v[112:115], v203 offset:32
	ds_read_b128 v[124:127], v204 offset:36864
	ds_read_b128 v[120:123], v204 offset:36896
	ds_read_b128 v[134:137], v203 offset:4608
	ds_read_b128 v[130:133], v203 offset:4640
	ds_read_b128 v[154:157], v204 offset:41472
	ds_read_b128 v[142:145], v204 offset:41504
	ds_read_b128 v[138:141], v203 offset:64
	ds_read_b128 v[146:149], v203 offset:96
	ds_read_b128 v[158:161], v203 offset:4672
	ds_read_b128 v[150:153], v203 offset:4704
	ds_read_b128 v[170:173], v204 offset:36928
	ds_read_b128 v[162:165], v204 offset:36960
	ds_read_b128 v[174:177], v204 offset:41536
	ds_read_b128 v[166:169], v204 offset:41568
	s_waitcnt lgkmcnt(0)
	s_barrier
	v_mfma_f32_32x32x16_bf16 v[48:63], v[116:119], v[124:127], v[48:63]
	v_mfma_f32_32x32x16_bf16 v[32:47], v[116:119], v[154:157], v[32:47]
	s_waitcnt vmcnt(11)
	ds_write_b128 v201, v[76:79] offset:55296
	v_mfma_f32_32x32x16_bf16 v[16:31], v[134:137], v[124:127], v[16:31]
	v_mfma_f32_32x32x16_bf16 v[0:15], v[134:137], v[154:157], v[0:15]
	s_waitcnt vmcnt(10)
	ds_write_b128 v201, v[80:83] offset:64512
	v_mfma_f32_32x32x16_bf16 v[48:63], v[112:115], v[120:123], v[48:63]
	v_mfma_f32_32x32x16_bf16 v[32:47], v[112:115], v[142:145], v[32:47]
	s_waitcnt vmcnt(9)
	ds_write_b128 v205, v[88:91] offset:18432
	v_mfma_f32_32x32x16_bf16 v[16:31], v[130:133], v[120:123], v[16:31]
	v_mfma_f32_32x32x16_bf16 v[0:15], v[130:133], v[142:145], v[0:15]
	s_waitcnt vmcnt(8)
	ds_write_b128 v205, v[92:95] offset:27648
	v_mfma_f32_32x32x16_bf16 v[48:63], v[138:141], v[170:173], v[48:63]
	v_mfma_f32_32x32x16_bf16 v[32:47], v[138:141], v[174:177], v[32:47]
	s_waitcnt vmcnt(7)
	ds_write_b128 v234, v[104:107]
	v_mfma_f32_32x32x16_bf16 v[16:31], v[158:161], v[170:173], v[16:31]
	v_mfma_f32_32x32x16_bf16 v[0:15], v[158:161], v[174:177], v[0:15]
	s_waitcnt vmcnt(6)
	ds_write_b128 v234, v[108:111] offset:9216
	v_mfma_f32_32x32x16_bf16 v[48:63], v[146:149], v[162:165], v[48:63]
	v_mfma_f32_32x32x16_bf16 v[32:47], v[146:149], v[166:169], v[32:47]
	v_mfma_f32_32x32x16_bf16 v[16:31], v[150:153], v[162:165], v[16:31]
	v_mfma_f32_32x32x16_bf16 v[0:15], v[150:153], v[166:169], v[0:15]
	global_load_dwordx4 v[76:79], v[182:183], off offset:1408
	global_load_dwordx4 v[80:83], v[186:187], off offset:1408
	global_load_dwordx4 v[88:91], v[188:189], off offset:1408
	global_load_dwordx4 v[92:95], v[190:191], off offset:1408
	global_load_dwordx4 v[104:107], v[184:185], off offset:1408
	global_load_dwordx4 v[108:111], v[192:193], off offset:1408
	s_waitcnt lgkmcnt(0)
	s_barrier
	ds_read_b128 v[116:119], v203 offset:55296
	ds_read_b128 v[112:115], v203 offset:55328
	ds_read_b128 v[124:127], v235
	ds_read_b128 v[120:123], v235 offset:32
	ds_read_b128 v[134:137], v203 offset:59904
	ds_read_b128 v[130:133], v203 offset:59936
	ds_read_b128 v[154:157], v235 offset:4608
	ds_read_b128 v[142:145], v235 offset:4640
	ds_read_b128 v[138:141], v203 offset:55360
	ds_read_b128 v[146:149], v203 offset:55392
	ds_read_b128 v[158:161], v203 offset:59968
	ds_read_b128 v[150:153], v203 offset:60000
	ds_read_b128 v[170:173], v235 offset:64
	ds_read_b128 v[162:165], v235 offset:96
	ds_read_b128 v[174:177], v235 offset:4672
	ds_read_b128 v[166:169], v235 offset:4704
	s_waitcnt lgkmcnt(0)
	s_barrier
	v_mfma_f32_32x32x16_bf16 v[48:63], v[116:119], v[124:127], v[48:63]
	v_mfma_f32_32x32x16_bf16 v[32:47], v[116:119], v[154:157], v[32:47]
	s_waitcnt vmcnt(11)
	ds_write_b128 v201, v[64:67]
	v_mfma_f32_32x32x16_bf16 v[16:31], v[134:137], v[124:127], v[16:31]
	v_mfma_f32_32x32x16_bf16 v[0:15], v[134:137], v[154:157], v[0:15]
	s_waitcnt vmcnt(10)
	ds_write_b128 v201, v[68:71] offset:9216
	v_mfma_f32_32x32x16_bf16 v[48:63], v[112:115], v[120:123], v[48:63]
	v_mfma_f32_32x32x16_bf16 v[32:47], v[112:115], v[142:145], v[32:47]
	s_waitcnt vmcnt(9)
	ds_write_b128 v201, v[84:87] offset:18432
	v_mfma_f32_32x32x16_bf16 v[16:31], v[130:133], v[120:123], v[16:31]
	v_mfma_f32_32x32x16_bf16 v[0:15], v[130:133], v[142:145], v[0:15]
	s_waitcnt vmcnt(8)
	ds_write_b128 v201, v[72:75] offset:27648
	v_mfma_f32_32x32x16_bf16 v[48:63], v[138:141], v[170:173], v[48:63]
	v_mfma_f32_32x32x16_bf16 v[32:47], v[138:141], v[174:177], v[32:47]
	s_waitcnt vmcnt(7)
	ds_write_b128 v201, v[96:99] offset:36864
	v_mfma_f32_32x32x16_bf16 v[16:31], v[158:161], v[170:173], v[16:31]
	v_mfma_f32_32x32x16_bf16 v[0:15], v[158:161], v[174:177], v[0:15]
	s_waitcnt vmcnt(6)
	ds_write_b128 v201, v[100:103] offset:46080
	v_mfma_f32_32x32x16_bf16 v[48:63], v[146:149], v[162:165], v[48:63]
	v_mfma_f32_32x32x16_bf16 v[32:47], v[146:149], v[166:169], v[32:47]
	v_mfma_f32_32x32x16_bf16 v[16:31], v[150:153], v[162:165], v[16:31]
	v_mfma_f32_32x32x16_bf16 v[0:15], v[150:153], v[166:169], v[0:15]
	global_load_dwordx4 v[64:67], v[182:183], off offset:1536
	global_load_dwordx4 v[68:71], v[186:187], off offset:1536
	global_load_dwordx4 v[84:87], v[188:189], off offset:1536
	global_load_dwordx4 v[72:75], v[190:191], off offset:1536
	global_load_dwordx4 v[96:99], v[184:185], off offset:1536
	global_load_dwordx4 v[100:103], v[192:193], off offset:1536
	s_waitcnt lgkmcnt(0)
	s_barrier
	ds_read_b128 v[116:119], v203
	ds_read_b128 v[112:115], v203 offset:32
	ds_read_b128 v[124:127], v204 offset:36864
	ds_read_b128 v[120:123], v204 offset:36896
	ds_read_b128 v[134:137], v203 offset:4608
	ds_read_b128 v[130:133], v203 offset:4640
	ds_read_b128 v[154:157], v204 offset:41472
	ds_read_b128 v[142:145], v204 offset:41504
	ds_read_b128 v[138:141], v203 offset:64
	ds_read_b128 v[146:149], v203 offset:96
	ds_read_b128 v[158:161], v203 offset:4672
	ds_read_b128 v[150:153], v203 offset:4704
	ds_read_b128 v[170:173], v204 offset:36928
	ds_read_b128 v[162:165], v204 offset:36960
	ds_read_b128 v[174:177], v204 offset:41536
	ds_read_b128 v[166:169], v204 offset:41568
	s_waitcnt lgkmcnt(0)
	s_barrier
	v_mfma_f32_32x32x16_bf16 v[48:63], v[116:119], v[124:127], v[48:63]
	v_mfma_f32_32x32x16_bf16 v[32:47], v[116:119], v[154:157], v[32:47]
	s_waitcnt vmcnt(11)
	ds_write_b128 v201, v[76:79] offset:55296
	v_mfma_f32_32x32x16_bf16 v[16:31], v[134:137], v[124:127], v[16:31]
	v_mfma_f32_32x32x16_bf16 v[0:15], v[134:137], v[154:157], v[0:15]
	s_waitcnt vmcnt(10)
	ds_write_b128 v201, v[80:83] offset:64512
	v_mfma_f32_32x32x16_bf16 v[48:63], v[112:115], v[120:123], v[48:63]
	v_mfma_f32_32x32x16_bf16 v[32:47], v[112:115], v[142:145], v[32:47]
	s_waitcnt vmcnt(9)
	ds_write_b128 v205, v[88:91] offset:18432
	v_mfma_f32_32x32x16_bf16 v[16:31], v[130:133], v[120:123], v[16:31]
	v_mfma_f32_32x32x16_bf16 v[0:15], v[130:133], v[142:145], v[0:15]
	s_waitcnt vmcnt(8)
	ds_write_b128 v205, v[92:95] offset:27648
	v_mfma_f32_32x32x16_bf16 v[48:63], v[138:141], v[170:173], v[48:63]
	v_mfma_f32_32x32x16_bf16 v[32:47], v[138:141], v[174:177], v[32:47]
	s_waitcnt vmcnt(7)
	ds_write_b128 v234, v[104:107]
	v_mfma_f32_32x32x16_bf16 v[16:31], v[158:161], v[170:173], v[16:31]
	v_mfma_f32_32x32x16_bf16 v[0:15], v[158:161], v[174:177], v[0:15]
	s_waitcnt vmcnt(6)
	ds_write_b128 v234, v[108:111] offset:9216
	v_mfma_f32_32x32x16_bf16 v[48:63], v[146:149], v[162:165], v[48:63]
	v_mfma_f32_32x32x16_bf16 v[32:47], v[146:149], v[166:169], v[32:47]
	v_mfma_f32_32x32x16_bf16 v[16:31], v[150:153], v[162:165], v[16:31]
	v_mfma_f32_32x32x16_bf16 v[0:15], v[150:153], v[166:169], v[0:15]
	global_load_dwordx4 v[76:79], v[182:183], off offset:1664
	global_load_dwordx4 v[80:83], v[186:187], off offset:1664
	global_load_dwordx4 v[88:91], v[188:189], off offset:1664
	global_load_dwordx4 v[92:95], v[190:191], off offset:1664
	global_load_dwordx4 v[104:107], v[184:185], off offset:1664
	global_load_dwordx4 v[108:111], v[192:193], off offset:1664
	s_waitcnt lgkmcnt(0)
	s_barrier
	ds_read_b128 v[116:119], v203 offset:55296
	ds_read_b128 v[112:115], v203 offset:55328
	ds_read_b128 v[124:127], v235
	ds_read_b128 v[120:123], v235 offset:32
	ds_read_b128 v[134:137], v203 offset:59904
	ds_read_b128 v[130:133], v203 offset:59936
	ds_read_b128 v[154:157], v235 offset:4608
	ds_read_b128 v[142:145], v235 offset:4640
	ds_read_b128 v[138:141], v203 offset:55360
	ds_read_b128 v[146:149], v203 offset:55392
	ds_read_b128 v[158:161], v203 offset:59968
	ds_read_b128 v[150:153], v203 offset:60000
	ds_read_b128 v[170:173], v235 offset:64
	ds_read_b128 v[162:165], v235 offset:96
	ds_read_b128 v[174:177], v235 offset:4672
	ds_read_b128 v[166:169], v235 offset:4704
	s_waitcnt lgkmcnt(0)
	s_barrier
	v_mfma_f32_32x32x16_bf16 v[48:63], v[116:119], v[124:127], v[48:63]
	v_mfma_f32_32x32x16_bf16 v[32:47], v[116:119], v[154:157], v[32:47]
	s_waitcnt vmcnt(11)
	ds_write_b128 v201, v[64:67]
	v_mfma_f32_32x32x16_bf16 v[16:31], v[134:137], v[124:127], v[16:31]
	v_mfma_f32_32x32x16_bf16 v[0:15], v[134:137], v[154:157], v[0:15]
	s_waitcnt vmcnt(10)
	ds_write_b128 v201, v[68:71] offset:9216
	v_mfma_f32_32x32x16_bf16 v[48:63], v[112:115], v[120:123], v[48:63]
	v_mfma_f32_32x32x16_bf16 v[32:47], v[112:115], v[142:145], v[32:47]
	s_waitcnt vmcnt(9)
	ds_write_b128 v201, v[84:87] offset:18432
	v_mfma_f32_32x32x16_bf16 v[16:31], v[130:133], v[120:123], v[16:31]
	v_mfma_f32_32x32x16_bf16 v[0:15], v[130:133], v[142:145], v[0:15]
	s_waitcnt vmcnt(8)
	ds_write_b128 v201, v[72:75] offset:27648
	v_mfma_f32_32x32x16_bf16 v[48:63], v[138:141], v[170:173], v[48:63]
	v_mfma_f32_32x32x16_bf16 v[32:47], v[138:141], v[174:177], v[32:47]
	s_waitcnt vmcnt(7)
	ds_write_b128 v201, v[96:99] offset:36864
	v_mfma_f32_32x32x16_bf16 v[16:31], v[158:161], v[170:173], v[16:31]
	v_mfma_f32_32x32x16_bf16 v[0:15], v[158:161], v[174:177], v[0:15]
	s_waitcnt vmcnt(6)
	ds_write_b128 v201, v[100:103] offset:46080
	v_mfma_f32_32x32x16_bf16 v[48:63], v[146:149], v[162:165], v[48:63]
	v_mfma_f32_32x32x16_bf16 v[32:47], v[146:149], v[166:169], v[32:47]
	v_mfma_f32_32x32x16_bf16 v[16:31], v[150:153], v[162:165], v[16:31]
	v_mfma_f32_32x32x16_bf16 v[0:15], v[150:153], v[166:169], v[0:15]
	global_load_dwordx4 v[64:67], v[182:183], off offset:1792
	global_load_dwordx4 v[68:71], v[186:187], off offset:1792
	global_load_dwordx4 v[84:87], v[188:189], off offset:1792
	global_load_dwordx4 v[72:75], v[190:191], off offset:1792
	global_load_dwordx4 v[96:99], v[184:185], off offset:1792
	global_load_dwordx4 v[100:103], v[192:193], off offset:1792
	s_waitcnt lgkmcnt(0)
	s_barrier
	ds_read_b128 v[116:119], v203
	ds_read_b128 v[112:115], v203 offset:32
	ds_read_b128 v[124:127], v204 offset:36864
	ds_read_b128 v[120:123], v204 offset:36896
	ds_read_b128 v[134:137], v203 offset:4608
	ds_read_b128 v[130:133], v203 offset:4640
	ds_read_b128 v[154:157], v204 offset:41472
	ds_read_b128 v[142:145], v204 offset:41504
	ds_read_b128 v[138:141], v203 offset:64
	ds_read_b128 v[146:149], v203 offset:96
	ds_read_b128 v[158:161], v203 offset:4672
	ds_read_b128 v[150:153], v203 offset:4704
	ds_read_b128 v[170:173], v204 offset:36928
	ds_read_b128 v[162:165], v204 offset:36960
	ds_read_b128 v[174:177], v204 offset:41536
	ds_read_b128 v[166:169], v204 offset:41568
	s_waitcnt lgkmcnt(0)
	s_barrier
	v_mfma_f32_32x32x16_bf16 v[48:63], v[116:119], v[124:127], v[48:63]
	v_mfma_f32_32x32x16_bf16 v[32:47], v[116:119], v[154:157], v[32:47]
	s_waitcnt vmcnt(11)
	ds_write_b128 v201, v[76:79] offset:55296
	v_mfma_f32_32x32x16_bf16 v[16:31], v[134:137], v[124:127], v[16:31]
	v_mfma_f32_32x32x16_bf16 v[0:15], v[134:137], v[154:157], v[0:15]
	s_waitcnt vmcnt(10)
	ds_write_b128 v201, v[80:83] offset:64512
	v_mfma_f32_32x32x16_bf16 v[48:63], v[112:115], v[120:123], v[48:63]
	v_mfma_f32_32x32x16_bf16 v[32:47], v[112:115], v[142:145], v[32:47]
	s_waitcnt vmcnt(9)
	ds_write_b128 v205, v[88:91] offset:18432
	v_mfma_f32_32x32x16_bf16 v[16:31], v[130:133], v[120:123], v[16:31]
	v_mfma_f32_32x32x16_bf16 v[0:15], v[130:133], v[142:145], v[0:15]
	s_waitcnt vmcnt(8)
	ds_write_b128 v205, v[92:95] offset:27648
	v_mfma_f32_32x32x16_bf16 v[48:63], v[138:141], v[170:173], v[48:63]
	v_mfma_f32_32x32x16_bf16 v[32:47], v[138:141], v[174:177], v[32:47]
	s_waitcnt vmcnt(7)
	ds_write_b128 v234, v[104:107]
	v_mfma_f32_32x32x16_bf16 v[16:31], v[158:161], v[170:173], v[16:31]
	v_mfma_f32_32x32x16_bf16 v[0:15], v[158:161], v[174:177], v[0:15]
	s_waitcnt vmcnt(6)
	ds_write_b128 v234, v[108:111] offset:9216
	v_mfma_f32_32x32x16_bf16 v[48:63], v[146:149], v[162:165], v[48:63]
	v_mfma_f32_32x32x16_bf16 v[32:47], v[146:149], v[166:169], v[32:47]
	v_mfma_f32_32x32x16_bf16 v[16:31], v[150:153], v[162:165], v[16:31]
	v_mfma_f32_32x32x16_bf16 v[0:15], v[150:153], v[166:169], v[0:15]
	global_load_dwordx4 v[76:79], v[182:183], off offset:1920
	global_load_dwordx4 v[80:83], v[186:187], off offset:1920
	global_load_dwordx4 v[88:91], v[188:189], off offset:1920
	global_load_dwordx4 v[92:95], v[190:191], off offset:1920
	global_load_dwordx4 v[104:107], v[184:185], off offset:1920
	global_load_dwordx4 v[108:111], v[192:193], off offset:1920
	s_waitcnt lgkmcnt(0)
	s_barrier
	ds_read_b128 v[116:119], v203 offset:55296
	ds_read_b128 v[112:115], v203 offset:55328
	ds_read_b128 v[124:127], v235
	ds_read_b128 v[120:123], v235 offset:32
	ds_read_b128 v[134:137], v203 offset:59904
	ds_read_b128 v[130:133], v203 offset:59936
	ds_read_b128 v[154:157], v235 offset:4608
	ds_read_b128 v[142:145], v235 offset:4640
	ds_read_b128 v[138:141], v203 offset:55360
	ds_read_b128 v[146:149], v203 offset:55392
	ds_read_b128 v[158:161], v203 offset:59968
	ds_read_b128 v[150:153], v203 offset:60000
	ds_read_b128 v[170:173], v235 offset:64
	ds_read_b128 v[162:165], v235 offset:96
	ds_read_b128 v[174:177], v235 offset:4672
	ds_read_b128 v[166:169], v235 offset:4704
	s_waitcnt lgkmcnt(0)
	s_barrier
	v_mfma_f32_32x32x16_bf16 v[48:63], v[116:119], v[124:127], v[48:63]
	v_mfma_f32_32x32x16_bf16 v[32:47], v[116:119], v[154:157], v[32:47]
	s_waitcnt vmcnt(11)
	ds_write_b128 v201, v[64:67]
	v_mfma_f32_32x32x16_bf16 v[16:31], v[134:137], v[124:127], v[16:31]
	v_mfma_f32_32x32x16_bf16 v[0:15], v[134:137], v[154:157], v[0:15]
	s_waitcnt vmcnt(10)
	ds_write_b128 v201, v[68:71] offset:9216
	v_mfma_f32_32x32x16_bf16 v[48:63], v[112:115], v[120:123], v[48:63]
	v_mfma_f32_32x32x16_bf16 v[32:47], v[112:115], v[142:145], v[32:47]
	s_waitcnt vmcnt(9)
	ds_write_b128 v201, v[84:87] offset:18432
	v_mfma_f32_32x32x16_bf16 v[16:31], v[130:133], v[120:123], v[16:31]
	v_mfma_f32_32x32x16_bf16 v[0:15], v[130:133], v[142:145], v[0:15]
	s_waitcnt vmcnt(8)
	ds_write_b128 v201, v[72:75] offset:27648
	v_mfma_f32_32x32x16_bf16 v[48:63], v[138:141], v[170:173], v[48:63]
	v_mfma_f32_32x32x16_bf16 v[32:47], v[138:141], v[174:177], v[32:47]
	s_waitcnt vmcnt(7)
	ds_write_b128 v201, v[96:99] offset:36864
	v_mfma_f32_32x32x16_bf16 v[16:31], v[158:161], v[170:173], v[16:31]
	v_mfma_f32_32x32x16_bf16 v[0:15], v[158:161], v[174:177], v[0:15]
	s_waitcnt vmcnt(6)
	ds_write_b128 v201, v[100:103] offset:46080
	v_mfma_f32_32x32x16_bf16 v[48:63], v[146:149], v[162:165], v[48:63]
	v_mfma_f32_32x32x16_bf16 v[32:47], v[146:149], v[166:169], v[32:47]
	v_mfma_f32_32x32x16_bf16 v[16:31], v[150:153], v[162:165], v[16:31]
	v_mfma_f32_32x32x16_bf16 v[0:15], v[150:153], v[166:169], v[0:15]
	s_waitcnt lgkmcnt(0)
	s_barrier
	ds_read_b128 v[116:119], v203
	ds_read_b128 v[112:115], v203 offset:32
	ds_read_b128 v[124:127], v204 offset:36864
	ds_read_b128 v[120:123], v204 offset:36896
	ds_read_b128 v[134:137], v203 offset:4608
	ds_read_b128 v[130:133], v203 offset:4640
	ds_read_b128 v[154:157], v204 offset:41472
	ds_read_b128 v[142:145], v204 offset:41504
	ds_read_b128 v[138:141], v203 offset:64
	ds_read_b128 v[146:149], v203 offset:96
	ds_read_b128 v[158:161], v203 offset:4672
	ds_read_b128 v[150:153], v203 offset:4704
	ds_read_b128 v[170:173], v204 offset:36928
	ds_read_b128 v[162:165], v204 offset:36960
	ds_read_b128 v[174:177], v204 offset:41536
	ds_read_b128 v[166:169], v204 offset:41568
	s_waitcnt lgkmcnt(0)
	s_barrier
	v_mfma_f32_32x32x16_bf16 v[48:63], v[116:119], v[124:127], v[48:63]
	v_mfma_f32_32x32x16_bf16 v[32:47], v[116:119], v[154:157], v[32:47]
	s_waitcnt vmcnt(5)
	ds_write_b128 v201, v[76:79] offset:55296
	v_mfma_f32_32x32x16_bf16 v[16:31], v[134:137], v[124:127], v[16:31]
	v_mfma_f32_32x32x16_bf16 v[0:15], v[134:137], v[154:157], v[0:15]
	s_waitcnt vmcnt(4)
	ds_write_b128 v201, v[80:83] offset:64512
	v_mfma_f32_32x32x16_bf16 v[48:63], v[112:115], v[120:123], v[48:63]
	v_mfma_f32_32x32x16_bf16 v[32:47], v[112:115], v[142:145], v[32:47]
	s_waitcnt vmcnt(3)
	ds_write_b128 v205, v[88:91] offset:18432
	v_mfma_f32_32x32x16_bf16 v[16:31], v[130:133], v[120:123], v[16:31]
	v_mfma_f32_32x32x16_bf16 v[0:15], v[130:133], v[142:145], v[0:15]
	s_waitcnt vmcnt(2)
	ds_write_b128 v205, v[92:95] offset:27648
	v_mfma_f32_32x32x16_bf16 v[48:63], v[138:141], v[170:173], v[48:63]
	v_mfma_f32_32x32x16_bf16 v[32:47], v[138:141], v[174:177], v[32:47]
	s_waitcnt vmcnt(1)
	ds_write_b128 v234, v[104:107]
	v_mfma_f32_32x32x16_bf16 v[16:31], v[158:161], v[170:173], v[16:31]
	v_mfma_f32_32x32x16_bf16 v[0:15], v[158:161], v[174:177], v[0:15]
	s_waitcnt vmcnt(0)
	ds_write_b128 v234, v[108:111] offset:9216
	v_mfma_f32_32x32x16_bf16 v[48:63], v[146:149], v[162:165], v[48:63]
	v_mfma_f32_32x32x16_bf16 v[32:47], v[146:149], v[166:169], v[32:47]
	v_mfma_f32_32x32x16_bf16 v[16:31], v[150:153], v[162:165], v[16:31]
	v_mfma_f32_32x32x16_bf16 v[0:15], v[150:153], v[166:169], v[0:15]
	s_waitcnt lgkmcnt(0)
	s_barrier
	ds_read_b128 v[116:119], v203 offset:55296
	ds_read_b128 v[112:115], v203 offset:55328
	ds_read_b128 v[124:127], v235
	ds_read_b128 v[120:123], v235 offset:32
	ds_read_b128 v[134:137], v203 offset:59904
	ds_read_b128 v[130:133], v203 offset:59936
	ds_read_b128 v[154:157], v235 offset:4608
	ds_read_b128 v[142:145], v235 offset:4640
	ds_read_b128 v[138:141], v203 offset:55360
	ds_read_b128 v[146:149], v203 offset:55392
	ds_read_b128 v[158:161], v203 offset:59968
	ds_read_b128 v[150:153], v203 offset:60000
	ds_read_b128 v[170:173], v235 offset:64
	ds_read_b128 v[162:165], v235 offset:96
	ds_read_b128 v[174:177], v235 offset:4672
	ds_read_b128 v[166:169], v235 offset:4704
	s_waitcnt lgkmcnt(0)
	s_barrier
	v_mfma_f32_32x32x16_bf16 v[48:63], v[116:119], v[124:127], v[48:63]
	v_mfma_f32_32x32x16_bf16 v[32:47], v[116:119], v[154:157], v[32:47]
	v_mfma_f32_32x32x16_bf16 v[16:31], v[134:137], v[124:127], v[16:31]
	v_mfma_f32_32x32x16_bf16 v[0:15], v[134:137], v[154:157], v[0:15]
	v_mfma_f32_32x32x16_bf16 v[48:63], v[112:115], v[120:123], v[48:63]
	v_mfma_f32_32x32x16_bf16 v[32:47], v[112:115], v[142:145], v[32:47]
	v_mfma_f32_32x32x16_bf16 v[16:31], v[130:133], v[120:123], v[16:31]
	v_mfma_f32_32x32x16_bf16 v[0:15], v[130:133], v[142:145], v[0:15]
	v_mfma_f32_32x32x16_bf16 v[48:63], v[138:141], v[170:173], v[48:63]
	v_mfma_f32_32x32x16_bf16 v[32:47], v[138:141], v[174:177], v[32:47]
	v_mfma_f32_32x32x16_bf16 v[16:31], v[158:161], v[170:173], v[16:31]
	v_mfma_f32_32x32x16_bf16 v[0:15], v[158:161], v[174:177], v[0:15]
	v_mfma_f32_32x32x16_bf16 v[48:63], v[146:149], v[162:165], v[48:63]
	v_mfma_f32_32x32x16_bf16 v[32:47], v[146:149], v[166:169], v[32:47]
	v_mfma_f32_32x32x16_bf16 v[16:31], v[150:153], v[162:165], v[16:31]
	v_mfma_f32_32x32x16_bf16 v[0:15], v[150:153], v[166:169], v[0:15]
	s_waitcnt lgkmcnt(0)
	s_barrier
	s_waitcnt lgkmcnt(0)
	s_barrier
	s_branch .LBB0_1240
